# v18 + one static priority raise for the half-workgroup that starts a phase behind in the GEMM phases, per-cluster s_setprio flips deleted (asm guide 7.4)
# baseline (speedup 1.0000x reference)
; #define LAS __attribute__((address_space(3)))
; template <bool REMAP = false>
; __device__ __forceinline__ void transpose_convert(LAS unsigned char* lds, const float* src, bf16_t* dst, int K, int N, int G, int bid) {
;     LAS float* tile = (LAS float*)lds;
;     const int tid = threadIdx.x, ntn = N / 64, ntiles = (K / 128) * ntn;
;     const int r0 = tid >> 4, c4 = tid & 15;
;     f32x4 v[4];
;     if (bid < ntiles) { const int k0 = (bid / ntn) * 128, n0 = (bid % ntn) * 64;
; #pragma unroll
;         for (int i = 0; i < 4; ++i) v[i] = __builtin_nontemporal_load((const f32x4*)(src + (size_t)(k0 + r0 + 32 * i) * N + n0 + c4 * 4)); }
;     for (int t = bid; t < ntiles; t += G) {
;         const int k0 = (t / ntn) * 128, n0 = (t % ntn) * 64;
;         asm volatile("s_waitcnt lgkmcnt(0)" ::: "memory"); __builtin_amdgcn_s_barrier(); asm volatile("" ::: "memory");
; #pragma unroll
;         for (int i = 0; i < 4; ++i) {
; #pragma unroll
;             for (int j = 0; j < 4; ++j) tile[(r0 + 32 * i) * 65 + c4 * 4 + j] = v[i][j]; }
; __global__ void __launch_bounds__(NTHREADS, 2) mk_fwd(Params P) {
;     ...
;     bf16_t* WINB = (bf16_t*)(ws + WS_WINB); bf16_t* WOUT1 = (bf16_t*)(ws + WS_WOUT1); bf16_t* WG1 = (bf16_t*)(ws + WS_WG1); bf16_t* WP = (bf16_t*)(ws + WS_WP);
;     bf16_t* PB = (bf16_t*)(ws + WS_PB); float* STATS = (float*)(ws + WS_STATS); float* KPART = (float*)(ws + WS_KPART); bf16_t* WSB = (bf16_t*)(ws + WS_WSB);
;     bf16_t* SLOTA = (bf16_t*)(ws + WS_SLOTA); bf16_t* WINA = (bf16_t*)(ws + WS_WINA); bf16_t* WOUT0 = (bf16_t*)(ws + WS_WOUT0); bf16_t* WG0 = (bf16_t*)(ws + WS_WG0);
.LBB0_19:
	s_add_u32 s58, s40, 0x3000000
	s_addc_u32 s59, s41, 0
	s_add_u32 s14, s40, 0x6000000
	s_addc_u32 s15, s41, 0
	s_add_u32 s56, s40, 0x7800000
	s_addc_u32 s57, s41, 0
	s_add_u32 s52, s40, 0x8000000
	s_addc_u32 s53, s41, 0
	s_load_dwordx16 s[16:31], s[0:1], 0x0
	s_cmp_lt_i32 s42, 1
	s_cselect_b64 s[0:1], -1, 0
	s_cmp_gt_i32 s43, 0
	s_setprio 0
	s_cselect_b64 s[4:5], -1, 0
	s_and_b64 s[8:9], s[0:1], s[4:5]
	s_andn2_b64 vcc, exec, s[8:9]
	v_lshrrev_b32_e32 v214, 4, v164
	s_cbranch_vccnz .LBB0_93
	s_cmpk_lt_i32 s2, 0x200
	s_cselect_b64 s[0:1], -1, 0
	s_cmpk_gt_i32 s2, 0x1ff
	v_lshl_add_u32 v24, v214, 2, 0
	s_cbranch_scc1 .LBB0_27
	s_ashr_i32 s3, s2, 31
	s_lshr_b32 s3, s3, 27
	s_add_i32 s3, s2, s3
	s_lshl_b32 s4, s3, 2
	s_and_b32 s3, s3, 0x3ffffe0
	s_sub_i32 s3, s2, s3
	s_and_b32 s5, s4, 0xffffff80
	s_lshl_b32 s4, s3, 6
	v_or_b32_e32 v8, s5, v214
	s_ashr_i32 s5, s4, 31
	s_lshl_b64 s[4:5], s[4:5], 2
	v_and_b32_e32 v21, 15, v164
	s_add_u32 s4, s44, s4
	s_addc_u32 s5, s45, s5
	v_lshlrev_b32_e32 v18, 4, v21
	v_mov_b32_e32 v19, 0
	v_ashrrev_i32_e32 v9, 31, v8
	v_lshl_add_u64 v[10:11], s[4:5], 0, v[18:19]
	v_lshlrev_b64 v[0:1], 13, v[8:9]
	v_lshl_add_u64 v[12:13], v[10:11], 0, v[0:1]
	s_mov_b32 s3, 0x40000
	v_add_co_u32_e32 v4, vcc, s3, v12
	v_or_b32_e32 v8, 64, v8
	s_nop 0
	v_addc_co_u32_e32 v5, vcc, 0, v13, vcc
	v_ashrrev_i32_e32 v9, 31, v8
	s_mov_b32 s10, 0xc0000
	global_load_dwordx4 v[0:3], v[12:13], off nt
	s_nop 0
	global_load_dwordx4 v[4:7], v[4:5], off nt
	v_lshlrev_b64 v[8:9], 13, v[8:9]
	v_add_co_u32_e32 v12, vcc, s10, v12
	v_lshl_add_u64 v[8:9], v[10:11], 0, v[8:9]
	s_nop 0
	v_addc_co_u32_e32 v13, vcc, 0, v13, vcc
	global_load_dwordx4 v[8:11], v[8:9], off nt
	s_nop 0
	global_load_dwordx4 v[12:15], v[12:13], off nt
	v_add_u32_e32 v20, 0x200, v164
	v_add_u32_e32 v22, 0, v18
	v_lshrrev_b32_e32 v20, 4, v20
	v_mul_u32_u24_e32 v28, 0x820, v21
	v_mul_u32_u24_e32 v21, 0x104, v214
	v_lshl_add_u32 v27, v20, 2, 0
	v_add_u32_e32 v21, v22, v21
	v_lshl_add_u64 v[16:17], s[44:45], 0, v[18:19]
	v_lshl_add_u64 v[18:19], s[56:57], 0, v[18:19]
	s_lshl_b32 s60, s2, 6
	s_lshl_b32 s11, s34, 6
	v_add_u32_e32 v22, 0x2080, v21
	v_add_u32_e32 v23, 0x2088, v21
	v_add_u32_e32 v25, 0x4100, v21
	v_add_u32_e32 v26, v24, v28
	v_add_u32_e32 v27, v27, v28
	v_add_u32_e32 v28, 0x4108, v21
	v_add_u32_e32 v29, 0x6180, v21
	s_mov_b32 s61, s2
	s_branch .LBB0_23

; __device__ __forceinline__ unsigned xb_ld(unsigned* p)              { return __hip_atomic_load(p, __ATOMIC_RELAXED, __HIP_MEMORY_SCOPE_AGENT); }
; __device__ __forceinline__ void xcd_barrier_complete(unsigned* bar, unsigned x, unsigned& nloc, unsigned& nx) {
;     const unsigned G = gridDim.x * gridDim.y * gridDim.z;
;     unsigned sum, cnt, mine, sp = 0u;
;     for (;;) {
;         sum = 0u; cnt = 0u; mine = 0u;
; #pragma unroll
;         for (unsigned j = 0; j < 16; ++j) { const unsigned c = xb_ld(&bar[XB_XCNT(j)]); sum += c; cnt += (c > 0u) ? 1u : 0u; mine = (j == x) ? c : mine; }
;         if (sum == G) break;
;         __builtin_amdgcn_s_sleep(1);
;         if ((++sp & 255u) == 0u) { if (xb_ld(&bar[XB_TMO])) break; if (sp > XB_SPIN_CAP) { atomicAdd(&bar[XB_TMO], 1u); break; } }
;     }
;     nloc = mine > 0u ? mine : 1u; nx = cnt > 0u ? cnt : 1u;
; }
; __device__ __forceinline__ void xcd_barrier(const XcdBarrier& b) {
;     asm volatile("s_waitcnt vmcnt(0)" ::: "memory");
;     __syncthreads();
;     if (threadIdx.x == 0) {
;         unsigned* bar = b.bar;
;         __builtin_amdgcn_s_waitcnt(0);
;         unsigned nloc = b.st[0], nx = b.st[1];
;         if (nloc == 0u) { xcd_barrier_complete(bar, b.x, nloc, nx); b.st[0] = nloc; b.st[1] = nx; }
.LBB0_93:
	s_cmp_gt_i32 s43, 1
	s_setprio 0
	s_cselect_b64 s[0:1], -1, 0
	s_and_b64 s[4:5], s[8:9], s[0:1]
	s_andn2_b64 vcc, exec, s[4:5]
	s_cbranch_vccnz .LBB0_143
	s_waitcnt vmcnt(0)
	s_waitcnt lgkmcnt(0)
	s_barrier
	s_and_saveexec_b64 s[4:5], s[12:13]
	s_cbranch_execz .LBB0_142
	s_add_i32 s3, 0, 0x20000
	s_waitcnt vmcnt(5)
	v_mov_b32_e32 v0, s3
	s_waitcnt vmcnt(0) expcnt(0) lgkmcnt(0)
	ds_read_b32 v2, v0
	s_add_i32 s3, 0, 0x20004
	v_mov_b32_e32 v0, s3
	ds_read_b32 v0, v0
	s_waitcnt lgkmcnt(1)
	v_cmp_ne_u32_e32 vcc, 0, v2
	s_cbranch_vccnz .LBB0_110
	s_add_u32 s6, s40, 0x3d00200
	s_addc_u32 s7, s41, 0
	s_add_u32 s8, s40, 0x3d00400
	s_addc_u32 s9, s41, 0
	s_add_u32 s10, s40, 0x3d00500
	s_addc_u32 s11, s41, 0
	s_add_u32 s16, s40, 0x3d00600
	s_addc_u32 s17, s41, 0
	s_add_u32 s18, s40, 0x3d00700
	s_addc_u32 s19, s41, 0
	s_add_u32 s20, s40, 0x3d00800
	s_addc_u32 s21, s41, 0
	s_add_u32 s26, s40, 0x3d00900
	s_addc_u32 s27, s41, 0
	s_add_u32 s36, s40, 0x3d00a00
	s_addc_u32 s37, s41, 0
	s_add_u32 s60, s40, 0x3d00b00
	s_addc_u32 s61, s41, 0
	s_add_u32 s62, s40, 0x3d00c00
	s_addc_u32 s63, s41, 0
	s_add_u32 s64, s40, 0x3d00d00
	s_addc_u32 s65, s41, 0
	s_add_u32 s66, s40, 0x3d00e00
	s_addc_u32 s67, s41, 0
	s_add_u32 s68, s40, 0x3d00f00
	s_addc_u32 s69, s41, 0
	s_add_u32 s70, s40, 0x3d01000
	s_addc_u32 s71, s41, 0
	s_add_u32 s72, s40, 0x3d01100
	s_addc_u32 s73, s41, 0
	s_add_u32 s74, s40, 0x3d01200
	s_addc_u32 s75, s41, 0
	s_mul_i32 s3, s35, s92
	s_add_u32 s76, s40, 0x3d01300
	s_mul_i32 s3, s3, s34
	s_addc_u32 s77, s41, 0
	s_mov_b32 s84, 1
	v_mov_b32_e32 v16, 0
	s_branch .LBB0_98

; #define PG8_STAGE(bufoff, gbase, voff) do { _Pragma("unroll") for (int _i = 0; _i < 2; ++_i) \
;         __builtin_amdgcn_global_load_lds((const unsigned*)((const char*)(gbase) + (voff)[_i]), (LAS unsigned*)(lds + (bufoff) + ldsw + _i * 8192), 16, 0, 0); } while (0)
; #define PG8_BAR __builtin_amdgcn_s_barrier()
; template <class Epi, bool ALIGN_EPI = false, bool SP2 = true>
; __device__ __forceinline__ void gemm_phase(LAS unsigned char* lds, const Gemm g, const StaticOrder& S, const Epi& E) {
;     const int tid = threadIdx.x, wid = __builtin_amdgcn_readfirstlane(tid >> 6), lane = tid & 63, wr = wid >> 2, wc = wid & 3, fr = lane & 15, fq = lane >> 4;
;     const int K = g.K, nt = K / BK;
;     unsigned voffA[2], voffB[2];
; #pragma unroll
;     for (int i = 0; i < 2; ++i) { int R, C; stage_rc(tid * 16 + i * 8192, R, C); const int Rb = (R & ~31) + perm32(R & 31);
;         voffA[i] = (unsigned)(R * K + C) * 2u; voffB[i] = (unsigned)(Rb * K + C) * 2u; }
;     const size_t kstep = (size_t)(BK * 2);
;     const size_t hstep = (size_t)HALF * K * 2;
;     const size_t tstep = 2 * hstep;
;     const unsigned ldsw = (unsigned)wid * 1024u;
;     const int aoff = lds_byte(wr * 64 + fr, fq * 8), boff = lds_byte(wc * 32 + fr, fq * 8);
;     ...
;     const char* cA = (const char*)g.A + (size_t)cur.pm * tstep; const char* cB = (const char*)g.Bt + (size_t)(cur.pn + (cur.pm >= g.bsplit ? g.badd : 0)) * tstep;
;     if constexpr (SP2) {
;         PG8_STAGE(PG8_SB(0, 0), cB, voffB); PG8_STAGE(PG8_SB(0, 1), cB + hstep, voffB); PG8_STAGE(PG8_SA(0, 0), cA, voffA); PG8_STAGE(PG8_SA(0, 1), cA + hstep, voffA);
;         if (wr == 1) PG8_BAR;
.LBB0_146:
	s_andn2_b64 vcc, exec, s[4:5]
	s_cbranch_vccnz .LBB0_182
	s_waitcnt vmcnt(5)
	v_lshrrev_b32_e32 v2, 1, v164
	v_lshrrev_b32_e32 v3, 5, v164
	v_and_b32_e32 v2, 24, v2
	v_and_b32_e32 v3, 4, v3
	s_waitcnt vmcnt(4)
	v_bfe_u32 v4, v164, 2, 2
	v_lshlrev_b32_e32 v0, 4, v164
	v_and_b32_e32 v1, 32, v164
	s_waitcnt vmcnt(3)
	v_bfe_u32 v10, v164, 2, 4
	v_or3_b32 v2, v3, v4, v2
	v_lshrrev_b32_e32 v3, 3, v164
	s_movk_i32 s3, 0x70
	v_bitop3_b32 v8, v0, v1, 48 bitop3:0x6c
	v_and_b32_e32 v9, 64, v164
	v_and_or_b32 v4, v3, s3, v10
	s_movk_i32 s3, 0x60
	v_add_u32_e32 v11, 0x2000, v0
	v_or_b32_e32 v1, v8, v9
	v_and_or_b32 v3, v3, s3, v2
	v_lshrrev_b32_e32 v0, 7, v11
	s_movk_i32 s3, 0xf0
	s_lshr_b32 s5, s6, 6
	v_lshl_or_b32 v130, v3, 12, v1
	v_and_or_b32 v3, v0, s3, v10
	s_movk_i32 s3, 0xe0
	s_ashr_i32 s19, s18, 31
	s_ashr_i32 s71, s70, 31
	v_and_or_b32 v0, v0, s3, v2
	s_lshr_b32 s4, s6, 8
	s_lshl_b32 s3, s5, 10
	s_lshl_b64 s[26:27], s[18:19], 20
	s_lshl_b64 s[36:37], s[70:71], 20
	s_add_u32 s74, s14, s36
	s_addc_u32 s75, s15, s37
	s_add_i32 s71, s3, 0
	s_add_i32 m0, s71, 0x10000
	v_lshl_or_b32 v134, v0, 12, v1
	global_load_lds_dwordx4 v130, s[74:75]
	s_add_i32 m0, s71, 0x12000
	s_add_u32 s36, s74, 0x80000
	global_load_lds_dwordx4 v134, s[74:75]
	s_addc_u32 s37, s75, 0
	s_add_i32 m0, s71, 0x14000
	v_lshl_or_b32 v128, v4, 12, v1
	global_load_lds_dwordx4 v130, s[36:37]
	s_add_i32 m0, s71, 0x16000
	s_add_u32 s72, s20, s26
	s_addc_u32 s73, s21, s27
	s_add_i32 s78, s71, 0x2000
	global_load_lds_dwordx4 v134, s[36:37]
	s_mov_b32 m0, s71
	s_add_u32 s26, s72, 0x80000
	v_lshl_or_b32 v132, v3, 12, v1
	global_load_lds_dwordx4 v128, s[72:73]
	s_mov_b32 m0, s78
	s_addc_u32 s27, s73, 0
	s_add_i32 s79, s71, 0x4000
	global_load_lds_dwordx4 v132, s[72:73]
	s_mov_b32 m0, s79
	s_add_i32 s80, s71, 0x6000
	global_load_lds_dwordx4 v128, s[26:27]
	s_mov_b32 m0, s80
	v_mov_b32_e32 v137, 0
	global_load_lds_dwordx4 v132, s[26:27]
	v_mov_b32_e32 v131, v137
	v_mov_b32_e32 v135, v137
	v_mov_b32_e32 v129, v137
	v_mov_b32_e32 v133, v137
	s_cmp_eq_u32 s4, 1
	s_mov_b32 s19, 0
	v_lshl_add_u64 v[6:7], s[74:75], 0, v[130:131]
	v_lshl_add_u64 v[4:5], s[74:75], 0, v[134:135]
	v_lshl_add_u64 v[0:1], s[72:73], 0, v[128:129]
	s_cselect_b64 s[26:27], -1, 0
	s_cmp_lg_u32 s4, 1
	v_lshl_add_u64 v[2:3], s[72:73], 0, v[132:133]
	s_cbranch_scc1 .LBB0_149
	s_barrier
	s_setprio 1

; #define PG8_STAGE(bufoff, gbase, voff) do { _Pragma("unroll") for (int _i = 0; _i < 2; ++_i) \
;         __builtin_amdgcn_global_load_lds((const unsigned*)((const char*)(gbase) + (voff)[_i]), (LAS unsigned*)(lds + (bufoff) + ldsw + _i * 8192), 16, 0, 0); } while (0)
; #define PG8_LDA(dst, b, h) do { _Pragma("unroll") for (int m = 0; m < 4; ++m) _Pragma("unroll") for (int k = 0; k < 2; ++k) dst[m][k] = *(const LAS bf16x8*)(lds + PG8_SA(b, h) + aoff + m * 2048 + k * 1024); } while (0)
; #define PG8_LDB(dst, b, h) do { _Pragma("unroll") for (int n = 0; n < 2; ++n) _Pragma("unroll") for (int k = 0; k < 2; ++k) dst[n][k] = *(const LAS bf16x8*)(lds + PG8_SB(b, h) + boff + n * 2048 + k * 1024); } while (0)
; #define PG8_MMA(ai, bj, At, Bt) do { __builtin_amdgcn_s_setprio(1); _Pragma("unroll") for (int m = 0; m < 4; ++m) _Pragma("unroll") for (int n = 0; n < 2; ++n) _Pragma("unroll") for (int k = 0; k < 2; ++k) \
;         acc[ai][bj][m][n] = __builtin_amdgcn_mfma_f32_16x16x32_bf16(Bt[n][k], At[m][k], acc[ai][bj][m][n], 0, 0, 0); __builtin_amdgcn_s_setprio(0); } while (0)
; #define PG8_WAIT_V(n) asm volatile("s_waitcnt vmcnt(" #n ")" ::: "memory")
; #define PG8_WAIT_L(n) asm volatile("s_waitcnt lgkmcnt(" #n ")" ::: "memory")
; #define PG8_BAR __builtin_amdgcn_s_barrier()
; template <class Epi, bool ALIGN_EPI = false, bool SP2 = true>
; __device__ __forceinline__ void gemm_phase(LAS unsigned char* lds, const Gemm g, const StaticOrder& S, const Epi& E) {
;     ...
;         for (int t = 0; t < nt; t += 2) {
;             const bool last = (t == nt - 2);
;             const char* a1 = cA + (size_t)(t + 1) * kstep;
;             const char* a2 = last ? nA : cA + (size_t)(t + 2) * kstep; const char* b2 = last ? nB : cB + (size_t)(t + 2) * kstep;
;             const char* a3 = a2 + kstep; const char* b3 = b2 + kstep;
;             if constexpr (SP2) {
;             PG8_LDB(B0, 0, 0); PG8_LDB(B1, 0, 1); PG8_SCHED; PG8_LDA(At, 0, 0); PG8_STAGE(PG8_SA(1, 1), a1 + hstep, voffA);
;             PG8_WAIT_V(8); PG8_WAIT_L(0); PG8_BAR; PG8_MMA(0, 0, At, B0); PG8_MMA(0, 1, At, B1); PG8_BAR; PG8_SCHED;
;             PG8_LDA(At, 0, 1); PG8_STAGE(PG8_SB(0, 0), b2, voffB); PG8_STAGE(PG8_SB(0, 1), b2 + hstep, voffB); PG8_STAGE(PG8_SA(0, 0), a2, voffA);
;             PG8_WAIT_V(8); PG8_WAIT_L(0); PG8_BAR; PG8_MMA(1, 0, At, B0); PG8_MMA(1, 1, At, B1); PG8_BAR; PG8_SCHED;
.LBB0_155:
	ds_read_b128 v[146:149], v157
	s_waitcnt lgkmcnt(0)
	ds_read_b128 v[150:153], v157 offset:1024
	ds_read_b128 v[166:169], v157 offset:2048
	ds_read_b128 v[170:173], v157 offset:3072
	ds_read_b128 v[174:177], v158
	ds_read_b128 v[178:181], v158 offset:1024
	ds_read_b128 v[182:185], v158 offset:2048
	ds_read_b128 v[186:189], v158 offset:3072
	s_add_u32 s74, s72, 0xfff80080
	s_addc_u32 s75, s73, -1
	s_cmp_eq_u32 s96, 28
	s_cselect_b32 s77, s65, s75
	s_cselect_b32 s76, s91, s74
	s_cselect_b32 s75, s63, s95
	s_cselect_b32 s74, s93, s94
	v_lshl_add_u64 v[162:163], s[72:73], 0, v[138:139]
	s_add_i32 m0, s71, 0xc000
	ds_read_b128 v[190:193], v159
	ds_read_b128 v[194:197], v159 offset:1024
	ds_read_b128 v[198:201], v159 offset:2048
	ds_read_b128 v[202:205], v159 offset:3072
	ds_read_b128 v[206:209], v159 offset:4096
	ds_read_b128 v[210:213], v159 offset:5120
	ds_read_b128 v[216:219], v159 offset:6144
	ds_read_b128 v[220:223], v159 offset:7168
	global_load_lds_dwordx4 v[162:163], off
	v_lshl_add_u64 v[162:163], s[72:73], 0, v[140:141]
	s_add_i32 m0, s71, 0xe000
	s_nop 0
	global_load_lds_dwordx4 v[162:163], off
	s_waitcnt vmcnt(8)
	s_waitcnt lgkmcnt(0)
	s_barrier
	s_waitcnt lgkmcnt(0)
	v_mfma_f32_16x16x32_bf16 v[124:127], v[146:149], v[190:193], v[124:127]
	v_mfma_f32_16x16x32_bf16 v[120:123], v[166:169], v[190:193], v[120:123]
	v_mfma_f32_16x16x32_bf16 v[108:111], v[146:149], v[198:201], v[108:111]
	v_mfma_f32_16x16x32_bf16 v[104:107], v[166:169], v[198:201], v[104:107]
	v_mfma_f32_16x16x32_bf16 v[92:95], v[146:149], v[206:209], v[92:95]
	v_mfma_f32_16x16x32_bf16 v[88:91], v[166:169], v[206:209], v[88:91]
	v_mfma_f32_16x16x32_bf16 v[76:79], v[146:149], v[216:219], v[76:79]
	v_mfma_f32_16x16x32_bf16 v[72:75], v[166:169], v[216:219], v[72:75]
	v_mfma_f32_16x16x32_bf16 v[124:127], v[150:153], v[194:197], v[124:127]
	v_mfma_f32_16x16x32_bf16 v[120:123], v[170:173], v[194:197], v[120:123]
	v_mfma_f32_16x16x32_bf16 v[108:111], v[150:153], v[202:205], v[108:111]
	v_mfma_f32_16x16x32_bf16 v[104:107], v[170:173], v[202:205], v[104:107]
	v_mfma_f32_16x16x32_bf16 v[92:95], v[150:153], v[210:213], v[92:95]
	v_mfma_f32_16x16x32_bf16 v[88:91], v[170:173], v[210:213], v[88:91]
	v_mfma_f32_16x16x32_bf16 v[76:79], v[150:153], v[220:223], v[76:79]
	v_mfma_f32_16x16x32_bf16 v[72:75], v[170:173], v[220:223], v[72:75]
	v_mfma_f32_16x16x32_bf16 v[116:119], v[174:177], v[190:193], v[116:119]
	v_mfma_f32_16x16x32_bf16 v[112:115], v[182:185], v[190:193], v[112:115]
	v_mfma_f32_16x16x32_bf16 v[100:103], v[174:177], v[198:201], v[100:103]
	v_mfma_f32_16x16x32_bf16 v[96:99], v[182:185], v[198:201], v[96:99]
	v_mfma_f32_16x16x32_bf16 v[84:87], v[174:177], v[206:209], v[84:87]
	v_mfma_f32_16x16x32_bf16 v[80:83], v[182:185], v[206:209], v[80:83]
	v_mfma_f32_16x16x32_bf16 v[68:71], v[174:177], v[216:219], v[68:71]
	v_mfma_f32_16x16x32_bf16 v[64:67], v[182:185], v[216:219], v[64:67]
	v_mfma_f32_16x16x32_bf16 v[116:119], v[178:181], v[194:197], v[116:119]
	v_mfma_f32_16x16x32_bf16 v[112:115], v[186:189], v[194:197], v[112:115]
	v_mfma_f32_16x16x32_bf16 v[100:103], v[178:181], v[202:205], v[100:103]
	v_mfma_f32_16x16x32_bf16 v[96:99], v[186:189], v[202:205], v[96:99]
	v_mfma_f32_16x16x32_bf16 v[84:87], v[178:181], v[210:213], v[84:87]
	v_mfma_f32_16x16x32_bf16 v[80:83], v[186:189], v[210:213], v[80:83]
	v_mfma_f32_16x16x32_bf16 v[68:71], v[178:181], v[220:223], v[68:71]
	v_mfma_f32_16x16x32_bf16 v[64:67], v[186:189], v[220:223], v[64:67]
	s_barrier
	s_add_i32 s97, s88, s3
	v_lshl_add_u64 v[162:163], s[74:75], 0, v[130:131]
	s_mov_b32 m0, s97
	ds_read_b128 v[190:193], v159 offset:16384
	ds_read_b128 v[194:197], v159 offset:17408
	ds_read_b128 v[198:201], v159 offset:18432
	ds_read_b128 v[202:205], v159 offset:19456
	ds_read_b128 v[206:209], v159 offset:20480
	ds_read_b128 v[210:213], v159 offset:21504
	ds_read_b128 v[216:219], v159 offset:22528
	ds_read_b128 v[220:223], v159 offset:23552
	global_load_lds_dwordx4 v[162:163], off
	s_add_i32 m0, s97, 0x2000
	s_add_u32 vcc_lo, s74, 0x80000
	v_lshl_add_u64 v[224:225], s[74:75], 0, v[134:135]
	s_addc_u32 vcc_hi, s75, 0
	s_add_i32 s97, s89, s3
	global_load_lds_dwordx4 v[224:225], off
	v_lshl_add_u64 v[226:227], vcc, 0, v[130:131]
	s_mov_b32 m0, s97
	v_lshl_add_u64 v[228:229], s[76:77], 0, v[132:133]
	global_load_lds_dwordx4 v[226:227], off
	v_lshl_add_u64 v[226:227], vcc, 0, v[134:135]
	s_add_i32 m0, s97, 0x2000
	s_nop 0
	global_load_lds_dwordx4 v[226:227], off
	v_lshl_add_u64 v[226:227], s[76:77], 0, v[128:129]
	s_mov_b32 m0, s71
	s_nop 0
	global_load_lds_dwordx4 v[226:227], off
	s_mov_b32 m0, s78
	s_nop 0
	global_load_lds_dwordx4 v[228:229], off
	s_waitcnt vmcnt(8)
	s_waitcnt lgkmcnt(0)
	s_barrier
; #define PG8_STAGE(bufoff, gbase, voff) do { _Pragma("unroll") for (int _i = 0; _i < 2; ++_i) \
;         __builtin_amdgcn_global_load_lds((const unsigned*)((const char*)(gbase) + (voff)[_i]), (LAS unsigned*)(lds + (bufoff) + ldsw + _i * 8192), 16, 0, 0); } while (0)
; #define PG8_LDA(dst, b, h) do { _Pragma("unroll") for (int m = 0; m < 4; ++m) _Pragma("unroll") for (int k = 0; k < 2; ++k) dst[m][k] = *(const LAS bf16x8*)(lds + PG8_SA(b, h) + aoff + m * 2048 + k * 1024); } while (0)
; #define PG8_LDB(dst, b, h) do { _Pragma("unroll") for (int n = 0; n < 2; ++n) _Pragma("unroll") for (int k = 0; k < 2; ++k) dst[n][k] = *(const LAS bf16x8*)(lds + PG8_SB(b, h) + boff + n * 2048 + k * 1024); } while (0)
; #define PG8_MMA(ai, bj, At, Bt) do { __builtin_amdgcn_s_setprio(1); _Pragma("unroll") for (int m = 0; m < 4; ++m) _Pragma("unroll") for (int n = 0; n < 2; ++n) _Pragma("unroll") for (int k = 0; k < 2; ++k) \
;         acc[ai][bj][m][n] = __builtin_amdgcn_mfma_f32_16x16x32_bf16(Bt[n][k], At[m][k], acc[ai][bj][m][n], 0, 0, 0); __builtin_amdgcn_s_setprio(0); } while (0)
; #define PG8_WAIT_V(n) asm volatile("s_waitcnt vmcnt(" #n ")" ::: "memory")
; #define PG8_WAIT_L(n) asm volatile("s_waitcnt lgkmcnt(" #n ")" ::: "memory")
; #define PG8_BAR __builtin_amdgcn_s_barrier()
; #define PG8_SCHED __builtin_amdgcn_sched_barrier(0)
; template <class Epi, bool ALIGN_EPI = false, bool SP2 = true>
; __device__ __forceinline__ void gemm_phase(LAS unsigned char* lds, const Gemm g, const StaticOrder& S, const Epi& E) {
;     ...
;             PG8_WAIT_V(8); PG8_WAIT_L(0); PG8_BAR; PG8_MMA(1, 0, At, B0); PG8_MMA(1, 1, At, B1); PG8_BAR; PG8_SCHED;
;             PG8_LDB(B0, 1, 0); PG8_LDB(B1, 1, 1); PG8_SCHED; PG8_LDA(At, 1, 0); PG8_STAGE(PG8_SA(0, 1), a2 + hstep, voffA);
;             PG8_WAIT_V(8); PG8_WAIT_L(0); PG8_BAR; PG8_MMA(0, 0, At, B0); PG8_MMA(0, 1, At, B1); PG8_BAR; PG8_SCHED;
	s_waitcnt lgkmcnt(0)
	v_mfma_f32_16x16x32_bf16 v[60:63], v[146:149], v[190:193], v[60:63]
	v_mfma_f32_16x16x32_bf16 v[56:59], v[166:169], v[190:193], v[56:59]
	v_mfma_f32_16x16x32_bf16 v[44:47], v[146:149], v[198:201], v[44:47]
	v_mfma_f32_16x16x32_bf16 v[40:43], v[166:169], v[198:201], v[40:43]
	v_mfma_f32_16x16x32_bf16 v[28:31], v[146:149], v[206:209], v[28:31]
	v_mfma_f32_16x16x32_bf16 v[24:27], v[166:169], v[206:209], v[24:27]
	v_mfma_f32_16x16x32_bf16 v[12:15], v[146:149], v[216:219], v[12:15]
	v_mfma_f32_16x16x32_bf16 v[8:11], v[166:169], v[216:219], v[8:11]
	v_mfma_f32_16x16x32_bf16 v[60:63], v[150:153], v[194:197], v[60:63]
	v_mfma_f32_16x16x32_bf16 v[56:59], v[170:173], v[194:197], v[56:59]
	v_mfma_f32_16x16x32_bf16 v[44:47], v[150:153], v[202:205], v[44:47]
	v_mfma_f32_16x16x32_bf16 v[40:43], v[170:173], v[202:205], v[40:43]
	v_mfma_f32_16x16x32_bf16 v[28:31], v[150:153], v[210:213], v[28:31]
	v_mfma_f32_16x16x32_bf16 v[24:27], v[170:173], v[210:213], v[24:27]
	v_mfma_f32_16x16x32_bf16 v[12:15], v[150:153], v[220:223], v[12:15]
	v_mfma_f32_16x16x32_bf16 v[8:11], v[170:173], v[220:223], v[8:11]
	v_mfma_f32_16x16x32_bf16 v[52:55], v[174:177], v[190:193], v[52:55]
	v_mfma_f32_16x16x32_bf16 v[48:51], v[182:185], v[190:193], v[48:51]
	v_mfma_f32_16x16x32_bf16 v[36:39], v[174:177], v[198:201], v[36:39]
	v_mfma_f32_16x16x32_bf16 v[32:35], v[182:185], v[198:201], v[32:35]
	v_mfma_f32_16x16x32_bf16 v[20:23], v[174:177], v[206:209], v[20:23]
	v_mfma_f32_16x16x32_bf16 v[16:19], v[182:185], v[206:209], v[16:19]
	v_mfma_f32_16x16x32_bf16 v[4:7], v[174:177], v[216:219], v[4:7]
	v_mfma_f32_16x16x32_bf16 v[0:3], v[182:185], v[216:219], v[0:3]
	v_mfma_f32_16x16x32_bf16 v[52:55], v[178:181], v[194:197], v[52:55]
	v_mfma_f32_16x16x32_bf16 v[48:51], v[186:189], v[194:197], v[48:51]
	v_mfma_f32_16x16x32_bf16 v[36:39], v[178:181], v[202:205], v[36:39]
	v_mfma_f32_16x16x32_bf16 v[32:35], v[186:189], v[202:205], v[32:35]
	v_mfma_f32_16x16x32_bf16 v[20:23], v[178:181], v[210:213], v[20:23]
	v_mfma_f32_16x16x32_bf16 v[16:19], v[186:189], v[210:213], v[16:19]
	v_mfma_f32_16x16x32_bf16 v[4:7], v[178:181], v[220:223], v[4:7]
	v_mfma_f32_16x16x32_bf16 v[0:3], v[186:189], v[220:223], v[0:3]
	s_barrier
	s_add_i32 s97, 0, 0x18000
	v_add_u32_e32 v136, s97, v155
	s_add_i32 vcc_lo, 0, 0x1c000
	ds_read_b128 v[146:149], v136
	ds_read_b128 v[150:153], v136 offset:1024
	ds_read_b128 v[166:169], v136 offset:2048
	ds_read_b128 v[170:173], v136 offset:3072
	v_add_u32_e32 v136, vcc_lo, v155
	ds_read_b128 v[174:177], v136
	ds_read_b128 v[178:181], v136 offset:1024
	ds_read_b128 v[182:185], v136 offset:2048
	ds_read_b128 v[186:189], v136 offset:3072
	s_add_u32 s76, s76, 0x80000
	s_addc_u32 s77, s77, 0
	s_mov_b32 m0, s79
	v_lshl_add_u64 v[230:231], s[76:77], 0, v[128:129]
	ds_read_b128 v[190:193], v159 offset:32768
	ds_read_b128 v[194:197], v159 offset:33792
	ds_read_b128 v[198:201], v159 offset:34816
	ds_read_b128 v[202:205], v159 offset:35840
	ds_read_b128 v[206:209], v159 offset:36864
	ds_read_b128 v[210:213], v159 offset:37888
	ds_read_b128 v[216:219], v159 offset:38912
	ds_read_b128 v[220:223], v159 offset:39936
	global_load_lds_dwordx4 v[230:231], off
	v_lshl_add_u64 v[230:231], s[76:77], 0, v[132:133]
	s_mov_b32 m0, s80
	s_nop 0
	global_load_lds_dwordx4 v[230:231], off
	s_waitcnt vmcnt(8)
	s_waitcnt lgkmcnt(0)
	s_barrier
	s_waitcnt lgkmcnt(0)
	v_mfma_f32_16x16x32_bf16 v[124:127], v[146:149], v[190:193], v[124:127]
	v_mfma_f32_16x16x32_bf16 v[120:123], v[166:169], v[190:193], v[120:123]
	v_mfma_f32_16x16x32_bf16 v[108:111], v[146:149], v[198:201], v[108:111]
	v_mfma_f32_16x16x32_bf16 v[104:107], v[166:169], v[198:201], v[104:107]
	v_mfma_f32_16x16x32_bf16 v[92:95], v[146:149], v[206:209], v[92:95]
	v_mfma_f32_16x16x32_bf16 v[88:91], v[166:169], v[206:209], v[88:91]
	v_mfma_f32_16x16x32_bf16 v[76:79], v[146:149], v[216:219], v[76:79]
	v_mfma_f32_16x16x32_bf16 v[72:75], v[166:169], v[216:219], v[72:75]
	v_mfma_f32_16x16x32_bf16 v[124:127], v[150:153], v[194:197], v[124:127]
	v_mfma_f32_16x16x32_bf16 v[120:123], v[170:173], v[194:197], v[120:123]
	v_mfma_f32_16x16x32_bf16 v[108:111], v[150:153], v[202:205], v[108:111]
	v_mfma_f32_16x16x32_bf16 v[104:107], v[170:173], v[202:205], v[104:107]
	v_mfma_f32_16x16x32_bf16 v[92:95], v[150:153], v[210:213], v[92:95]
	v_mfma_f32_16x16x32_bf16 v[88:91], v[170:173], v[210:213], v[88:91]
	v_mfma_f32_16x16x32_bf16 v[76:79], v[150:153], v[220:223], v[76:79]
	v_mfma_f32_16x16x32_bf16 v[72:75], v[170:173], v[220:223], v[72:75]
	v_mfma_f32_16x16x32_bf16 v[116:119], v[174:177], v[190:193], v[116:119]
	v_mfma_f32_16x16x32_bf16 v[112:115], v[182:185], v[190:193], v[112:115]
	v_mfma_f32_16x16x32_bf16 v[100:103], v[174:177], v[198:201], v[100:103]
	v_mfma_f32_16x16x32_bf16 v[96:99], v[182:185], v[198:201], v[96:99]
	v_mfma_f32_16x16x32_bf16 v[84:87], v[174:177], v[206:209], v[84:87]
	v_mfma_f32_16x16x32_bf16 v[80:83], v[182:185], v[206:209], v[80:83]
	v_mfma_f32_16x16x32_bf16 v[68:71], v[174:177], v[216:219], v[68:71]
	v_mfma_f32_16x16x32_bf16 v[64:67], v[182:185], v[216:219], v[64:67]
	v_mfma_f32_16x16x32_bf16 v[116:119], v[178:181], v[194:197], v[116:119]
	v_mfma_f32_16x16x32_bf16 v[112:115], v[186:189], v[194:197], v[112:115]
	v_mfma_f32_16x16x32_bf16 v[100:103], v[178:181], v[202:205], v[100:103]
	v_mfma_f32_16x16x32_bf16 v[96:99], v[186:189], v[202:205], v[96:99]
	v_mfma_f32_16x16x32_bf16 v[84:87], v[178:181], v[210:213], v[84:87]
	v_mfma_f32_16x16x32_bf16 v[80:83], v[186:189], v[210:213], v[80:83]
	v_mfma_f32_16x16x32_bf16 v[68:71], v[178:181], v[220:223], v[68:71]
	v_mfma_f32_16x16x32_bf16 v[64:67], v[186:189], v[220:223], v[64:67]
	s_barrier
; #define PG8_STAGE(bufoff, gbase, voff) do { _Pragma("unroll") for (int _i = 0; _i < 2; ++_i) \
;         __builtin_amdgcn_global_load_lds((const unsigned*)((const char*)(gbase) + (voff)[_i]), (LAS unsigned*)(lds + (bufoff) + ldsw + _i * 8192), 16, 0, 0); } while (0)
; #define PG8_LDA(dst, b, h) do { _Pragma("unroll") for (int m = 0; m < 4; ++m) _Pragma("unroll") for (int k = 0; k < 2; ++k) dst[m][k] = *(const LAS bf16x8*)(lds + PG8_SA(b, h) + aoff + m * 2048 + k * 1024); } while (0)
; #define PG8_MMA(ai, bj, At, Bt) do { __builtin_amdgcn_s_setprio(1); _Pragma("unroll") for (int m = 0; m < 4; ++m) _Pragma("unroll") for (int n = 0; n < 2; ++n) _Pragma("unroll") for (int k = 0; k < 2; ++k) \
;         acc[ai][bj][m][n] = __builtin_amdgcn_mfma_f32_16x16x32_bf16(Bt[n][k], At[m][k], acc[ai][bj][m][n], 0, 0, 0); __builtin_amdgcn_s_setprio(0); } while (0)
; #define PG8_WAIT_V(n) asm volatile("s_waitcnt vmcnt(" #n ")" ::: "memory")
; #define PG8_WAIT_L(n) asm volatile("s_waitcnt lgkmcnt(" #n ")" ::: "memory")
; #define PG8_BAR __builtin_amdgcn_s_barrier()
; #define PG8_SCHED __builtin_amdgcn_sched_barrier(0)
; template <class Epi, bool ALIGN_EPI = false, bool SP2 = true>
; __device__ __forceinline__ void gemm_phase(LAS unsigned char* lds, const Gemm g, const StaticOrder& S, const Epi& E) {
;     ...
;             PG8_LDA(At, 1, 1); PG8_STAGE(PG8_SB(1, 0), b3, voffB); PG8_STAGE(PG8_SB(1, 1), b3 + hstep, voffB); PG8_STAGE(PG8_SA(1, 0), a3, voffA);
;             PG8_WAIT_V(8); PG8_WAIT_L(0); PG8_BAR; PG8_MMA(1, 0, At, B0); PG8_MMA(1, 1, At, B1); PG8_BAR; PG8_SCHED;
;     ...
;         if constexpr (ALIGN_EPI) { if (wr == 0) PG8_BAR; }
	s_add_i32 s76, s97, s3
	v_lshl_add_u64 v[162:163], v[162:163], 0, s[36:37]
	s_mov_b32 m0, s76
	ds_read_b128 v[190:193], v159 offset:49152
	ds_read_b128 v[194:197], v159 offset:50176
	ds_read_b128 v[198:201], v159 offset:51200
	ds_read_b128 v[202:205], v159 offset:52224
	ds_read_b128 v[206:209], v159 offset:53248
	ds_read_b128 v[210:213], v159 offset:54272
	ds_read_b128 v[216:219], v159 offset:55296
	ds_read_b128 v[220:223], v159 offset:56320
	global_load_lds_dwordx4 v[162:163], off
	s_add_i32 m0, s76, 0x2000
	s_add_u32 s74, s74, 0x80080
	v_lshl_add_u64 v[162:163], v[224:225], 0, s[36:37]
	s_addc_u32 s75, s75, 0
	s_add_i32 s76, vcc_lo, s3
	global_load_lds_dwordx4 v[162:163], off
	v_lshl_add_u64 v[162:163], s[74:75], 0, v[130:131]
	s_mov_b32 m0, s76
	s_nop 0
	global_load_lds_dwordx4 v[162:163], off
	v_lshl_add_u64 v[162:163], s[74:75], 0, v[134:135]
	s_add_i32 m0, s76, 0x2000
	s_nop 0
	global_load_lds_dwordx4 v[162:163], off
	v_lshl_add_u64 v[162:163], v[226:227], 0, s[36:37]
	s_mov_b32 m0, s82
	s_nop 0
	global_load_lds_dwordx4 v[162:163], off
	v_lshl_add_u64 v[162:163], v[228:229], 0, s[36:37]
	s_mov_b32 m0, s83
	s_nop 0
	global_load_lds_dwordx4 v[162:163], off
	s_waitcnt vmcnt(8)
	s_waitcnt lgkmcnt(0)
	s_barrier
	s_waitcnt lgkmcnt(0)
	v_mfma_f32_16x16x32_bf16 v[60:63], v[146:149], v[190:193], v[60:63]
	v_mfma_f32_16x16x32_bf16 v[56:59], v[166:169], v[190:193], v[56:59]
	v_mfma_f32_16x16x32_bf16 v[44:47], v[146:149], v[198:201], v[44:47]
	v_mfma_f32_16x16x32_bf16 v[40:43], v[166:169], v[198:201], v[40:43]
	v_mfma_f32_16x16x32_bf16 v[28:31], v[146:149], v[206:209], v[28:31]
	v_mfma_f32_16x16x32_bf16 v[24:27], v[166:169], v[206:209], v[24:27]
	v_mfma_f32_16x16x32_bf16 v[12:15], v[146:149], v[216:219], v[12:15]
	v_mfma_f32_16x16x32_bf16 v[8:11], v[166:169], v[216:219], v[8:11]
	v_mfma_f32_16x16x32_bf16 v[60:63], v[150:153], v[194:197], v[60:63]
	v_mfma_f32_16x16x32_bf16 v[56:59], v[170:173], v[194:197], v[56:59]
	v_mfma_f32_16x16x32_bf16 v[44:47], v[150:153], v[202:205], v[44:47]
	v_mfma_f32_16x16x32_bf16 v[40:43], v[170:173], v[202:205], v[40:43]
	v_mfma_f32_16x16x32_bf16 v[28:31], v[150:153], v[210:213], v[28:31]
	v_mfma_f32_16x16x32_bf16 v[24:27], v[170:173], v[210:213], v[24:27]
	v_mfma_f32_16x16x32_bf16 v[12:15], v[150:153], v[220:223], v[12:15]
	v_mfma_f32_16x16x32_bf16 v[8:11], v[170:173], v[220:223], v[8:11]
	v_mfma_f32_16x16x32_bf16 v[52:55], v[174:177], v[190:193], v[52:55]
	v_mfma_f32_16x16x32_bf16 v[48:51], v[182:185], v[190:193], v[48:51]
	v_mfma_f32_16x16x32_bf16 v[36:39], v[174:177], v[198:201], v[36:39]
	v_mfma_f32_16x16x32_bf16 v[32:35], v[182:185], v[198:201], v[32:35]
	v_mfma_f32_16x16x32_bf16 v[20:23], v[174:177], v[206:209], v[20:23]
	v_mfma_f32_16x16x32_bf16 v[16:19], v[182:185], v[206:209], v[16:19]
	v_mfma_f32_16x16x32_bf16 v[4:7], v[174:177], v[216:219], v[4:7]
	v_mfma_f32_16x16x32_bf16 v[0:3], v[182:185], v[216:219], v[0:3]
	v_mfma_f32_16x16x32_bf16 v[52:55], v[178:181], v[194:197], v[52:55]
	v_mfma_f32_16x16x32_bf16 v[48:51], v[186:189], v[194:197], v[48:51]
	v_mfma_f32_16x16x32_bf16 v[36:39], v[178:181], v[202:205], v[36:39]
	v_mfma_f32_16x16x32_bf16 v[32:35], v[186:189], v[202:205], v[32:35]
	v_mfma_f32_16x16x32_bf16 v[20:23], v[178:181], v[210:213], v[20:23]
	v_mfma_f32_16x16x32_bf16 v[16:19], v[186:189], v[210:213], v[16:19]
	v_mfma_f32_16x16x32_bf16 v[4:7], v[178:181], v[220:223], v[4:7]
	v_mfma_f32_16x16x32_bf16 v[0:3], v[186:189], v[220:223], v[0:3]
	s_barrier
	s_add_i32 s96, s96, 2
	s_add_u32 s72, s72, 0x100
	s_addc_u32 s73, s73, 0
	s_add_u32 s94, s94, 0x100
	s_addc_u32 s95, s95, 0
	s_cmp_gt_u32 s96, 29
	s_cbranch_scc0 .LBB0_155
	s_and_b64 vcc, exec, s[60:61]
	s_cbranch_vccz .LBB0_158
	s_barrier

; __device__ __forceinline__ unsigned xb_add(unsigned* p, unsigned v) { return __hip_atomic_fetch_add(p, v, __ATOMIC_RELAXED, __HIP_MEMORY_SCOPE_AGENT); }
; __device__ __forceinline__ void xcd_barrier(const XcdBarrier& b) {
;     asm volatile("s_waitcnt vmcnt(0)" ::: "memory");
;     __syncthreads();
;     if (threadIdx.x == 0) {
;         unsigned* bar = b.bar;
;         __builtin_amdgcn_s_waitcnt(0);
;         unsigned nloc = b.st[0], nx = b.st[1];
;         if (nloc == 0u) { xcd_barrier_complete(bar, b.x, nloc, nx); b.st[0] = nloc; b.st[1] = nx; }
;         const unsigned old = xb_add(&bar[XB_XSUB(b.x)], 1u);
.LBB0_182:
	s_cmp_gt_i32 s43, 2
	s_setprio 0
	s_cselect_b64 s[4:5], -1, 0
	s_and_b64 s[0:1], s[0:1], s[4:5]
	s_andn2_b64 vcc, exec, s[0:1]
	s_cbranch_vccnz .LBB0_232
	s_waitcnt vmcnt(0)
	s_waitcnt vmcnt(0) lgkmcnt(0)
	s_barrier
	s_and_saveexec_b64 s[0:1], s[12:13]
	s_cbranch_execz .LBB0_231
	v_readfirstlane_b32 s99, v255
	s_bcnt1_i32_b32 s99, s99
	v_mov_b32_e32 v253, 0x2000c
	v_mov_b32_e32 v254, s99
	ds_write_b32 v253, v254
	s_cmp_eq_u32 s99, 1
	s_cbranch_scc1 .Lpc1_fast
	buffer_wbl2 sc1
	s_waitcnt vmcnt(0)

; __device__ __forceinline__ unsigned xb_add(unsigned* p, unsigned v) { return __hip_atomic_fetch_add(p, v, __ATOMIC_RELAXED, __HIP_MEMORY_SCOPE_AGENT); }
; __device__ __forceinline__ void xcd_barrier(const XcdBarrier& b) {
;     asm volatile("s_waitcnt vmcnt(0)" ::: "memory");
;     __syncthreads();
;     if (threadIdx.x == 0) {
;         unsigned* bar = b.bar;
;         __builtin_amdgcn_s_waitcnt(0);
;         unsigned nloc = b.st[0], nx = b.st[1];
;         if (nloc == 0u) { xcd_barrier_complete(bar, b.x, nloc, nx); b.st[0] = nloc; b.st[1] = nx; }
;         const unsigned old = xb_add(&bar[XB_XSUB(b.x)], 1u);
.LBB0_241:
	s_cmp_gt_i32 s43, 3
	s_setprio 0
	s_cselect_b64 s[0:1], -1, 0
	s_and_b64 s[4:5], s[4:5], s[0:1]
	s_andn2_b64 vcc, exec, s[4:5]
	s_cbranch_vccnz .LBB0_291
	s_waitcnt vmcnt(0)
	s_waitcnt vmcnt(0) lgkmcnt(0)
	s_barrier
	s_and_saveexec_b64 s[4:5], s[12:13]
	s_cbranch_execz .LBB0_290
	v_mov_b32_e32 v253, 0x2000c
	ds_read_b32 v254, v253
	s_waitcnt lgkmcnt(0)
	v_readfirstlane_b32 s99, v254
	s_cmp_eq_u32 s99, 1
	s_cbranch_scc1 .Lpc2_fast
	buffer_wbl2 sc1
	s_waitcnt vmcnt(0)

; #define PG8_STAGE(bufoff, gbase, voff) do { _Pragma("unroll") for (int _i = 0; _i < 2; ++_i) \
;         __builtin_amdgcn_global_load_lds((const unsigned*)((const char*)(gbase) + (voff)[_i]), (LAS unsigned*)(lds + (bufoff) + ldsw + _i * 8192), 16, 0, 0); } while (0)
; #define PG8_WAIT_V(n) asm volatile("s_waitcnt vmcnt(" #n ")" ::: "memory")
; #define PG8_BAR __builtin_amdgcn_s_barrier()
;     __device__ bool next(int i, Unit& u) const {
;         const long L = (long)i * G + c; if (L >= nwg) return false;
;         int wgid = (int)L; { const int q = nwg / NXCD, r = nwg % NXCD, xcd = wgid % NXCD, off = wgid / NXCD; wgid = (xcd < r ? xcd * (q + 1) : r * (q + 1) + (xcd - r) * q) + off; }
;         const int nig = WGM * nN, gid = wgid / nig, fm = gid * WGM, gsz = (nM - fm) < WGM ? (nM - fm) : WGM;
;         u.pm = fm + ((wgid % nig) % gsz); u.pn = (wgid % nig) / gsz; return true;
; template <class Epi, bool ALIGN_EPI = false, bool SP2 = true>
; __device__ __forceinline__ void gemm_phase(LAS unsigned char* lds, const Gemm g, const StaticOrder& S, const Epi& E) {
;     ...
;     const char* cA = (const char*)g.A + (size_t)cur.pm * tstep; const char* cB = (const char*)g.Bt + (size_t)(cur.pn + (cur.pm >= g.bsplit ? g.badd : 0)) * tstep;
;     if constexpr (SP2) {
;         PG8_STAGE(PG8_SB(0, 0), cB, voffB); PG8_STAGE(PG8_SB(0, 1), cB + hstep, voffB); PG8_STAGE(PG8_SA(0, 0), cA, voffA); PG8_STAGE(PG8_SA(0, 1), cA + hstep, voffA);
;         if (wr == 1) PG8_BAR;
;         PG8_WAIT_V(2); PG8_BAR;
;         PG8_STAGE(PG8_SB(1, 0), cB + kstep, voffB); PG8_STAGE(PG8_SA(1, 0), cA + kstep, voffA); PG8_STAGE(PG8_SB(1, 1), cB + hstep + kstep, voffB);
;         PG8_WAIT_V(6); PG8_BAR;
.LBB0_297:
	s_lshr_b32 s0, s68, 6
	s_ashr_i32 s1, s4, 3
	s_lshr_b32 s4, s68, 8
	s_lshl_b32 s69, s0, 10
	s_add_u32 s70, s40, 0x3200000
	s_addc_u32 s71, s41, 0
	s_add_i32 s1, s5, s1
	s_ashr_i32 s5, s1, 31
	s_lshr_b32 s5, s5, 27
	s_add_i32 s5, s1, s5
	s_ashr_i32 s6, s5, 5
	s_andn2_b32 s5, s5, 31
	s_sub_i32 s1, s1, s5
	s_bfe_i32 s5, s1, 0x80000
	s_bfe_u32 s5, s5, 0x2000d
	s_add_i32 s5, s1, s5
	s_bfe_i32 s7, s5, 0x80000
	s_and_b32 s5, s5, 0xfc
	s_sub_i32 s1, s1, s5
	s_lshl_b32 s6, s6, 2
	s_sext_i32_i8 s1, s1
	s_add_i32 s36, s6, s1
	s_and_b32 s36, s2, 7
	s_lshl_b32 s36, s36, 2
	s_bfe_u32 s1, s2, 0x20003
	s_or_b32 s36, s36, s1
	s_sext_i32_i16 s7, s7
	s_ashr_i32 s37, s36, 31
	s_ashr_i32 s84, s7, 2
	s_lshr_b32 s84, s2, 5
	s_lshl_b64 s[6:7], s[36:37], 17
	s_cmp_gt_i32 s36, 31
	s_cselect_b32 s1, 8, 0
	s_add_i32 s18, s1, s84
	s_ashr_i32 s19, s18, 31
	s_lshl_b64 s[18:19], s[18:19], 17
	s_add_u32 s62, s58, s18
	s_addc_u32 s63, s59, s19
	s_add_i32 s37, s69, 0
	v_lshl_or_b32 v42, v64, 9, v62
	s_add_i32 m0, s37, 0x10000
	v_lshl_or_b32 v46, v66, 9, v62
	global_load_lds_dwordx4 v42, s[62:63]
	s_add_i32 m0, s37, 0x12000
	s_add_u32 s18, s62, 0x10000
	global_load_lds_dwordx4 v46, s[62:63]
	s_addc_u32 s19, s63, 0
	s_add_i32 m0, s37, 0x14000
	v_lshl_or_b32 v40, v63, 9, v62
	global_load_lds_dwordx4 v42, s[18:19]
	s_add_i32 m0, s37, 0x16000
	s_add_u32 s60, s70, s6
	s_addc_u32 s61, s71, s7
	s_add_i32 s72, s37, 0x2000
	global_load_lds_dwordx4 v46, s[18:19]
	s_mov_b32 m0, s37
	s_add_u32 s6, s60, 0x10000
	v_lshl_or_b32 v44, v65, 9, v62
	global_load_lds_dwordx4 v40, s[60:61]
	s_mov_b32 m0, s72
	s_addc_u32 s7, s61, 0
	s_add_i32 s73, s37, 0x4000
	global_load_lds_dwordx4 v44, s[60:61]
	s_mov_b32 m0, s73
	s_add_i32 s74, s37, 0x6000
	global_load_lds_dwordx4 v40, s[6:7]
	s_mov_b32 m0, s74
	v_mov_b32_e32 v43, 0
	global_load_lds_dwordx4 v44, s[6:7]
	v_mov_b32_e32 v47, v43
	v_mov_b32_e32 v41, v43
	v_mov_b32_e32 v45, v43
	v_lshl_add_u64 v[6:7], s[62:63], 0, v[42:43]
	v_lshl_add_u64 v[4:5], s[62:63], 0, v[46:47]
	v_lshl_add_u64 v[2:3], s[60:61], 0, v[40:41]
	s_cmp_lg_u32 s4, 1
	v_lshl_add_u64 v[0:1], s[60:61], 0, v[44:45]
	s_cbranch_scc1 .LBB0_299
	s_barrier
	s_setprio 1

; #define PG8_STAGE(bufoff, gbase, voff) do { _Pragma("unroll") for (int _i = 0; _i < 2; ++_i) \
;         __builtin_amdgcn_global_load_lds((const unsigned*)((const char*)(gbase) + (voff)[_i]), (LAS unsigned*)(lds + (bufoff) + ldsw + _i * 8192), 16, 0, 0); } while (0)
; #define PG8_LDA(dst, b, h) do { _Pragma("unroll") for (int m = 0; m < 4; ++m) _Pragma("unroll") for (int k = 0; k < 2; ++k) dst[m][k] = *(const LAS bf16x8*)(lds + PG8_SA(b, h) + aoff + m * 2048 + k * 1024); } while (0)
; #define PG8_LDB(dst, b, h) do { _Pragma("unroll") for (int n = 0; n < 2; ++n) _Pragma("unroll") for (int k = 0; k < 2; ++k) dst[n][k] = *(const LAS bf16x8*)(lds + PG8_SB(b, h) + boff + n * 2048 + k * 1024); } while (0)
; #define PG8_WAIT_V(n) asm volatile("s_waitcnt vmcnt(" #n ")" ::: "memory")
; #define PG8_WAIT_L(n) asm volatile("s_waitcnt lgkmcnt(" #n ")" ::: "memory")
; #define PG8_BAR __builtin_amdgcn_s_barrier()
; #define PG8_SCHED __builtin_amdgcn_sched_barrier(0)
; template <class Epi, bool ALIGN_EPI = false, bool SP2 = true>
; __device__ __forceinline__ void gemm_phase(LAS unsigned char* lds, const Gemm g, const StaticOrder& S, const Epi& E) {
;     ...
;         const bool has_next = S.next(ui + 1, nxt);
;         const char* nA = has_next ? (const char*)g.A + (size_t)nxt.pm * tstep : cA; const char* nB = has_next ? (const char*)g.Bt + (size_t)(nxt.pn + (nxt.pm >= g.bsplit ? g.badd : 0)) * tstep : cB;
;         for (int t = 0; t < nt; t += 2) {
;             const bool last = (t == nt - 2);
;             const char* a1 = cA + (size_t)(t + 1) * kstep;
;             const char* a2 = last ? nA : cA + (size_t)(t + 2) * kstep; const char* b2 = last ? nB : cB + (size_t)(t + 2) * kstep;
;             const char* a3 = a2 + kstep; const char* b3 = b2 + kstep;
;             if constexpr (SP2) {
;             PG8_LDB(B0, 0, 0); PG8_LDB(B1, 0, 1); PG8_SCHED; PG8_LDA(At, 0, 0); PG8_STAGE(PG8_SA(1, 1), a1 + hstep, voffA);
;             PG8_WAIT_V(8); PG8_WAIT_L(0); PG8_BAR; PG8_MMA(0, 0, At, B0); PG8_MMA(0, 1, At, B1); PG8_BAR; PG8_SCHED;
;             PG8_LDA(At, 0, 1); PG8_STAGE(PG8_SB(0, 0), b2, voffB); PG8_STAGE(PG8_SB(0, 1), b2 + hstep, voffB); PG8_STAGE(PG8_SA(0, 0), a2, voffA);
;             PG8_WAIT_V(8); PG8_WAIT_L(0); PG8_BAR; PG8_MMA(1, 0, At, B0); PG8_MMA(1, 1, At, B1); PG8_BAR; PG8_SCHED;
.LBB0_301:
	s_add_i32 s24, s36, 32
	s_mov_b32 s3, s84
	s_ashr_i32 s25, s24, 31
	s_lshl_b64 s[26:27], s[24:25], 17
	s_add_u32 s26, s70, s26
	ds_read_b128 v[0:3], v70
	ds_read_b128 v[4:7], v70 offset:1024
	ds_read_b128 v[8:11], v70 offset:2048
	ds_read_b128 v[12:15], v70 offset:3072
	ds_read_b128 v[16:19], v71
	ds_read_b128 v[20:23], v71 offset:1024
	ds_read_b128 v[24:27], v71 offset:2048
	ds_read_b128 v[28:31], v71 offset:3072
	v_cmp_lt_i64_e32 vcc, s[22:23], v[48:49]
	s_addc_u32 s27, s71, s27
	s_and_b64 s[28:29], vcc, exec
	s_cselect_b32 s67, s27, s61
	s_cselect_b32 s66, s26, s60
	s_cmp_gt_i32 s24, 31
	s_cselect_b32 s25, 8, 0
	s_add_i32 s28, s25, s3
	s_ashr_i32 s29, s28, 31
	s_lshl_b64 s[28:29], s[28:29], 17
	s_add_u32 s28, s58, s28
	s_addc_u32 s29, s59, s29
	s_and_b64 s[64:65], vcc, exec
	s_cselect_b32 s65, s29, s63
	s_cselect_b32 s64, s28, s62
	s_add_u32 s86, s60, 0x10080
	s_addc_u32 s87, s61, 0
	s_mov_b32 m0, s81
	v_lshl_add_u64 v[94:95], s[86:87], 0, v[40:41]
	ds_read_b128 v[32:35], v72
	ds_read_b128 v[36:39], v72 offset:1024
	ds_read_b128 v[52:55], v72 offset:2048
	ds_read_b128 v[74:77], v72 offset:3072
	ds_read_b128 v[78:81], v72 offset:4096
	ds_read_b128 v[82:85], v72 offset:5120
	ds_read_b128 v[86:89], v72 offset:6144
	ds_read_b128 v[90:93], v72 offset:7168
	global_load_lds_dwordx4 v[94:95], off
	v_lshl_add_u64 v[94:95], s[86:87], 0, v[44:45]
	s_mov_b32 m0, s82
	s_nop 0
	global_load_lds_dwordx4 v[94:95], off
	s_waitcnt vmcnt(8)
	s_waitcnt lgkmcnt(0)
	s_barrier
	s_waitcnt lgkmcnt(0)
	v_mfma_f32_16x16x32_bf16 v[94:97], v[0:3], v[32:35], 0
	v_mfma_f32_16x16x32_bf16 v[98:101], v[8:11], v[32:35], 0
	v_mfma_f32_16x16x32_bf16 v[102:105], v[0:3], v[52:55], 0
	v_mfma_f32_16x16x32_bf16 v[106:109], v[8:11], v[52:55], 0
	v_mfma_f32_16x16x32_bf16 v[110:113], v[0:3], v[78:81], 0
	v_mfma_f32_16x16x32_bf16 v[114:117], v[8:11], v[78:81], 0
	v_mfma_f32_16x16x32_bf16 v[118:121], v[0:3], v[86:89], 0
	v_mfma_f32_16x16x32_bf16 v[122:125], v[8:11], v[86:89], 0
	v_mfma_f32_16x16x32_bf16 v[94:97], v[4:7], v[36:39], v[94:97]
	v_mfma_f32_16x16x32_bf16 v[98:101], v[12:15], v[36:39], v[98:101]
	v_mfma_f32_16x16x32_bf16 v[102:105], v[4:7], v[74:77], v[102:105]
	v_mfma_f32_16x16x32_bf16 v[106:109], v[12:15], v[74:77], v[106:109]
	v_mfma_f32_16x16x32_bf16 v[110:113], v[4:7], v[82:85], v[110:113]
	v_mfma_f32_16x16x32_bf16 v[114:117], v[12:15], v[82:85], v[114:117]
	v_mfma_f32_16x16x32_bf16 v[118:121], v[4:7], v[90:93], v[118:121]
	v_mfma_f32_16x16x32_bf16 v[122:125], v[12:15], v[90:93], v[122:125]
	v_mfma_f32_16x16x32_bf16 v[126:129], v[16:19], v[32:35], 0
	v_mfma_f32_16x16x32_bf16 v[32:35], v[24:27], v[32:35], 0
	v_mfma_f32_16x16x32_bf16 v[126:129], v[20:23], v[36:39], v[126:129]
	v_mfma_f32_16x16x32_bf16 v[32:35], v[28:31], v[36:39], v[32:35]
	v_mfma_f32_16x16x32_bf16 v[36:39], v[16:19], v[52:55], 0
	v_mfma_f32_16x16x32_bf16 v[52:55], v[24:27], v[52:55], 0
	v_mfma_f32_16x16x32_bf16 v[36:39], v[20:23], v[74:77], v[36:39]
	v_mfma_f32_16x16x32_bf16 v[52:55], v[28:31], v[74:77], v[52:55]
	v_mfma_f32_16x16x32_bf16 v[74:77], v[16:19], v[78:81], 0
	v_mfma_f32_16x16x32_bf16 v[78:81], v[24:27], v[78:81], 0
	v_mfma_f32_16x16x32_bf16 v[74:77], v[20:23], v[82:85], v[74:77]
	v_mfma_f32_16x16x32_bf16 v[78:81], v[28:31], v[82:85], v[78:81]
	v_mfma_f32_16x16x32_bf16 v[82:85], v[16:19], v[86:89], 0
	v_mfma_f32_16x16x32_bf16 v[86:89], v[24:27], v[86:89], 0
	v_mfma_f32_16x16x32_bf16 v[82:85], v[20:23], v[90:93], v[82:85]
	v_mfma_f32_16x16x32_bf16 v[86:89], v[28:31], v[90:93], v[86:89]
	s_barrier
	v_lshl_add_u64 v[146:147], s[62:63], 0, v[42:43]
	s_mov_b32 m0, s83
	v_lshl_add_u64 v[162:163], v[146:147], 0, s[6:7]
	s_add_i32 s25, s83, 0x2000
	ds_read_b128 v[90:93], v72 offset:16384
	ds_read_b128 v[130:133], v72 offset:17408
	ds_read_b128 v[134:137], v72 offset:18432
	ds_read_b128 v[138:141], v72 offset:19456
	ds_read_b128 v[142:145], v72 offset:20480
	ds_read_b128 v[150:153], v72 offset:21504
	ds_read_b128 v[154:157], v72 offset:22528
	ds_read_b128 v[158:161], v72 offset:23552
	global_load_lds_dwordx4 v[162:163], off
	v_lshl_add_u64 v[162:163], s[62:63], 0, v[46:47]
	s_add_u32 s86, s62, 0x10100
	v_lshl_add_u64 v[166:167], v[162:163], 0, s[6:7]
	s_mov_b32 m0, s25
	s_addc_u32 s87, s63, 0
	s_add_i32 s85, s80, s69
	global_load_lds_dwordx4 v[166:167], off
	v_lshl_add_u64 v[166:167], s[86:87], 0, v[42:43]
	s_mov_b32 m0, s85
	v_lshl_add_u64 v[232:233], s[60:61], 0, v[40:41]
	global_load_lds_dwordx4 v[166:167], off
	v_lshl_add_u64 v[166:167], s[86:87], 0, v[46:47]
	s_add_i32 s86, s85, 0x2000
	s_mov_b32 m0, s86
	v_lshl_add_u64 v[234:235], s[60:61], 0, v[44:45]
	global_load_lds_dwordx4 v[166:167], off
	v_lshl_add_u64 v[166:167], v[232:233], 0, s[6:7]
	s_mov_b32 m0, s37
	s_nop 0
	global_load_lds_dwordx4 v[166:167], off
	v_lshl_add_u64 v[166:167], v[234:235], 0, s[6:7]
	s_mov_b32 m0, s72
	s_nop 0
	global_load_lds_dwordx4 v[166:167], off
	s_waitcnt vmcnt(8)
	s_waitcnt lgkmcnt(0)
	s_barrier
; #define PG8_STAGE(bufoff, gbase, voff) do { _Pragma("unroll") for (int _i = 0; _i < 2; ++_i) \
;         __builtin_amdgcn_global_load_lds((const unsigned*)((const char*)(gbase) + (voff)[_i]), (LAS unsigned*)(lds + (bufoff) + ldsw + _i * 8192), 16, 0, 0); } while (0)
; #define PG8_LDA(dst, b, h) do { _Pragma("unroll") for (int m = 0; m < 4; ++m) _Pragma("unroll") for (int k = 0; k < 2; ++k) dst[m][k] = *(const LAS bf16x8*)(lds + PG8_SA(b, h) + aoff + m * 2048 + k * 1024); } while (0)
; #define PG8_LDB(dst, b, h) do { _Pragma("unroll") for (int n = 0; n < 2; ++n) _Pragma("unroll") for (int k = 0; k < 2; ++k) dst[n][k] = *(const LAS bf16x8*)(lds + PG8_SB(b, h) + boff + n * 2048 + k * 1024); } while (0)
; #define PG8_MMA(ai, bj, At, Bt) do { __builtin_amdgcn_s_setprio(1); _Pragma("unroll") for (int m = 0; m < 4; ++m) _Pragma("unroll") for (int n = 0; n < 2; ++n) _Pragma("unroll") for (int k = 0; k < 2; ++k) \
;         acc[ai][bj][m][n] = __builtin_amdgcn_mfma_f32_16x16x32_bf16(Bt[n][k], At[m][k], acc[ai][bj][m][n], 0, 0, 0); __builtin_amdgcn_s_setprio(0); } while (0)
; #define PG8_WAIT_V(n) asm volatile("s_waitcnt vmcnt(" #n ")" ::: "memory")
; #define PG8_WAIT_L(n) asm volatile("s_waitcnt lgkmcnt(" #n ")" ::: "memory")
; #define PG8_BAR __builtin_amdgcn_s_barrier()
; #define PG8_SCHED __builtin_amdgcn_sched_barrier(0)
; template <class Epi, bool ALIGN_EPI = false, bool SP2 = true>
; __device__ __forceinline__ void gemm_phase(LAS unsigned char* lds, const Gemm g, const StaticOrder& S, const Epi& E) {
;     ...
;             PG8_WAIT_V(8); PG8_WAIT_L(0); PG8_BAR; PG8_MMA(0, 0, At, B0); PG8_MMA(0, 1, At, B1); PG8_BAR; PG8_SCHED;
;             PG8_LDA(At, 0, 1); PG8_STAGE(PG8_SB(0, 0), b2, voffB); PG8_STAGE(PG8_SB(0, 1), b2 + hstep, voffB); PG8_STAGE(PG8_SA(0, 0), a2, voffA);
;             PG8_WAIT_V(8); PG8_WAIT_L(0); PG8_BAR; PG8_MMA(1, 0, At, B0); PG8_MMA(1, 1, At, B1); PG8_BAR; PG8_SCHED;
;             PG8_LDB(B0, 1, 0); PG8_LDB(B1, 1, 1); PG8_SCHED; PG8_LDA(At, 1, 0); PG8_STAGE(PG8_SA(0, 1), a2 + hstep, voffA);
;             PG8_WAIT_V(8); PG8_WAIT_L(0); PG8_BAR; PG8_MMA(0, 0, At, B0); PG8_MMA(0, 1, At, B1); PG8_BAR; PG8_SCHED;
	s_waitcnt lgkmcnt(0)
	v_mfma_f32_16x16x32_bf16 v[166:169], v[0:3], v[90:93], 0
	v_mfma_f32_16x16x32_bf16 v[174:177], v[0:3], v[134:137], 0
	v_mfma_f32_16x16x32_bf16 v[182:185], v[0:3], v[142:145], 0
	v_mfma_f32_16x16x32_bf16 v[0:3], v[0:3], v[154:157], 0
	v_mfma_f32_16x16x32_bf16 v[166:169], v[4:7], v[130:133], v[166:169]
	v_mfma_f32_16x16x32_bf16 v[170:173], v[8:11], v[90:93], 0
	v_mfma_f32_16x16x32_bf16 v[174:177], v[4:7], v[138:141], v[174:177]
	v_mfma_f32_16x16x32_bf16 v[178:181], v[8:11], v[134:137], 0
	v_mfma_f32_16x16x32_bf16 v[182:185], v[4:7], v[150:153], v[182:185]
	v_mfma_f32_16x16x32_bf16 v[186:189], v[8:11], v[142:145], 0
	v_mfma_f32_16x16x32_bf16 v[0:3], v[4:7], v[158:161], v[0:3]
	v_mfma_f32_16x16x32_bf16 v[4:7], v[8:11], v[154:157], 0
	v_mfma_f32_16x16x32_bf16 v[170:173], v[12:15], v[130:133], v[170:173]
	v_mfma_f32_16x16x32_bf16 v[178:181], v[12:15], v[138:141], v[178:181]
	v_mfma_f32_16x16x32_bf16 v[186:189], v[12:15], v[150:153], v[186:189]
	v_mfma_f32_16x16x32_bf16 v[4:7], v[12:15], v[158:161], v[4:7]
	v_mfma_f32_16x16x32_bf16 v[8:11], v[16:19], v[90:93], 0
	v_mfma_f32_16x16x32_bf16 v[12:15], v[24:27], v[90:93], 0
	v_mfma_f32_16x16x32_bf16 v[8:11], v[20:23], v[130:133], v[8:11]
	v_mfma_f32_16x16x32_bf16 v[12:15], v[28:31], v[130:133], v[12:15]
	v_mfma_f32_16x16x32_bf16 v[90:93], v[16:19], v[134:137], 0
	v_mfma_f32_16x16x32_bf16 v[130:133], v[24:27], v[134:137], 0
	v_mfma_f32_16x16x32_bf16 v[134:137], v[16:19], v[142:145], 0
	v_mfma_f32_16x16x32_bf16 v[16:19], v[16:19], v[154:157], 0
	v_mfma_f32_16x16x32_bf16 v[90:93], v[20:23], v[138:141], v[90:93]
	v_mfma_f32_16x16x32_bf16 v[130:133], v[28:31], v[138:141], v[130:133]
	v_mfma_f32_16x16x32_bf16 v[134:137], v[20:23], v[150:153], v[134:137]
	v_mfma_f32_16x16x32_bf16 v[138:141], v[24:27], v[142:145], 0
	v_mfma_f32_16x16x32_bf16 v[16:19], v[20:23], v[158:161], v[16:19]
	v_mfma_f32_16x16x32_bf16 v[20:23], v[24:27], v[154:157], 0
	v_mfma_f32_16x16x32_bf16 v[138:141], v[28:31], v[150:153], v[138:141]
	v_mfma_f32_16x16x32_bf16 v[20:23], v[28:31], v[158:161], v[20:23]
	s_barrier
	s_add_i32 s87, 0, 0x18000
	s_add_i32 s93, 0, 0x1c000
	v_add_u32_e32 v73, s87, v68
	v_add_u32_e32 v165, s93, v68
	ds_read_b128 v[24:27], v73
	ds_read_b128 v[28:31], v73 offset:1024
	ds_read_b128 v[142:145], v73 offset:2048
	ds_read_b128 v[150:153], v73 offset:3072
	ds_read_b128 v[154:157], v165
	ds_read_b128 v[158:161], v165 offset:1024
	ds_read_b128 v[190:193], v165 offset:2048
	ds_read_b128 v[194:197], v165 offset:3072
	s_add_u32 s88, s60, 0x10100
	s_addc_u32 s89, s61, 0
	s_mov_b32 m0, s73
	v_lshl_add_u64 v[236:237], s[88:89], 0, v[40:41]
	ds_read_b128 v[198:201], v72 offset:32768
	ds_read_b128 v[202:205], v72 offset:33792
	ds_read_b128 v[206:209], v72 offset:34816
	ds_read_b128 v[210:213], v72 offset:35840
	ds_read_b128 v[216:219], v72 offset:36864
	ds_read_b128 v[220:223], v72 offset:37888
	ds_read_b128 v[224:227], v72 offset:38912
	ds_read_b128 v[228:231], v72 offset:39936
	global_load_lds_dwordx4 v[236:237], off
	v_lshl_add_u64 v[236:237], s[88:89], 0, v[44:45]
	s_mov_b32 m0, s74
	s_nop 0
	global_load_lds_dwordx4 v[236:237], off
	s_waitcnt vmcnt(8)
	s_waitcnt lgkmcnt(0)
	s_barrier
	s_waitcnt lgkmcnt(0)
	v_mfma_f32_16x16x32_bf16 v[94:97], v[24:27], v[198:201], v[94:97]
	v_mfma_f32_16x16x32_bf16 v[98:101], v[142:145], v[198:201], v[98:101]
	v_mfma_f32_16x16x32_bf16 v[102:105], v[24:27], v[206:209], v[102:105]
	v_mfma_f32_16x16x32_bf16 v[106:109], v[142:145], v[206:209], v[106:109]
	v_mfma_f32_16x16x32_bf16 v[110:113], v[24:27], v[216:219], v[110:113]
	v_mfma_f32_16x16x32_bf16 v[114:117], v[142:145], v[216:219], v[114:117]
	v_mfma_f32_16x16x32_bf16 v[118:121], v[24:27], v[224:227], v[118:121]
	v_mfma_f32_16x16x32_bf16 v[122:125], v[142:145], v[224:227], v[122:125]
	v_mfma_f32_16x16x32_bf16 v[94:97], v[28:31], v[202:205], v[94:97]
	v_mfma_f32_16x16x32_bf16 v[98:101], v[150:153], v[202:205], v[98:101]
	v_mfma_f32_16x16x32_bf16 v[102:105], v[28:31], v[210:213], v[102:105]
	v_mfma_f32_16x16x32_bf16 v[106:109], v[150:153], v[210:213], v[106:109]
	v_mfma_f32_16x16x32_bf16 v[110:113], v[28:31], v[220:223], v[110:113]
	v_mfma_f32_16x16x32_bf16 v[114:117], v[150:153], v[220:223], v[114:117]
	v_mfma_f32_16x16x32_bf16 v[118:121], v[28:31], v[228:231], v[118:121]
	v_mfma_f32_16x16x32_bf16 v[122:125], v[150:153], v[228:231], v[122:125]
	v_mfma_f32_16x16x32_bf16 v[126:129], v[154:157], v[198:201], v[126:129]
	v_mfma_f32_16x16x32_bf16 v[32:35], v[190:193], v[198:201], v[32:35]
	v_mfma_f32_16x16x32_bf16 v[36:39], v[154:157], v[206:209], v[36:39]
	v_mfma_f32_16x16x32_bf16 v[52:55], v[190:193], v[206:209], v[52:55]
	v_mfma_f32_16x16x32_bf16 v[74:77], v[154:157], v[216:219], v[74:77]
	v_mfma_f32_16x16x32_bf16 v[78:81], v[190:193], v[216:219], v[78:81]
	v_mfma_f32_16x16x32_bf16 v[82:85], v[154:157], v[224:227], v[82:85]
	v_mfma_f32_16x16x32_bf16 v[86:89], v[190:193], v[224:227], v[86:89]
	v_mfma_f32_16x16x32_bf16 v[126:129], v[158:161], v[202:205], v[126:129]
	v_mfma_f32_16x16x32_bf16 v[32:35], v[194:197], v[202:205], v[32:35]
	v_mfma_f32_16x16x32_bf16 v[36:39], v[158:161], v[210:213], v[36:39]
	v_mfma_f32_16x16x32_bf16 v[52:55], v[194:197], v[210:213], v[52:55]
	v_mfma_f32_16x16x32_bf16 v[74:77], v[158:161], v[220:223], v[74:77]
	v_mfma_f32_16x16x32_bf16 v[78:81], v[194:197], v[220:223], v[78:81]
	v_mfma_f32_16x16x32_bf16 v[82:85], v[158:161], v[228:231], v[82:85]
	v_mfma_f32_16x16x32_bf16 v[86:89], v[194:197], v[228:231], v[86:89]
	s_barrier
; #define PG8_STAGE(bufoff, gbase, voff) do { _Pragma("unroll") for (int _i = 0; _i < 2; ++_i) \
;         __builtin_amdgcn_global_load_lds((const unsigned*)((const char*)(gbase) + (voff)[_i]), (LAS unsigned*)(lds + (bufoff) + ldsw + _i * 8192), 16, 0, 0); } while (0)
; #define PG8_LDA(dst, b, h) do { _Pragma("unroll") for (int m = 0; m < 4; ++m) _Pragma("unroll") for (int k = 0; k < 2; ++k) dst[m][k] = *(const LAS bf16x8*)(lds + PG8_SA(b, h) + aoff + m * 2048 + k * 1024); } while (0)
; #define PG8_LDB(dst, b, h) do { _Pragma("unroll") for (int n = 0; n < 2; ++n) _Pragma("unroll") for (int k = 0; k < 2; ++k) dst[n][k] = *(const LAS bf16x8*)(lds + PG8_SB(b, h) + boff + n * 2048 + k * 1024); } while (0)
; #define PG8_MMA(ai, bj, At, Bt) do { __builtin_amdgcn_s_setprio(1); _Pragma("unroll") for (int m = 0; m < 4; ++m) _Pragma("unroll") for (int n = 0; n < 2; ++n) _Pragma("unroll") for (int k = 0; k < 2; ++k) \
;         acc[ai][bj][m][n] = __builtin_amdgcn_mfma_f32_16x16x32_bf16(Bt[n][k], At[m][k], acc[ai][bj][m][n], 0, 0, 0); __builtin_amdgcn_s_setprio(0); } while (0)
; #define PG8_WAIT_V(n) asm volatile("s_waitcnt vmcnt(" #n ")" ::: "memory")
; template <class Epi, bool ALIGN_EPI = false, bool SP2 = true>
; __device__ __forceinline__ void gemm_phase(LAS unsigned char* lds, const Gemm g, const StaticOrder& S, const Epi& E) {
;     ...
;             PG8_LDB(B0, 0, 0); PG8_LDB(B1, 0, 1); PG8_SCHED; PG8_LDA(At, 0, 0); PG8_STAGE(PG8_SA(1, 1), a1 + hstep, voffA);
;             PG8_WAIT_V(8); PG8_WAIT_L(0); PG8_BAR; PG8_MMA(0, 0, At, B0); PG8_MMA(0, 1, At, B1); PG8_BAR; PG8_SCHED;
;             PG8_LDA(At, 0, 1); PG8_STAGE(PG8_SB(0, 0), b2, voffB); PG8_STAGE(PG8_SB(0, 1), b2 + hstep, voffB); PG8_STAGE(PG8_SA(0, 0), a2, voffA);
;             PG8_WAIT_V(8); PG8_WAIT_L(0); PG8_BAR; PG8_MMA(1, 0, At, B0); PG8_MMA(1, 1, At, B1); PG8_BAR; PG8_SCHED;
;             PG8_LDB(B0, 1, 0); PG8_LDB(B1, 1, 1); PG8_SCHED; PG8_LDA(At, 1, 0); PG8_STAGE(PG8_SA(0, 1), a2 + hstep, voffA);
;             PG8_WAIT_V(8); PG8_WAIT_L(0); PG8_BAR; PG8_MMA(0, 0, At, B0); PG8_MMA(0, 1, At, B1); PG8_BAR; PG8_SCHED;
;             PG8_LDA(At, 1, 1); PG8_STAGE(PG8_SB(1, 0), b3, voffB); PG8_STAGE(PG8_SB(1, 1), b3 + hstep, voffB); PG8_STAGE(PG8_SA(1, 0), a3, voffA);
;             PG8_WAIT_V(8); PG8_WAIT_L(0); PG8_BAR; PG8_MMA(1, 0, At, B0); PG8_MMA(1, 1, At, B1); PG8_BAR; PG8_SCHED;
	s_add_i32 s88, s87, s69
	s_add_i32 s87, s88, 0x2000
	v_lshl_add_u64 v[146:147], v[146:147], 0, s[18:19]
	s_mov_b32 m0, s88
	s_add_u32 s90, s62, 0x10180
	ds_read_b128 v[198:201], v72 offset:49152
	ds_read_b128 v[202:205], v72 offset:50176
	ds_read_b128 v[206:209], v72 offset:51200
	ds_read_b128 v[210:213], v72 offset:52224
	ds_read_b128 v[216:219], v72 offset:53248
	ds_read_b128 v[220:223], v72 offset:54272
	ds_read_b128 v[224:227], v72 offset:55296
	ds_read_b128 v[228:231], v72 offset:56320
	global_load_lds_dwordx4 v[146:147], off
	v_lshl_add_u64 v[146:147], v[162:163], 0, s[18:19]
	s_mov_b32 m0, s87
	s_addc_u32 s91, s63, 0
	s_add_i32 s62, s93, s69
	global_load_lds_dwordx4 v[146:147], off
	v_lshl_add_u64 v[146:147], s[90:91], 0, v[42:43]
	s_mov_b32 m0, s62
	s_add_i32 s63, s62, 0x2000
	global_load_lds_dwordx4 v[146:147], off
	v_lshl_add_u64 v[146:147], s[90:91], 0, v[46:47]
	s_mov_b32 m0, s63
	s_nop 0
	global_load_lds_dwordx4 v[146:147], off
	v_lshl_add_u64 v[146:147], v[232:233], 0, s[18:19]
	s_mov_b32 m0, s75
	s_nop 0
	global_load_lds_dwordx4 v[146:147], off
	v_lshl_add_u64 v[146:147], v[234:235], 0, s[18:19]
	s_mov_b32 m0, s76
	s_nop 0
	global_load_lds_dwordx4 v[146:147], off
	s_waitcnt vmcnt(8)
	s_waitcnt lgkmcnt(0)
	s_barrier
	s_waitcnt lgkmcnt(0)
	v_mfma_f32_16x16x32_bf16 v[166:169], v[24:27], v[198:201], v[166:169]
	v_mfma_f32_16x16x32_bf16 v[170:173], v[142:145], v[198:201], v[170:173]
	v_mfma_f32_16x16x32_bf16 v[174:177], v[24:27], v[206:209], v[174:177]
	v_mfma_f32_16x16x32_bf16 v[178:181], v[142:145], v[206:209], v[178:181]
	v_mfma_f32_16x16x32_bf16 v[182:185], v[24:27], v[216:219], v[182:185]
	v_mfma_f32_16x16x32_bf16 v[186:189], v[142:145], v[216:219], v[186:189]
	v_mfma_f32_16x16x32_bf16 v[0:3], v[24:27], v[224:227], v[0:3]
	v_mfma_f32_16x16x32_bf16 v[4:7], v[142:145], v[224:227], v[4:7]
	v_mfma_f32_16x16x32_bf16 v[166:169], v[28:31], v[202:205], v[166:169]
	v_mfma_f32_16x16x32_bf16 v[170:173], v[150:153], v[202:205], v[170:173]
	v_mfma_f32_16x16x32_bf16 v[174:177], v[28:31], v[210:213], v[174:177]
	v_mfma_f32_16x16x32_bf16 v[178:181], v[150:153], v[210:213], v[178:181]
	v_mfma_f32_16x16x32_bf16 v[182:185], v[28:31], v[220:223], v[182:185]
	v_mfma_f32_16x16x32_bf16 v[186:189], v[150:153], v[220:223], v[186:189]
	v_mfma_f32_16x16x32_bf16 v[0:3], v[28:31], v[228:231], v[0:3]
	v_mfma_f32_16x16x32_bf16 v[4:7], v[150:153], v[228:231], v[4:7]
	v_mfma_f32_16x16x32_bf16 v[8:11], v[154:157], v[198:201], v[8:11]
	v_mfma_f32_16x16x32_bf16 v[12:15], v[190:193], v[198:201], v[12:15]
	v_mfma_f32_16x16x32_bf16 v[24:27], v[154:157], v[206:209], v[90:93]
	v_mfma_f32_16x16x32_bf16 v[28:31], v[190:193], v[206:209], v[130:133]
	v_mfma_f32_16x16x32_bf16 v[90:93], v[154:157], v[216:219], v[134:137]
	v_mfma_f32_16x16x32_bf16 v[130:133], v[190:193], v[216:219], v[138:141]
	v_mfma_f32_16x16x32_bf16 v[16:19], v[154:157], v[224:227], v[16:19]
	v_mfma_f32_16x16x32_bf16 v[20:23], v[190:193], v[224:227], v[20:23]
	v_mfma_f32_16x16x32_bf16 v[8:11], v[158:161], v[202:205], v[8:11]
	v_mfma_f32_16x16x32_bf16 v[12:15], v[194:197], v[202:205], v[12:15]
	v_mfma_f32_16x16x32_bf16 v[24:27], v[158:161], v[210:213], v[24:27]
	v_mfma_f32_16x16x32_bf16 v[28:31], v[194:197], v[210:213], v[28:31]
	v_mfma_f32_16x16x32_bf16 v[90:93], v[158:161], v[220:223], v[90:93]
	v_mfma_f32_16x16x32_bf16 v[130:133], v[194:197], v[220:223], v[130:133]
	v_mfma_f32_16x16x32_bf16 v[16:19], v[158:161], v[228:231], v[16:19]
	v_mfma_f32_16x16x32_bf16 v[20:23], v[194:197], v[228:231], v[20:23]
	s_barrier
	ds_read_b128 v[134:137], v70
	ds_read_b128 v[138:141], v70 offset:1024
	ds_read_b128 v[142:145], v70 offset:2048
	ds_read_b128 v[150:153], v70 offset:3072
	ds_read_b128 v[154:157], v71
	ds_read_b128 v[158:161], v71 offset:1024
	ds_read_b128 v[190:193], v71 offset:2048
	ds_read_b128 v[194:197], v71 offset:3072
	s_add_u32 s60, s60, 0x10180
	s_addc_u32 s61, s61, 0
	s_mov_b32 m0, s81
	v_lshl_add_u64 v[146:147], s[60:61], 0, v[40:41]
	ds_read_b128 v[198:201], v72
	ds_read_b128 v[202:205], v72 offset:1024
	ds_read_b128 v[206:209], v72 offset:2048
	ds_read_b128 v[210:213], v72 offset:3072
	ds_read_b128 v[216:219], v72 offset:4096
	ds_read_b128 v[220:223], v72 offset:5120
	ds_read_b128 v[224:227], v72 offset:6144
	ds_read_b128 v[228:231], v72 offset:7168
	global_load_lds_dwordx4 v[146:147], off
	v_lshl_add_u64 v[146:147], s[60:61], 0, v[44:45]
	s_mov_b32 m0, s82
	s_nop 0
	global_load_lds_dwordx4 v[146:147], off
	s_waitcnt vmcnt(8)
	s_waitcnt lgkmcnt(0)
	s_barrier
	s_waitcnt lgkmcnt(0)
	v_mfma_f32_16x16x32_bf16 v[94:97], v[134:137], v[198:201], v[94:97]
	v_mfma_f32_16x16x32_bf16 v[98:101], v[142:145], v[198:201], v[98:101]
	v_mfma_f32_16x16x32_bf16 v[102:105], v[134:137], v[206:209], v[102:105]
	v_mfma_f32_16x16x32_bf16 v[106:109], v[142:145], v[206:209], v[106:109]
	v_mfma_f32_16x16x32_bf16 v[110:113], v[134:137], v[216:219], v[110:113]
	v_mfma_f32_16x16x32_bf16 v[114:117], v[142:145], v[216:219], v[114:117]
	v_mfma_f32_16x16x32_bf16 v[118:121], v[134:137], v[224:227], v[118:121]
	v_mfma_f32_16x16x32_bf16 v[122:125], v[142:145], v[224:227], v[122:125]
	v_mfma_f32_16x16x32_bf16 v[94:97], v[138:141], v[202:205], v[94:97]
	v_mfma_f32_16x16x32_bf16 v[98:101], v[150:153], v[202:205], v[98:101]
	v_mfma_f32_16x16x32_bf16 v[102:105], v[138:141], v[210:213], v[102:105]
	v_mfma_f32_16x16x32_bf16 v[106:109], v[150:153], v[210:213], v[106:109]
	v_mfma_f32_16x16x32_bf16 v[110:113], v[138:141], v[220:223], v[110:113]
	v_mfma_f32_16x16x32_bf16 v[114:117], v[150:153], v[220:223], v[114:117]
	v_mfma_f32_16x16x32_bf16 v[118:121], v[138:141], v[228:231], v[118:121]
	v_mfma_f32_16x16x32_bf16 v[122:125], v[150:153], v[228:231], v[122:125]
	v_mfma_f32_16x16x32_bf16 v[126:129], v[154:157], v[198:201], v[126:129]
	v_mfma_f32_16x16x32_bf16 v[32:35], v[190:193], v[198:201], v[32:35]
	v_mfma_f32_16x16x32_bf16 v[36:39], v[154:157], v[206:209], v[36:39]
	v_mfma_f32_16x16x32_bf16 v[52:55], v[190:193], v[206:209], v[52:55]
	v_mfma_f32_16x16x32_bf16 v[74:77], v[154:157], v[216:219], v[74:77]
	v_mfma_f32_16x16x32_bf16 v[78:81], v[190:193], v[216:219], v[78:81]
	v_mfma_f32_16x16x32_bf16 v[82:85], v[154:157], v[224:227], v[82:85]
	v_mfma_f32_16x16x32_bf16 v[86:89], v[190:193], v[224:227], v[86:89]
	v_mfma_f32_16x16x32_bf16 v[126:129], v[158:161], v[202:205], v[126:129]
	v_mfma_f32_16x16x32_bf16 v[32:35], v[194:197], v[202:205], v[32:35]
	v_mfma_f32_16x16x32_bf16 v[36:39], v[158:161], v[210:213], v[36:39]
	v_mfma_f32_16x16x32_bf16 v[52:55], v[194:197], v[210:213], v[52:55]
	v_mfma_f32_16x16x32_bf16 v[74:77], v[158:161], v[220:223], v[74:77]
	v_mfma_f32_16x16x32_bf16 v[78:81], v[194:197], v[220:223], v[78:81]
	v_mfma_f32_16x16x32_bf16 v[82:85], v[158:161], v[228:231], v[82:85]
	v_mfma_f32_16x16x32_bf16 v[86:89], v[194:197], v[228:231], v[86:89]
	s_barrier
; #define PG8_STAGE(bufoff, gbase, voff) do { _Pragma("unroll") for (int _i = 0; _i < 2; ++_i) \
;         __builtin_amdgcn_global_load_lds((const unsigned*)((const char*)(gbase) + (voff)[_i]), (LAS unsigned*)(lds + (bufoff) + ldsw + _i * 8192), 16, 0, 0); } while (0)
; #define PG8_LDA(dst, b, h) do { _Pragma("unroll") for (int m = 0; m < 4; ++m) _Pragma("unroll") for (int k = 0; k < 2; ++k) dst[m][k] = *(const LAS bf16x8*)(lds + PG8_SA(b, h) + aoff + m * 2048 + k * 1024); } while (0)
; #define PG8_LDB(dst, b, h) do { _Pragma("unroll") for (int n = 0; n < 2; ++n) _Pragma("unroll") for (int k = 0; k < 2; ++k) dst[n][k] = *(const LAS bf16x8*)(lds + PG8_SB(b, h) + boff + n * 2048 + k * 1024); } while (0)
; #define PG8_MMA(ai, bj, At, Bt) do { __builtin_amdgcn_s_setprio(1); _Pragma("unroll") for (int m = 0; m < 4; ++m) _Pragma("unroll") for (int n = 0; n < 2; ++n) _Pragma("unroll") for (int k = 0; k < 2; ++k) \
;         acc[ai][bj][m][n] = __builtin_amdgcn_mfma_f32_16x16x32_bf16(Bt[n][k], At[m][k], acc[ai][bj][m][n], 0, 0, 0); __builtin_amdgcn_s_setprio(0); } while (0)
; #define PG8_WAIT_V(n) asm volatile("s_waitcnt vmcnt(" #n ")" ::: "memory")
; #define PG8_WAIT_L(n) asm volatile("s_waitcnt lgkmcnt(" #n ")" ::: "memory")
; #define PG8_BAR __builtin_amdgcn_s_barrier()
; #define PG8_SCHED __builtin_amdgcn_sched_barrier(0)
; template <class Epi, bool ALIGN_EPI = false, bool SP2 = true>
; __device__ __forceinline__ void gemm_phase(LAS unsigned char* lds, const Gemm g, const StaticOrder& S, const Epi& E) {
;     ...
;             PG8_LDB(B0, 0, 0); PG8_LDB(B1, 0, 1); PG8_SCHED; PG8_LDA(At, 0, 0); PG8_STAGE(PG8_SA(1, 1), a1 + hstep, voffA);
;             PG8_WAIT_V(8); PG8_WAIT_L(0); PG8_BAR; PG8_MMA(0, 0, At, B0); PG8_MMA(0, 1, At, B1); PG8_BAR; PG8_SCHED;
;             PG8_LDA(At, 0, 1); PG8_STAGE(PG8_SB(0, 0), b2, voffB); PG8_STAGE(PG8_SB(0, 1), b2 + hstep, voffB); PG8_STAGE(PG8_SA(0, 0), a2, voffA);
;             PG8_WAIT_V(8); PG8_WAIT_L(0); PG8_BAR; PG8_MMA(1, 0, At, B0); PG8_MMA(1, 1, At, B1); PG8_BAR; PG8_SCHED;
;             PG8_LDB(B0, 1, 0); PG8_LDB(B1, 1, 1); PG8_SCHED; PG8_LDA(At, 1, 0); PG8_STAGE(PG8_SA(0, 1), a2 + hstep, voffA);
;             PG8_WAIT_V(8); PG8_WAIT_L(0); PG8_BAR; PG8_MMA(0, 0, At, B0); PG8_MMA(0, 1, At, B1); PG8_BAR; PG8_SCHED;
	s_mov_b32 m0, s83
	v_lshl_add_u64 v[146:147], s[64:65], 0, v[42:43]
	s_add_u32 s60, s64, 0x10000
	ds_read_b128 v[198:201], v72 offset:16384
	ds_read_b128 v[202:205], v72 offset:17408
	ds_read_b128 v[206:209], v72 offset:18432
	ds_read_b128 v[210:213], v72 offset:19456
	ds_read_b128 v[216:219], v72 offset:20480
	ds_read_b128 v[220:223], v72 offset:21504
	ds_read_b128 v[224:227], v72 offset:22528
	ds_read_b128 v[228:231], v72 offset:23552
	global_load_lds_dwordx4 v[146:147], off
	v_lshl_add_u64 v[162:163], s[64:65], 0, v[46:47]
	s_mov_b32 m0, s25
	s_addc_u32 s61, s65, 0
	global_load_lds_dwordx4 v[162:163], off
	v_lshl_add_u64 v[232:233], s[60:61], 0, v[42:43]
	s_mov_b32 m0, s85
	v_lshl_add_u64 v[244:245], s[66:67], 0, v[40:41]
	global_load_lds_dwordx4 v[232:233], off
	v_lshl_add_u64 v[232:233], s[60:61], 0, v[46:47]
	s_mov_b32 m0, s86
	v_lshl_add_u64 v[246:247], s[66:67], 0, v[44:45]
	global_load_lds_dwordx4 v[232:233], off
	s_mov_b32 m0, s37
	s_nop 0
	global_load_lds_dwordx4 v[244:245], off
	s_mov_b32 m0, s72
	s_nop 0
	global_load_lds_dwordx4 v[246:247], off
	s_waitcnt vmcnt(8)
	s_waitcnt lgkmcnt(0)
	s_barrier
	s_waitcnt lgkmcnt(0)
	v_mfma_f32_16x16x32_bf16 v[166:169], v[134:137], v[198:201], v[166:169]
	v_mfma_f32_16x16x32_bf16 v[170:173], v[142:145], v[198:201], v[170:173]
	v_mfma_f32_16x16x32_bf16 v[174:177], v[134:137], v[206:209], v[174:177]
	v_mfma_f32_16x16x32_bf16 v[178:181], v[142:145], v[206:209], v[178:181]
	v_mfma_f32_16x16x32_bf16 v[182:185], v[134:137], v[216:219], v[182:185]
	v_mfma_f32_16x16x32_bf16 v[186:189], v[142:145], v[216:219], v[186:189]
	v_mfma_f32_16x16x32_bf16 v[0:3], v[134:137], v[224:227], v[0:3]
	v_mfma_f32_16x16x32_bf16 v[4:7], v[142:145], v[224:227], v[4:7]
	v_mfma_f32_16x16x32_bf16 v[166:169], v[138:141], v[202:205], v[166:169]
	v_mfma_f32_16x16x32_bf16 v[170:173], v[150:153], v[202:205], v[170:173]
	v_mfma_f32_16x16x32_bf16 v[174:177], v[138:141], v[210:213], v[174:177]
	v_mfma_f32_16x16x32_bf16 v[178:181], v[150:153], v[210:213], v[178:181]
	v_mfma_f32_16x16x32_bf16 v[182:185], v[138:141], v[220:223], v[182:185]
	v_mfma_f32_16x16x32_bf16 v[186:189], v[150:153], v[220:223], v[186:189]
	v_mfma_f32_16x16x32_bf16 v[0:3], v[138:141], v[228:231], v[0:3]
	v_mfma_f32_16x16x32_bf16 v[4:7], v[150:153], v[228:231], v[4:7]
	v_mfma_f32_16x16x32_bf16 v[8:11], v[154:157], v[198:201], v[8:11]
	v_mfma_f32_16x16x32_bf16 v[134:137], v[158:161], v[202:205], v[8:11]
	v_mfma_f32_16x16x32_bf16 v[8:11], v[190:193], v[198:201], v[12:15]
	v_mfma_f32_16x16x32_bf16 v[12:15], v[194:197], v[202:205], v[8:11]
	v_mfma_f32_16x16x32_bf16 v[8:11], v[154:157], v[206:209], v[24:27]
	v_mfma_f32_16x16x32_bf16 v[138:141], v[158:161], v[210:213], v[8:11]
	v_mfma_f32_16x16x32_bf16 v[8:11], v[190:193], v[206:209], v[28:31]
	v_mfma_f32_16x16x32_bf16 v[28:31], v[194:197], v[210:213], v[8:11]
	v_mfma_f32_16x16x32_bf16 v[8:11], v[154:157], v[216:219], v[90:93]
	v_mfma_f32_16x16x32_bf16 v[90:93], v[158:161], v[220:223], v[8:11]
	v_mfma_f32_16x16x32_bf16 v[8:11], v[190:193], v[216:219], v[130:133]
	v_mfma_f32_16x16x32_bf16 v[130:133], v[194:197], v[220:223], v[8:11]
	v_mfma_f32_16x16x32_bf16 v[8:11], v[154:157], v[224:227], v[16:19]
	v_mfma_f32_16x16x32_bf16 v[142:145], v[158:161], v[228:231], v[8:11]
	v_mfma_f32_16x16x32_bf16 v[8:11], v[190:193], v[224:227], v[20:23]
	v_mfma_f32_16x16x32_bf16 v[150:153], v[194:197], v[228:231], v[8:11]
	s_barrier
	s_nop 4
	ds_read_b128 v[8:11], v73
	ds_read_b128 v[20:23], v73 offset:1024
	ds_read_b128 v[154:157], v73 offset:2048
	ds_read_b128 v[158:161], v73 offset:3072
	ds_read_b128 v[190:193], v165
	ds_read_b128 v[194:197], v165 offset:1024
	ds_read_b128 v[198:201], v165 offset:2048
	ds_read_b128 v[202:205], v165 offset:3072
	s_add_u32 s60, s66, 0x10000
	s_addc_u32 s61, s67, 0
	s_mov_b32 m0, s73
	v_lshl_add_u64 v[232:233], s[60:61], 0, v[40:41]
	ds_read_b128 v[16:19], v72 offset:32768
	ds_read_b128 v[24:27], v72 offset:33792
	ds_read_b128 v[206:209], v72 offset:34816
	ds_read_b128 v[210:213], v72 offset:35840
	ds_read_b128 v[216:219], v72 offset:36864
	ds_read_b128 v[220:223], v72 offset:37888
	ds_read_b128 v[224:227], v72 offset:38912
	ds_read_b128 v[228:231], v72 offset:39936
	global_load_lds_dwordx4 v[232:233], off
	v_lshl_add_u64 v[232:233], s[60:61], 0, v[44:45]
	s_mov_b32 m0, s74
	s_nop 0
	global_load_lds_dwordx4 v[232:233], off
	s_waitcnt vmcnt(8)
	s_waitcnt lgkmcnt(0)
	s_barrier
	s_waitcnt lgkmcnt(0)
	v_mfma_f32_16x16x32_bf16 v[94:97], v[8:11], v[16:19], v[94:97]
	v_mfma_f32_16x16x32_bf16 v[98:101], v[154:157], v[16:19], v[98:101]
	v_mfma_f32_16x16x32_bf16 v[102:105], v[8:11], v[206:209], v[102:105]
	v_mfma_f32_16x16x32_bf16 v[106:109], v[154:157], v[206:209], v[106:109]
	v_mfma_f32_16x16x32_bf16 v[110:113], v[8:11], v[216:219], v[110:113]
	v_mfma_f32_16x16x32_bf16 v[114:117], v[154:157], v[216:219], v[114:117]
	v_mfma_f32_16x16x32_bf16 v[118:121], v[8:11], v[224:227], v[118:121]
	v_mfma_f32_16x16x32_bf16 v[122:125], v[154:157], v[224:227], v[122:125]
	v_mfma_f32_16x16x32_bf16 v[94:97], v[20:23], v[24:27], v[94:97]
	v_mfma_f32_16x16x32_bf16 v[98:101], v[158:161], v[24:27], v[98:101]
	v_mfma_f32_16x16x32_bf16 v[102:105], v[20:23], v[210:213], v[102:105]
	v_mfma_f32_16x16x32_bf16 v[106:109], v[158:161], v[210:213], v[106:109]
	v_mfma_f32_16x16x32_bf16 v[110:113], v[20:23], v[220:223], v[110:113]
	v_mfma_f32_16x16x32_bf16 v[114:117], v[158:161], v[220:223], v[114:117]
	v_mfma_f32_16x16x32_bf16 v[118:121], v[20:23], v[228:231], v[118:121]
	v_mfma_f32_16x16x32_bf16 v[122:125], v[158:161], v[228:231], v[122:125]
	v_mfma_f32_16x16x32_bf16 v[126:129], v[190:193], v[16:19], v[126:129]
	v_mfma_f32_16x16x32_bf16 v[16:19], v[198:201], v[16:19], v[32:35]
	v_mfma_f32_16x16x32_bf16 v[232:235], v[202:205], v[24:27], v[16:19]
	v_mfma_f32_16x16x32_bf16 v[16:19], v[190:193], v[206:209], v[36:39]
	v_mfma_f32_16x16x32_bf16 v[236:239], v[194:197], v[210:213], v[16:19]
	v_mfma_f32_16x16x32_bf16 v[16:19], v[198:201], v[206:209], v[52:55]
	v_mfma_f32_16x16x32_bf16 v[206:209], v[202:205], v[210:213], v[16:19]
	v_mfma_f32_16x16x32_bf16 v[16:19], v[190:193], v[216:219], v[74:77]
	v_mfma_f32_16x16x32_bf16 v[74:77], v[194:197], v[220:223], v[16:19]
	v_mfma_f32_16x16x32_bf16 v[16:19], v[198:201], v[216:219], v[78:81]
	v_mfma_f32_16x16x32_bf16 v[78:81], v[202:205], v[220:223], v[16:19]
	v_mfma_f32_16x16x32_bf16 v[16:19], v[190:193], v[224:227], v[82:85]
	v_mfma_f32_16x16x32_bf16 v[82:85], v[194:197], v[228:231], v[16:19]
	v_mfma_f32_16x16x32_bf16 v[16:19], v[198:201], v[224:227], v[86:89]
	v_mfma_f32_16x16x32_bf16 v[126:129], v[194:197], v[24:27], v[126:129]
	v_mfma_f32_16x16x32_bf16 v[86:89], v[202:205], v[228:231], v[16:19]
	s_barrier
; #define PG8_STAGE(bufoff, gbase, voff) do { _Pragma("unroll") for (int _i = 0; _i < 2; ++_i) \
;         __builtin_amdgcn_global_load_lds((const unsigned*)((const char*)(gbase) + (voff)[_i]), (LAS unsigned*)(lds + (bufoff) + ldsw + _i * 8192), 16, 0, 0); } while (0)
; #define PG8_LDA(dst, b, h) do { _Pragma("unroll") for (int m = 0; m < 4; ++m) _Pragma("unroll") for (int k = 0; k < 2; ++k) dst[m][k] = *(const LAS bf16x8*)(lds + PG8_SA(b, h) + aoff + m * 2048 + k * 1024); } while (0)
; #define PG8_LDB(dst, b, h) do { _Pragma("unroll") for (int n = 0; n < 2; ++n) _Pragma("unroll") for (int k = 0; k < 2; ++k) dst[n][k] = *(const LAS bf16x8*)(lds + PG8_SB(b, h) + boff + n * 2048 + k * 1024); } while (0)
; #define PG8_MMA(ai, bj, At, Bt) do { __builtin_amdgcn_s_setprio(1); _Pragma("unroll") for (int m = 0; m < 4; ++m) _Pragma("unroll") for (int n = 0; n < 2; ++n) _Pragma("unroll") for (int k = 0; k < 2; ++k) \
;         acc[ai][bj][m][n] = __builtin_amdgcn_mfma_f32_16x16x32_bf16(Bt[n][k], At[m][k], acc[ai][bj][m][n], 0, 0, 0); __builtin_amdgcn_s_setprio(0); } while (0)
; #define PG8_WAIT_V(n) asm volatile("s_waitcnt vmcnt(" #n ")" ::: "memory")
; #define PG8_WAIT_L(n) asm volatile("s_waitcnt lgkmcnt(" #n ")" ::: "memory")
; #define PG8_BAR __builtin_amdgcn_s_barrier()
; #define PG8_SCHED __builtin_amdgcn_sched_barrier(0)
; template <class Epi, bool ALIGN_EPI = false, bool SP2 = true>
; __device__ __forceinline__ void gemm_phase(LAS unsigned char* lds, const Gemm g, const StaticOrder& S, const Epi& E) {
;     ...
;             PG8_LDB(B0, 1, 0); PG8_LDB(B1, 1, 1); PG8_SCHED; PG8_LDA(At, 1, 0); PG8_STAGE(PG8_SA(0, 1), a2 + hstep, voffA);
;             PG8_WAIT_V(8); PG8_WAIT_L(0); PG8_BAR; PG8_MMA(0, 0, At, B0); PG8_MMA(0, 1, At, B1); PG8_BAR; PG8_SCHED;
;             PG8_LDA(At, 1, 1); PG8_STAGE(PG8_SB(1, 0), b3, voffB); PG8_STAGE(PG8_SB(1, 1), b3 + hstep, voffB); PG8_STAGE(PG8_SA(1, 0), a3, voffA);
;             PG8_WAIT_V(8); PG8_WAIT_L(0); PG8_BAR; PG8_MMA(1, 0, At, B0); PG8_MMA(1, 1, At, B1); PG8_BAR; PG8_SCHED;
	s_mov_b32 m0, s88
	s_nop 2
	v_lshl_add_u64 v[16:17], v[146:147], 0, s[0:1]
	s_add_u32 s60, s64, 0x10080
	ds_read_b128 v[36:39], v72 offset:49152
	ds_read_b128 v[52:55], v72 offset:50176
	ds_read_b128 v[210:213], v72 offset:51200
	ds_read_b128 v[216:219], v72 offset:52224
	ds_read_b128 v[220:223], v72 offset:53248
	ds_read_b128 v[224:227], v72 offset:54272
	ds_read_b128 v[228:231], v72 offset:55296
	ds_read_b128 v[240:243], v72 offset:56320
	global_load_lds_dwordx4 v[16:17], off
	v_lshl_add_u64 v[16:17], v[162:163], 0, s[0:1]
	s_mov_b32 m0, s87
	s_addc_u32 s61, s65, 0
	global_load_lds_dwordx4 v[16:17], off
	v_lshl_add_u64 v[16:17], s[60:61], 0, v[42:43]
	s_mov_b32 m0, s62
	s_nop 0
	global_load_lds_dwordx4 v[16:17], off
	v_lshl_add_u64 v[16:17], s[60:61], 0, v[46:47]
	s_mov_b32 m0, s63
	s_nop 0
	global_load_lds_dwordx4 v[16:17], off
	v_lshl_add_u64 v[16:17], v[244:245], 0, s[0:1]
	s_mov_b32 m0, s75
	s_nop 0
	global_load_lds_dwordx4 v[16:17], off
	v_lshl_add_u64 v[16:17], v[246:247], 0, s[0:1]
	s_mov_b32 m0, s76
	s_nop 0
	global_load_lds_dwordx4 v[16:17], off
	s_waitcnt vmcnt(8)
	s_waitcnt lgkmcnt(0)
	s_barrier
	s_waitcnt lgkmcnt(0)
	v_mfma_f32_16x16x32_bf16 v[16:19], v[8:11], v[36:39], v[166:169]
	v_mfma_f32_16x16x32_bf16 v[166:169], v[20:23], v[52:55], v[16:19]
	v_mfma_f32_16x16x32_bf16 v[16:19], v[154:157], v[36:39], v[170:173]
	v_mfma_f32_16x16x32_bf16 v[170:173], v[158:161], v[52:55], v[16:19]
	v_mfma_f32_16x16x32_bf16 v[16:19], v[8:11], v[210:213], v[174:177]
	v_mfma_f32_16x16x32_bf16 v[174:177], v[20:23], v[216:219], v[16:19]
	v_mfma_f32_16x16x32_bf16 v[16:19], v[154:157], v[210:213], v[178:181]
	v_mfma_f32_16x16x32_bf16 v[32:35], v[158:161], v[216:219], v[16:19]
	v_mfma_f32_16x16x32_bf16 v[16:19], v[8:11], v[220:223], v[182:185]
	v_mfma_f32_16x16x32_bf16 v[0:3], v[8:11], v[228:231], v[0:3]
	v_mfma_f32_16x16x32_bf16 v[24:27], v[20:23], v[224:227], v[16:19]
	v_mfma_f32_16x16x32_bf16 v[16:19], v[154:157], v[220:223], v[186:189]
	v_mfma_f32_16x16x32_bf16 v[8:11], v[20:23], v[240:243], v[0:3]
	v_mfma_f32_16x16x32_bf16 v[0:3], v[154:157], v[228:231], v[4:7]
	v_mfma_f32_16x16x32_bf16 v[16:19], v[158:161], v[224:227], v[16:19]
	v_mfma_f32_16x16x32_bf16 v[0:3], v[158:161], v[240:243], v[0:3]
	v_mfma_f32_16x16x32_bf16 v[4:7], v[190:193], v[36:39], v[134:137]
	v_mfma_f32_16x16x32_bf16 v[134:137], v[194:197], v[52:55], v[4:7]
	v_mfma_f32_16x16x32_bf16 v[4:7], v[198:201], v[36:39], v[12:15]
	v_mfma_f32_16x16x32_bf16 v[154:157], v[202:205], v[52:55], v[4:7]
	v_mfma_f32_16x16x32_bf16 v[4:7], v[190:193], v[210:213], v[138:141]
	v_mfma_f32_16x16x32_bf16 v[138:141], v[194:197], v[216:219], v[4:7]
	v_mfma_f32_16x16x32_bf16 v[4:7], v[198:201], v[210:213], v[28:31]
	v_mfma_f32_16x16x32_bf16 v[36:39], v[202:205], v[216:219], v[4:7]
	v_mfma_f32_16x16x32_bf16 v[4:7], v[190:193], v[220:223], v[90:93]
	v_mfma_f32_16x16x32_bf16 v[28:31], v[194:197], v[224:227], v[4:7]
	v_mfma_f32_16x16x32_bf16 v[4:7], v[198:201], v[220:223], v[130:133]
	v_mfma_f32_16x16x32_bf16 v[20:23], v[202:205], v[224:227], v[4:7]
	v_mfma_f32_16x16x32_bf16 v[4:7], v[190:193], v[228:231], v[142:145]
	v_mfma_f32_16x16x32_bf16 v[12:15], v[194:197], v[240:243], v[4:7]
	v_mfma_f32_16x16x32_bf16 v[4:7], v[198:201], v[228:231], v[150:153]
	v_mfma_f32_16x16x32_bf16 v[4:7], v[202:205], v[240:243], v[4:7]
	s_barrier
; __device__ __forceinline__ u32x4 pack8(const f32x4 a, const f32x4 b) { u32x4 w; w.x = cvt_pk_bf16(a[0], a[1]); w.y = cvt_pk_bf16(a[2], a[3]); w.z = cvt_pk_bf16(b[0], b[1]); w.w = cvt_pk_bf16(b[2], b[3]); return w; }
;     __device__ __forceinline__ void operator()(const Acc& acc, const Unit& u, int wr, int wc, int fr, int fq) const {
;         const int cb = u.pn * 256 + wc * 32 + 8 * fq;
;         bf16_t* Ob = O + (u.pm >= 32 ? delta2 - (long long)32 * 256 * DM : 0ll);
; #pragma unroll
;         for (int ai = 0; ai < 2; ++ai)
; #pragma unroll
;             for (int m = 0; m < 4; ++m) {
;                 const int row = u.pm * 256 + ai * 128 + wr * 64 + m * 16 + fr;
; #pragma unroll
;                 for (int bj = 0; bj < 2; ++bj) *(u32x4*)(Ob + (size_t)row * DM + cb + bj * 128) = pack8(acc[ai][bj][m][0], acc[ai][bj][m][1]);
;             }
;     }
	s_cmp_gt_i32 s36, 31
	s_cselect_b32 s25, 0x3800000, 0
	v_lshl_or_b32 v52, s84, 8, v69
	s_add_u32 s60, s8, s25
	v_lshl_add_u32 v54, s36, 8, v67
	s_addc_u32 s61, s9, 0
	v_ashrrev_i32_e32 v53, 31, v52
	v_ashrrev_i32_e32 v55, 31, v54
	v_lshl_add_u64 v[52:53], v[52:53], 1, s[60:61]
	v_lshlrev_b64 v[90:91], 12, v[54:55]
	v_lshl_add_u64 v[130:131], v[52:53], 0, v[90:91]
	v_cvt_pk_bf16_f32 v90, v94, v95
	v_cvt_pk_bf16_f32 v91, v96, v97
	v_cvt_pk_bf16_f32 v92, v98, v99
	v_cvt_pk_bf16_f32 v93, v100, v101
	global_store_dwordx4 v[130:131], v[90:93], off
	s_add_i32 s79, s79, s34
	s_andn2_b64 vcc, exec, s[4:5]
	v_cvt_pk_bf16_f32 v90, v126, v127
	v_cvt_pk_bf16_f32 v91, v128, v129
	v_cvt_pk_bf16_f32 v92, v232, v233
	v_cvt_pk_bf16_f32 v93, v234, v235
	global_store_dwordx4 v[130:131], v[90:93], off offset:256
	s_mov_b32 s84, s3
	s_mov_b32 s36, s24
	v_or_b32_e32 v90, 16, v54
	v_ashrrev_i32_e32 v91, 31, v90
	v_lshlrev_b64 v[90:91], 12, v[90:91]
	v_lshl_add_u64 v[94:95], v[52:53], 0, v[90:91]
	v_cvt_pk_bf16_f32 v90, v102, v103
	v_cvt_pk_bf16_f32 v91, v104, v105
	v_cvt_pk_bf16_f32 v92, v106, v107
	v_cvt_pk_bf16_f32 v93, v108, v109
	global_store_dwordx4 v[94:95], v[90:93], off
	s_mov_b64 s[62:63], s[28:29]
	s_mov_b64 s[60:61], s[26:27]
	v_cvt_pk_bf16_f32 v90, v236, v237
	v_cvt_pk_bf16_f32 v91, v238, v239
	v_cvt_pk_bf16_f32 v92, v206, v207
	v_cvt_pk_bf16_f32 v93, v208, v209
	global_store_dwordx4 v[94:95], v[90:93], off offset:256
	s_nop 1
	v_or_b32_e32 v90, 32, v54
	v_ashrrev_i32_e32 v91, 31, v90
	v_lshlrev_b64 v[90:91], 12, v[90:91]
	v_lshl_add_u64 v[94:95], v[52:53], 0, v[90:91]
	v_cvt_pk_bf16_f32 v90, v110, v111
	v_cvt_pk_bf16_f32 v91, v112, v113
	v_cvt_pk_bf16_f32 v92, v114, v115
	v_cvt_pk_bf16_f32 v93, v116, v117
	global_store_dwordx4 v[94:95], v[90:93], off
	v_cvt_pk_bf16_f32 v74, v74, v75
	v_cvt_pk_bf16_f32 v75, v76, v77
	v_cvt_pk_bf16_f32 v76, v78, v79
	v_cvt_pk_bf16_f32 v77, v80, v81
	global_store_dwordx4 v[94:95], v[74:77], off offset:256
	s_nop 1
	v_or_b32_e32 v74, 48, v54
	v_ashrrev_i32_e32 v75, 31, v74
	v_lshlrev_b64 v[74:75], 12, v[74:75]
	v_lshl_add_u64 v[78:79], v[52:53], 0, v[74:75]
	v_cvt_pk_bf16_f32 v74, v118, v119
	v_cvt_pk_bf16_f32 v75, v120, v121
	v_cvt_pk_bf16_f32 v76, v122, v123
	v_cvt_pk_bf16_f32 v77, v124, v125
	global_store_dwordx4 v[78:79], v[74:77], off
	s_nop 1
	v_cvt_pk_bf16_f32 v74, v82, v83
	v_cvt_pk_bf16_f32 v75, v84, v85
	v_cvt_pk_bf16_f32 v76, v86, v87
	v_cvt_pk_bf16_f32 v77, v88, v89
	global_store_dwordx4 v[78:79], v[74:77], off offset:256
	s_nop 1
	v_add_u32_e32 v74, 0x80, v54
	v_ashrrev_i32_e32 v75, 31, v74
	v_lshlrev_b64 v[74:75], 12, v[74:75]
	v_lshl_add_u64 v[78:79], v[52:53], 0, v[74:75]
	v_cvt_pk_bf16_f32 v74, v166, v167
	v_cvt_pk_bf16_f32 v75, v168, v169
	v_cvt_pk_bf16_f32 v76, v170, v171
	v_cvt_pk_bf16_f32 v77, v172, v173
	global_store_dwordx4 v[78:79], v[74:77], off
	s_nop 1
	v_cvt_pk_bf16_f32 v74, v134, v135
	v_cvt_pk_bf16_f32 v75, v136, v137
	v_cvt_pk_bf16_f32 v76, v154, v155
	v_cvt_pk_bf16_f32 v77, v156, v157
	global_store_dwordx4 v[78:79], v[74:77], off offset:256
	s_nop 1
	v_add_u32_e32 v74, 0x90, v54
	v_ashrrev_i32_e32 v75, 31, v74
	v_lshlrev_b64 v[74:75], 12, v[74:75]
	v_lshl_add_u64 v[78:79], v[52:53], 0, v[74:75]
	v_cvt_pk_bf16_f32 v74, v174, v175
	v_cvt_pk_bf16_f32 v75, v176, v177
	v_cvt_pk_bf16_f32 v76, v32, v33
	v_cvt_pk_bf16_f32 v77, v34, v35
	global_store_dwordx4 v[78:79], v[74:77], off
	v_cvt_pk_bf16_f32 v32, v138, v139
	v_cvt_pk_bf16_f32 v33, v140, v141
	v_cvt_pk_bf16_f32 v34, v36, v37
	v_cvt_pk_bf16_f32 v35, v38, v39
	global_store_dwordx4 v[78:79], v[32:35], off offset:256
	v_cvt_pk_bf16_f32 v24, v24, v25
	v_cvt_pk_bf16_f32 v25, v26, v27
	v_cvt_pk_bf16_f32 v26, v16, v17
	v_cvt_pk_bf16_f32 v27, v18, v19
	s_nop 1
	v_add_u32_e32 v32, 0xa0, v54
	v_ashrrev_i32_e32 v33, 31, v32
	v_lshlrev_b64 v[32:33], 12, v[32:33]
	v_lshl_add_u64 v[32:33], v[52:53], 0, v[32:33]
	global_store_dwordx4 v[32:33], v[24:27], off
	v_cvt_pk_bf16_f32 v16, v28, v29
	v_cvt_pk_bf16_f32 v17, v30, v31
	v_cvt_pk_bf16_f32 v18, v20, v21
	v_cvt_pk_bf16_f32 v19, v22, v23
	global_store_dwordx4 v[32:33], v[16:19], off offset:256
	v_cvt_pk_bf16_f32 v8, v8, v9
	v_cvt_pk_bf16_f32 v9, v10, v11
	v_cvt_pk_bf16_f32 v10, v0, v1
	v_cvt_pk_bf16_f32 v11, v2, v3
	s_nop 1
	v_add_u32_e32 v16, 0xb0, v54
	v_ashrrev_i32_e32 v17, 31, v16
	v_lshlrev_b64 v[16:17], 12, v[16:17]
	v_lshl_add_u64 v[16:17], v[52:53], 0, v[16:17]
	global_store_dwordx4 v[16:17], v[8:11], off
	v_cvt_pk_bf16_f32 v0, v12, v13
	v_cvt_pk_bf16_f32 v1, v14, v15
	v_cvt_pk_bf16_f32 v2, v4, v5
	v_cvt_pk_bf16_f32 v3, v6, v7
	global_store_dwordx4 v[16:17], v[0:3], off offset:256
	s_cbranch_vccz .LBB0_307

; #define PG8_STAGE(bufoff, gbase, voff) do { _Pragma("unroll") for (int _i = 0; _i < 2; ++_i) \
;         __builtin_amdgcn_global_load_lds((const unsigned*)((const char*)(gbase) + (voff)[_i]), (LAS unsigned*)(lds + (bufoff) + ldsw + _i * 8192), 16, 0, 0); } while (0)
; #define PG8_WAIT_V(n) asm volatile("s_waitcnt vmcnt(" #n ")" ::: "memory")
; #define PG8_BAR __builtin_amdgcn_s_barrier()
;     __device__ bool next(int i, Unit& u) const {
;         const long L = (long)i * G + c; if (L >= nwg) return false;
;         int wgid = (int)L; { const int q = nwg / NXCD, r = nwg % NXCD, xcd = wgid % NXCD, off = wgid / NXCD; wgid = (xcd < r ? xcd * (q + 1) : r * (q + 1) + (xcd - r) * q) + off; }
;         const int nig = WGM * nN, gid = wgid / nig, fm = gid * WGM, gsz = (nM - fm) < WGM ? (nM - fm) : WGM;
;         u.pm = fm + ((wgid % nig) % gsz); u.pn = (wgid % nig) / gsz; return true;
; template <class Epi, bool ALIGN_EPI = false, bool SP2 = true>
; __device__ __forceinline__ void gemm_phase(LAS unsigned char* lds, const Gemm g, const StaticOrder& S, const Epi& E) {
;     ...
;     const char* cA = (const char*)g.A + (size_t)cur.pm * tstep; const char* cB = (const char*)g.Bt + (size_t)(cur.pn + (cur.pm >= g.bsplit ? g.badd : 0)) * tstep;
;     if constexpr (SP2) {
;         PG8_STAGE(PG8_SB(0, 0), cB, voffB); PG8_STAGE(PG8_SB(0, 1), cB + hstep, voffB); PG8_STAGE(PG8_SA(0, 0), cA, voffA); PG8_STAGE(PG8_SA(0, 1), cA + hstep, voffA);
;         if (wr == 1) PG8_BAR;
;         PG8_WAIT_V(2); PG8_BAR;
;         PG8_STAGE(PG8_SB(1, 0), cB + kstep, voffB); PG8_STAGE(PG8_SA(1, 0), cA + kstep, voffA); PG8_STAGE(PG8_SB(1, 1), cB + hstep + kstep, voffB);
;         PG8_WAIT_V(6); PG8_BAR;
.LBB0_315:
	s_ashr_i32 s0, s4, 3
	s_add_i32 s0, s6, s0
	s_ashr_i32 s1, s0, 31
	s_lshr_b32 s1, s1, 27
	s_add_i32 s1, s0, s1
	s_ashr_i32 s4, s1, 5
	s_andn2_b32 s1, s1, 31
	s_sub_i32 s0, s0, s1
	s_bfe_i32 s1, s0, 0x80000
	s_bfe_u32 s1, s1, 0x2000d
	s_add_i32 s1, s0, s1
	s_lshl_b32 s6, s4, 2
	s_bfe_i32 s4, s1, 0x80000
	s_and_b32 s1, s1, 0xfc
	s_sub_i32 s0, s0, s1
	s_sext_i32_i16 s4, s4
	s_sext_i32_i8 s0, s0
	s_lshr_b32 s5, s3, 8
	s_lshr_b32 s4, s4, 2
	s_add_i32 s18, s6, s0
	s_lshr_b32 s23, s3, 6
	s_ashr_i32 s19, s18, 31
	s_bfe_i64 s[6:7], s[4:5], 0x100000
	s_lshl_b32 s67, s23, 10
	s_lshl_b64 s[0:1], s[18:19], 20
	s_lshl_b64 s[6:7], s[6:7], 20
	s_add_u32 s60, s56, s6
	s_addc_u32 s61, s57, s7
	s_add_i32 s68, s67, 0
	v_lshl_or_b32 v130, v64, 12, v62
	s_add_i32 m0, s68, 0x10000
	v_lshl_or_b32 v134, v66, 12, v62
	global_load_lds_dwordx4 v130, s[60:61]
	s_add_i32 m0, s68, 0x12000
	s_add_u32 s6, s60, 0x80000
	global_load_lds_dwordx4 v134, s[60:61]
	s_addc_u32 s7, s61, 0
	s_add_i32 m0, s68, 0x14000
	v_lshl_or_b32 v128, v63, 12, v62
	global_load_lds_dwordx4 v130, s[6:7]
	s_add_i32 m0, s68, 0x16000
	s_add_u32 s0, s38, s0
	s_addc_u32 s1, s39, s1
	s_add_i32 s69, s68, 0x2000
	global_load_lds_dwordx4 v134, s[6:7]
	s_mov_b32 m0, s68
	s_add_u32 s6, s0, 0x80000
	v_lshl_or_b32 v132, v65, 12, v62
	global_load_lds_dwordx4 v128, s[0:1]
	s_mov_b32 m0, s69
	s_addc_u32 s7, s1, 0
	s_add_i32 s70, s68, 0x4000
	global_load_lds_dwordx4 v132, s[0:1]
	s_mov_b32 m0, s70
	s_add_i32 s71, s68, 0x6000
	global_load_lds_dwordx4 v128, s[6:7]
	s_mov_b32 m0, s71
	v_mov_b32_e32 v131, 0
	global_load_lds_dwordx4 v132, s[6:7]
	v_mov_b32_e32 v135, v131
	v_mov_b32_e32 v129, v131
	v_mov_b32_e32 v133, v131
	v_lshl_add_u64 v[6:7], s[60:61], 0, v[130:131]
	v_lshl_add_u64 v[4:5], s[60:61], 0, v[134:135]
	v_lshl_add_u64 v[2:3], s[0:1], 0, v[128:129]
	s_cmp_lg_u32 s5, 1
	v_lshl_add_u64 v[0:1], s[0:1], 0, v[132:133]
	s_cbranch_scc1 .LBB0_317
	s_barrier
	s_setprio 1

; #define PG8_STAGE(bufoff, gbase, voff) do { _Pragma("unroll") for (int _i = 0; _i < 2; ++_i) \
;         __builtin_amdgcn_global_load_lds((const unsigned*)((const char*)(gbase) + (voff)[_i]), (LAS unsigned*)(lds + (bufoff) + ldsw + _i * 8192), 16, 0, 0); } while (0)
; #define PG8_LDA(dst, b, h) do { _Pragma("unroll") for (int m = 0; m < 4; ++m) _Pragma("unroll") for (int k = 0; k < 2; ++k) dst[m][k] = *(const LAS bf16x8*)(lds + PG8_SA(b, h) + aoff + m * 2048 + k * 1024); } while (0)
; #define PG8_LDB(dst, b, h) do { _Pragma("unroll") for (int n = 0; n < 2; ++n) _Pragma("unroll") for (int k = 0; k < 2; ++k) dst[n][k] = *(const LAS bf16x8*)(lds + PG8_SB(b, h) + boff + n * 2048 + k * 1024); } while (0)
; #define PG8_WAIT_V(n) asm volatile("s_waitcnt vmcnt(" #n ")" ::: "memory")
; #define PG8_WAIT_L(n) asm volatile("s_waitcnt lgkmcnt(" #n ")" ::: "memory")
; #define PG8_BAR __builtin_amdgcn_s_barrier()
; #define PG8_SCHED __builtin_amdgcn_sched_barrier(0)
; template <class Epi, bool ALIGN_EPI = false, bool SP2 = true>
; __device__ __forceinline__ void gemm_phase(LAS unsigned char* lds, const Gemm g, const StaticOrder& S, const Epi& E) {
;     ...
;         const bool has_next = S.next(ui + 1, nxt);
;         const char* nA = has_next ? (const char*)g.A + (size_t)nxt.pm * tstep : cA; const char* nB = has_next ? (const char*)g.Bt + (size_t)(nxt.pn + (nxt.pm >= g.bsplit ? g.badd : 0)) * tstep : cB;
;         for (int t = 0; t < nt; t += 2) {
;             const bool last = (t == nt - 2);
;             const char* a1 = cA + (size_t)(t + 1) * kstep;
;             const char* a2 = last ? nA : cA + (size_t)(t + 2) * kstep; const char* b2 = last ? nB : cB + (size_t)(t + 2) * kstep;
;             const char* a3 = a2 + kstep; const char* b3 = b2 + kstep;
;             if constexpr (SP2) {
;             PG8_LDB(B0, 0, 0); PG8_LDB(B1, 0, 1); PG8_SCHED; PG8_LDA(At, 0, 0); PG8_STAGE(PG8_SA(1, 1), a1 + hstep, voffA);
;             PG8_WAIT_V(8); PG8_WAIT_L(0); PG8_BAR; PG8_MMA(0, 0, At, B0); PG8_MMA(0, 1, At, B1); PG8_BAR; PG8_SCHED;
;             PG8_LDA(At, 0, 1); PG8_STAGE(PG8_SB(0, 0), b2, voffB); PG8_STAGE(PG8_SB(0, 1), b2 + hstep, voffB); PG8_STAGE(PG8_SA(0, 0), a2, voffA);
;             PG8_WAIT_V(8); PG8_WAIT_L(0); PG8_BAR; PG8_MMA(1, 0, At, B0); PG8_MMA(1, 1, At, B1); PG8_BAR; PG8_SCHED;
.LBB0_325:
	v_add_u32_e32 v161, s76, v150
	s_waitcnt lgkmcnt(0)
	ds_read_b128 v[152:155], v161
	ds_read_b128 v[156:159], v161 offset:1024
	ds_read_b128 v[166:169], v161 offset:2048
	ds_read_b128 v[170:173], v161 offset:3072
	v_add_u32_e32 v161, s77, v150
	s_add_u32 s62, s0, s60
	ds_read_b128 v[174:177], v161
	ds_read_b128 v[178:181], v161 offset:1024
	ds_read_b128 v[182:185], v161 offset:2048
	ds_read_b128 v[186:189], v161 offset:3072
	s_addc_u32 s63, s1, s61
	s_add_u32 s62, s62, 0x100
	s_addc_u32 s63, s63, 0
	s_add_u32 s84, s79, s60
	s_addc_u32 s85, s80, s61
	s_cmpk_eq_i32 s60, 0xf00
	s_cselect_b32 s65, s29, s63
	s_cselect_b32 s64, s81, s62
	s_cselect_b32 s63, s27, s85
	s_cselect_b32 s62, s82, s84
	v_lshl_add_u64 v[162:163], v[144:145], 0, s[60:61]
	s_add_i32 m0, s68, 0xc000
	ds_read_b128 v[190:193], v151
	ds_read_b128 v[194:197], v151 offset:1024
	ds_read_b128 v[198:201], v151 offset:2048
	ds_read_b128 v[202:205], v151 offset:3072
	ds_read_b128 v[206:209], v151 offset:4096
	ds_read_b128 v[210:213], v151 offset:5120
	ds_read_b128 v[216:219], v151 offset:6144
	ds_read_b128 v[220:223], v151 offset:7168
	global_load_lds_dwordx4 v[162:163], off
	v_lshl_add_u64 v[162:163], v[146:147], 0, s[60:61]
	s_add_i32 m0, s68, 0xe000
	s_nop 0
	global_load_lds_dwordx4 v[162:163], off
	s_waitcnt vmcnt(8)
	s_waitcnt lgkmcnt(0)
	s_barrier
	s_waitcnt lgkmcnt(0)
	v_mfma_f32_16x16x32_bf16 v[124:127], v[152:155], v[190:193], v[124:127]
	v_mfma_f32_16x16x32_bf16 v[120:123], v[166:169], v[190:193], v[120:123]
	v_mfma_f32_16x16x32_bf16 v[108:111], v[152:155], v[198:201], v[108:111]
	v_mfma_f32_16x16x32_bf16 v[104:107], v[166:169], v[198:201], v[104:107]
	v_mfma_f32_16x16x32_bf16 v[92:95], v[152:155], v[206:209], v[92:95]
	v_mfma_f32_16x16x32_bf16 v[88:91], v[166:169], v[206:209], v[88:91]
	v_mfma_f32_16x16x32_bf16 v[76:79], v[152:155], v[216:219], v[76:79]
	v_mfma_f32_16x16x32_bf16 v[72:75], v[166:169], v[216:219], v[72:75]
	v_mfma_f32_16x16x32_bf16 v[124:127], v[156:159], v[194:197], v[124:127]
	v_mfma_f32_16x16x32_bf16 v[120:123], v[170:173], v[194:197], v[120:123]
	v_mfma_f32_16x16x32_bf16 v[108:111], v[156:159], v[202:205], v[108:111]
	v_mfma_f32_16x16x32_bf16 v[104:107], v[170:173], v[202:205], v[104:107]
	v_mfma_f32_16x16x32_bf16 v[92:95], v[156:159], v[210:213], v[92:95]
	v_mfma_f32_16x16x32_bf16 v[88:91], v[170:173], v[210:213], v[88:91]
	v_mfma_f32_16x16x32_bf16 v[76:79], v[156:159], v[220:223], v[76:79]
	v_mfma_f32_16x16x32_bf16 v[72:75], v[170:173], v[220:223], v[72:75]
	v_mfma_f32_16x16x32_bf16 v[116:119], v[174:177], v[190:193], v[116:119]
	v_mfma_f32_16x16x32_bf16 v[112:115], v[182:185], v[190:193], v[112:115]
	v_mfma_f32_16x16x32_bf16 v[100:103], v[174:177], v[198:201], v[100:103]
	v_mfma_f32_16x16x32_bf16 v[96:99], v[182:185], v[198:201], v[96:99]
	v_mfma_f32_16x16x32_bf16 v[84:87], v[174:177], v[206:209], v[84:87]
	v_mfma_f32_16x16x32_bf16 v[80:83], v[182:185], v[206:209], v[80:83]
	v_mfma_f32_16x16x32_bf16 v[68:71], v[174:177], v[216:219], v[68:71]
	v_mfma_f32_16x16x32_bf16 v[64:67], v[182:185], v[216:219], v[64:67]
	v_mfma_f32_16x16x32_bf16 v[116:119], v[178:181], v[194:197], v[116:119]
	v_mfma_f32_16x16x32_bf16 v[112:115], v[186:189], v[194:197], v[112:115]
	v_mfma_f32_16x16x32_bf16 v[100:103], v[178:181], v[202:205], v[100:103]
	v_mfma_f32_16x16x32_bf16 v[96:99], v[186:189], v[202:205], v[96:99]
	v_mfma_f32_16x16x32_bf16 v[84:87], v[178:181], v[210:213], v[84:87]
	v_mfma_f32_16x16x32_bf16 v[80:83], v[186:189], v[210:213], v[80:83]
	v_mfma_f32_16x16x32_bf16 v[68:71], v[178:181], v[220:223], v[68:71]
	v_mfma_f32_16x16x32_bf16 v[64:67], v[186:189], v[220:223], v[64:67]
	s_barrier
	s_add_i32 s84, s76, s67
	v_lshl_add_u64 v[162:163], s[62:63], 0, v[130:131]
	s_mov_b32 m0, s84
	ds_read_b128 v[190:193], v151 offset:16384
	ds_read_b128 v[194:197], v151 offset:17408
	ds_read_b128 v[198:201], v151 offset:18432
	ds_read_b128 v[202:205], v151 offset:19456
	ds_read_b128 v[206:209], v151 offset:20480
	ds_read_b128 v[210:213], v151 offset:21504
	ds_read_b128 v[216:219], v151 offset:22528
	ds_read_b128 v[220:223], v151 offset:23552
	global_load_lds_dwordx4 v[162:163], off
	s_add_i32 m0, s84, 0x2000
	s_add_u32 s84, s62, 0x80000
	v_lshl_add_u64 v[224:225], s[62:63], 0, v[134:135]
	s_addc_u32 s85, s63, 0
	s_add_i32 s86, s77, s67
	global_load_lds_dwordx4 v[224:225], off
	v_lshl_add_u64 v[226:227], s[84:85], 0, v[130:131]
	s_mov_b32 m0, s86
	v_lshl_add_u64 v[228:229], s[64:65], 0, v[132:133]
	global_load_lds_dwordx4 v[226:227], off
	v_lshl_add_u64 v[226:227], s[84:85], 0, v[134:135]
	s_add_i32 m0, s86, 0x2000
	s_nop 0
	global_load_lds_dwordx4 v[226:227], off
	v_lshl_add_u64 v[226:227], s[64:65], 0, v[128:129]
	s_mov_b32 m0, s68
	s_nop 0
	global_load_lds_dwordx4 v[226:227], off
	s_mov_b32 m0, s69
	s_nop 0
	global_load_lds_dwordx4 v[228:229], off
	s_waitcnt vmcnt(8)
	s_waitcnt lgkmcnt(0)
	s_barrier
; #define PG8_STAGE(bufoff, gbase, voff) do { _Pragma("unroll") for (int _i = 0; _i < 2; ++_i) \
;         __builtin_amdgcn_global_load_lds((const unsigned*)((const char*)(gbase) + (voff)[_i]), (LAS unsigned*)(lds + (bufoff) + ldsw + _i * 8192), 16, 0, 0); } while (0)
; #define PG8_LDA(dst, b, h) do { _Pragma("unroll") for (int m = 0; m < 4; ++m) _Pragma("unroll") for (int k = 0; k < 2; ++k) dst[m][k] = *(const LAS bf16x8*)(lds + PG8_SA(b, h) + aoff + m * 2048 + k * 1024); } while (0)
; #define PG8_LDB(dst, b, h) do { _Pragma("unroll") for (int n = 0; n < 2; ++n) _Pragma("unroll") for (int k = 0; k < 2; ++k) dst[n][k] = *(const LAS bf16x8*)(lds + PG8_SB(b, h) + boff + n * 2048 + k * 1024); } while (0)
; #define PG8_MMA(ai, bj, At, Bt) do { __builtin_amdgcn_s_setprio(1); _Pragma("unroll") for (int m = 0; m < 4; ++m) _Pragma("unroll") for (int n = 0; n < 2; ++n) _Pragma("unroll") for (int k = 0; k < 2; ++k) \
;         acc[ai][bj][m][n] = __builtin_amdgcn_mfma_f32_16x16x32_bf16(Bt[n][k], At[m][k], acc[ai][bj][m][n], 0, 0, 0); __builtin_amdgcn_s_setprio(0); } while (0)
; #define PG8_WAIT_V(n) asm volatile("s_waitcnt vmcnt(" #n ")" ::: "memory")
; #define PG8_WAIT_L(n) asm volatile("s_waitcnt lgkmcnt(" #n ")" ::: "memory")
; #define PG8_BAR __builtin_amdgcn_s_barrier()
; #define PG8_SCHED __builtin_amdgcn_sched_barrier(0)
; template <class Epi, bool ALIGN_EPI = false, bool SP2 = true>
; __device__ __forceinline__ void gemm_phase(LAS unsigned char* lds, const Gemm g, const StaticOrder& S, const Epi& E) {
;     ...
;             PG8_WAIT_V(8); PG8_WAIT_L(0); PG8_BAR; PG8_MMA(0, 0, At, B0); PG8_MMA(0, 1, At, B1); PG8_BAR; PG8_SCHED;
;             PG8_LDA(At, 0, 1); PG8_STAGE(PG8_SB(0, 0), b2, voffB); PG8_STAGE(PG8_SB(0, 1), b2 + hstep, voffB); PG8_STAGE(PG8_SA(0, 0), a2, voffA);
;             PG8_WAIT_V(8); PG8_WAIT_L(0); PG8_BAR; PG8_MMA(1, 0, At, B0); PG8_MMA(1, 1, At, B1); PG8_BAR; PG8_SCHED;
;             PG8_LDB(B0, 1, 0); PG8_LDB(B1, 1, 1); PG8_SCHED; PG8_LDA(At, 1, 0); PG8_STAGE(PG8_SA(0, 1), a2 + hstep, voffA);
;             PG8_WAIT_V(8); PG8_WAIT_L(0); PG8_BAR; PG8_MMA(0, 0, At, B0); PG8_MMA(0, 1, At, B1); PG8_BAR; PG8_SCHED;
	s_waitcnt lgkmcnt(0)
	v_mfma_f32_16x16x32_bf16 v[60:63], v[152:155], v[190:193], v[60:63]
	v_mfma_f32_16x16x32_bf16 v[56:59], v[166:169], v[190:193], v[56:59]
	v_mfma_f32_16x16x32_bf16 v[44:47], v[152:155], v[198:201], v[44:47]
	v_mfma_f32_16x16x32_bf16 v[40:43], v[166:169], v[198:201], v[40:43]
	v_mfma_f32_16x16x32_bf16 v[28:31], v[152:155], v[206:209], v[28:31]
	v_mfma_f32_16x16x32_bf16 v[24:27], v[166:169], v[206:209], v[24:27]
	v_mfma_f32_16x16x32_bf16 v[12:15], v[152:155], v[216:219], v[12:15]
	v_mfma_f32_16x16x32_bf16 v[8:11], v[166:169], v[216:219], v[8:11]
	v_mfma_f32_16x16x32_bf16 v[60:63], v[156:159], v[194:197], v[60:63]
	v_mfma_f32_16x16x32_bf16 v[56:59], v[170:173], v[194:197], v[56:59]
	v_mfma_f32_16x16x32_bf16 v[44:47], v[156:159], v[202:205], v[44:47]
	v_mfma_f32_16x16x32_bf16 v[40:43], v[170:173], v[202:205], v[40:43]
	v_mfma_f32_16x16x32_bf16 v[28:31], v[156:159], v[210:213], v[28:31]
	v_mfma_f32_16x16x32_bf16 v[24:27], v[170:173], v[210:213], v[24:27]
	v_mfma_f32_16x16x32_bf16 v[12:15], v[156:159], v[220:223], v[12:15]
	v_mfma_f32_16x16x32_bf16 v[8:11], v[170:173], v[220:223], v[8:11]
	v_mfma_f32_16x16x32_bf16 v[52:55], v[174:177], v[190:193], v[52:55]
	v_mfma_f32_16x16x32_bf16 v[48:51], v[182:185], v[190:193], v[48:51]
	v_mfma_f32_16x16x32_bf16 v[36:39], v[174:177], v[198:201], v[36:39]
	v_mfma_f32_16x16x32_bf16 v[32:35], v[182:185], v[198:201], v[32:35]
	v_mfma_f32_16x16x32_bf16 v[20:23], v[174:177], v[206:209], v[20:23]
	v_mfma_f32_16x16x32_bf16 v[16:19], v[182:185], v[206:209], v[16:19]
	v_mfma_f32_16x16x32_bf16 v[4:7], v[174:177], v[216:219], v[4:7]
	v_mfma_f32_16x16x32_bf16 v[0:3], v[182:185], v[216:219], v[0:3]
	v_mfma_f32_16x16x32_bf16 v[52:55], v[178:181], v[194:197], v[52:55]
	v_mfma_f32_16x16x32_bf16 v[48:51], v[186:189], v[194:197], v[48:51]
	v_mfma_f32_16x16x32_bf16 v[36:39], v[178:181], v[202:205], v[36:39]
	v_mfma_f32_16x16x32_bf16 v[32:35], v[186:189], v[202:205], v[32:35]
	v_mfma_f32_16x16x32_bf16 v[20:23], v[178:181], v[210:213], v[20:23]
	v_mfma_f32_16x16x32_bf16 v[16:19], v[186:189], v[210:213], v[16:19]
	v_mfma_f32_16x16x32_bf16 v[4:7], v[178:181], v[220:223], v[4:7]
	v_mfma_f32_16x16x32_bf16 v[0:3], v[186:189], v[220:223], v[0:3]
	s_barrier
	s_add_i32 s84, 0, 0x18000
	v_add_u32_e32 v161, s84, v150
	s_add_i32 s85, 0, 0x1c000
	ds_read_b128 v[152:155], v161
	ds_read_b128 v[156:159], v161 offset:1024
	ds_read_b128 v[166:169], v161 offset:2048
	ds_read_b128 v[170:173], v161 offset:3072
	v_add_u32_e32 v161, s85, v150
	ds_read_b128 v[174:177], v161
	ds_read_b128 v[178:181], v161 offset:1024
	ds_read_b128 v[182:185], v161 offset:2048
	ds_read_b128 v[186:189], v161 offset:3072
	s_add_u32 s64, s64, 0x80000
	s_addc_u32 s65, s65, 0
	s_mov_b32 m0, s70
	v_lshl_add_u64 v[230:231], s[64:65], 0, v[128:129]
	ds_read_b128 v[190:193], v151 offset:32768
	ds_read_b128 v[194:197], v151 offset:33792
	ds_read_b128 v[198:201], v151 offset:34816
	ds_read_b128 v[202:205], v151 offset:35840
	ds_read_b128 v[206:209], v151 offset:36864
	ds_read_b128 v[210:213], v151 offset:37888
	ds_read_b128 v[216:219], v151 offset:38912
	ds_read_b128 v[220:223], v151 offset:39936
	global_load_lds_dwordx4 v[230:231], off
	v_lshl_add_u64 v[230:231], s[64:65], 0, v[132:133]
	s_mov_b32 m0, s71
	s_nop 0
	global_load_lds_dwordx4 v[230:231], off
	s_waitcnt vmcnt(8)
	s_waitcnt lgkmcnt(0)
	s_barrier
	s_waitcnt lgkmcnt(0)
	v_mfma_f32_16x16x32_bf16 v[124:127], v[152:155], v[190:193], v[124:127]
	v_mfma_f32_16x16x32_bf16 v[120:123], v[166:169], v[190:193], v[120:123]
	v_mfma_f32_16x16x32_bf16 v[108:111], v[152:155], v[198:201], v[108:111]
	v_mfma_f32_16x16x32_bf16 v[104:107], v[166:169], v[198:201], v[104:107]
	v_mfma_f32_16x16x32_bf16 v[92:95], v[152:155], v[206:209], v[92:95]
	v_mfma_f32_16x16x32_bf16 v[88:91], v[166:169], v[206:209], v[88:91]
	v_mfma_f32_16x16x32_bf16 v[76:79], v[152:155], v[216:219], v[76:79]
	v_mfma_f32_16x16x32_bf16 v[72:75], v[166:169], v[216:219], v[72:75]
	v_mfma_f32_16x16x32_bf16 v[124:127], v[156:159], v[194:197], v[124:127]
	v_mfma_f32_16x16x32_bf16 v[120:123], v[170:173], v[194:197], v[120:123]
	v_mfma_f32_16x16x32_bf16 v[108:111], v[156:159], v[202:205], v[108:111]
	v_mfma_f32_16x16x32_bf16 v[104:107], v[170:173], v[202:205], v[104:107]
	v_mfma_f32_16x16x32_bf16 v[92:95], v[156:159], v[210:213], v[92:95]
	v_mfma_f32_16x16x32_bf16 v[88:91], v[170:173], v[210:213], v[88:91]
	v_mfma_f32_16x16x32_bf16 v[76:79], v[156:159], v[220:223], v[76:79]
	v_mfma_f32_16x16x32_bf16 v[72:75], v[170:173], v[220:223], v[72:75]
	v_mfma_f32_16x16x32_bf16 v[116:119], v[174:177], v[190:193], v[116:119]
	v_mfma_f32_16x16x32_bf16 v[112:115], v[182:185], v[190:193], v[112:115]
	v_mfma_f32_16x16x32_bf16 v[100:103], v[174:177], v[198:201], v[100:103]
	v_mfma_f32_16x16x32_bf16 v[96:99], v[182:185], v[198:201], v[96:99]
	v_mfma_f32_16x16x32_bf16 v[84:87], v[174:177], v[206:209], v[84:87]
	v_mfma_f32_16x16x32_bf16 v[80:83], v[182:185], v[206:209], v[80:83]
	v_mfma_f32_16x16x32_bf16 v[68:71], v[174:177], v[216:219], v[68:71]
	v_mfma_f32_16x16x32_bf16 v[64:67], v[182:185], v[216:219], v[64:67]
	v_mfma_f32_16x16x32_bf16 v[116:119], v[178:181], v[194:197], v[116:119]
	v_mfma_f32_16x16x32_bf16 v[112:115], v[186:189], v[194:197], v[112:115]
	v_mfma_f32_16x16x32_bf16 v[100:103], v[178:181], v[202:205], v[100:103]
	v_mfma_f32_16x16x32_bf16 v[96:99], v[186:189], v[202:205], v[96:99]
	v_mfma_f32_16x16x32_bf16 v[84:87], v[178:181], v[210:213], v[84:87]
	v_mfma_f32_16x16x32_bf16 v[80:83], v[186:189], v[210:213], v[80:83]
	v_mfma_f32_16x16x32_bf16 v[68:71], v[178:181], v[220:223], v[68:71]
	v_mfma_f32_16x16x32_bf16 v[64:67], v[186:189], v[220:223], v[64:67]
	s_barrier
; #define PG8_STAGE(bufoff, gbase, voff) do { _Pragma("unroll") for (int _i = 0; _i < 2; ++_i) \
;         __builtin_amdgcn_global_load_lds((const unsigned*)((const char*)(gbase) + (voff)[_i]), (LAS unsigned*)(lds + (bufoff) + ldsw + _i * 8192), 16, 0, 0); } while (0)
; #define PG8_LDA(dst, b, h) do { _Pragma("unroll") for (int m = 0; m < 4; ++m) _Pragma("unroll") for (int k = 0; k < 2; ++k) dst[m][k] = *(const LAS bf16x8*)(lds + PG8_SA(b, h) + aoff + m * 2048 + k * 1024); } while (0)
; #define PG8_LDB(dst, b, h) do { _Pragma("unroll") for (int n = 0; n < 2; ++n) _Pragma("unroll") for (int k = 0; k < 2; ++k) dst[n][k] = *(const LAS bf16x8*)(lds + PG8_SB(b, h) + boff + n * 2048 + k * 1024); } while (0)
; #define PG8_MMA(ai, bj, At, Bt) do { __builtin_amdgcn_s_setprio(1); _Pragma("unroll") for (int m = 0; m < 4; ++m) _Pragma("unroll") for (int n = 0; n < 2; ++n) _Pragma("unroll") for (int k = 0; k < 2; ++k) \
;         acc[ai][bj][m][n] = __builtin_amdgcn_mfma_f32_16x16x32_bf16(Bt[n][k], At[m][k], acc[ai][bj][m][n], 0, 0, 0); __builtin_amdgcn_s_setprio(0); } while (0)
; #define PG8_WAIT_V(n) asm volatile("s_waitcnt vmcnt(" #n ")" ::: "memory")
; #define PG8_WAIT_L(n) asm volatile("s_waitcnt lgkmcnt(" #n ")" ::: "memory")
; #define PG8_BAR __builtin_amdgcn_s_barrier()
; #define PG8_SCHED __builtin_amdgcn_sched_barrier(0)
; template <class Epi, bool ALIGN_EPI = false, bool SP2 = true>
; __device__ __forceinline__ void gemm_phase(LAS unsigned char* lds, const Gemm g, const StaticOrder& S, const Epi& E) {
;     ...
;             PG8_LDB(B0, 1, 0); PG8_LDB(B1, 1, 1); PG8_SCHED; PG8_LDA(At, 1, 0); PG8_STAGE(PG8_SA(0, 1), a2 + hstep, voffA);
;             PG8_WAIT_V(8); PG8_WAIT_L(0); PG8_BAR; PG8_MMA(0, 0, At, B0); PG8_MMA(0, 1, At, B1); PG8_BAR; PG8_SCHED;
;             PG8_LDA(At, 1, 1); PG8_STAGE(PG8_SB(1, 0), b3, voffB); PG8_STAGE(PG8_SB(1, 1), b3 + hstep, voffB); PG8_STAGE(PG8_SA(1, 0), a3, voffA);
;             PG8_WAIT_V(8); PG8_WAIT_L(0); PG8_BAR; PG8_MMA(1, 0, At, B0); PG8_MMA(1, 1, At, B1); PG8_BAR; PG8_SCHED;
;     ...
; #pragma unroll
;         for (int a = 0; a < 2; ++a)
; #pragma unroll
;             for (int b = 0; b < 2; ++b)
; #pragma unroll
;                 for (int m = 0; m < 4; ++m)
; #pragma unroll
;                     for (int n = 0; n < 2; ++n) acc[a][b][m][n] = (f32x4){0.f, 0.f, 0.f, 0.f};
;         cur = nxt; cA = nA; cB = nB; ++ui;
	s_add_i32 s64, s84, s67
	v_lshl_add_u64 v[162:163], v[162:163], 0, s[24:25]
	s_mov_b32 m0, s64
	ds_read_b128 v[190:193], v151 offset:49152
	ds_read_b128 v[194:197], v151 offset:50176
	ds_read_b128 v[198:201], v151 offset:51200
	ds_read_b128 v[202:205], v151 offset:52224
	ds_read_b128 v[206:209], v151 offset:53248
	ds_read_b128 v[210:213], v151 offset:54272
	ds_read_b128 v[216:219], v151 offset:55296
	ds_read_b128 v[220:223], v151 offset:56320
	global_load_lds_dwordx4 v[162:163], off
	s_add_i32 m0, s64, 0x2000
	s_add_u32 s62, s62, 0x80080
	v_lshl_add_u64 v[162:163], v[224:225], 0, s[24:25]
	s_addc_u32 s63, s63, 0
	s_add_i32 s64, s85, s67
	global_load_lds_dwordx4 v[162:163], off
	v_lshl_add_u64 v[162:163], s[62:63], 0, v[130:131]
	s_mov_b32 m0, s64
	s_nop 0
	global_load_lds_dwordx4 v[162:163], off
	v_lshl_add_u64 v[162:163], s[62:63], 0, v[134:135]
	s_add_i32 m0, s64, 0x2000
	s_nop 0
	global_load_lds_dwordx4 v[162:163], off
	v_lshl_add_u64 v[162:163], v[226:227], 0, s[24:25]
	s_mov_b32 m0, s73
	s_nop 0
	global_load_lds_dwordx4 v[162:163], off
	v_lshl_add_u64 v[162:163], v[228:229], 0, s[24:25]
	s_mov_b32 m0, s74
	s_nop 0
	global_load_lds_dwordx4 v[162:163], off
	s_waitcnt vmcnt(8)
	s_waitcnt lgkmcnt(0)
	s_barrier
	s_waitcnt lgkmcnt(0)
	v_mfma_f32_16x16x32_bf16 v[60:63], v[152:155], v[190:193], v[60:63]
	v_mfma_f32_16x16x32_bf16 v[56:59], v[166:169], v[190:193], v[56:59]
	v_mfma_f32_16x16x32_bf16 v[44:47], v[152:155], v[198:201], v[44:47]
	v_mfma_f32_16x16x32_bf16 v[40:43], v[166:169], v[198:201], v[40:43]
	v_mfma_f32_16x16x32_bf16 v[28:31], v[152:155], v[206:209], v[28:31]
	v_mfma_f32_16x16x32_bf16 v[24:27], v[166:169], v[206:209], v[24:27]
	v_mfma_f32_16x16x32_bf16 v[12:15], v[152:155], v[216:219], v[12:15]
	v_mfma_f32_16x16x32_bf16 v[8:11], v[166:169], v[216:219], v[8:11]
	v_mfma_f32_16x16x32_bf16 v[60:63], v[156:159], v[194:197], v[60:63]
	v_mfma_f32_16x16x32_bf16 v[56:59], v[170:173], v[194:197], v[56:59]
	v_mfma_f32_16x16x32_bf16 v[44:47], v[156:159], v[202:205], v[44:47]
	v_mfma_f32_16x16x32_bf16 v[40:43], v[170:173], v[202:205], v[40:43]
	v_mfma_f32_16x16x32_bf16 v[28:31], v[156:159], v[210:213], v[28:31]
	v_mfma_f32_16x16x32_bf16 v[24:27], v[170:173], v[210:213], v[24:27]
	v_mfma_f32_16x16x32_bf16 v[12:15], v[156:159], v[220:223], v[12:15]
	v_mfma_f32_16x16x32_bf16 v[8:11], v[170:173], v[220:223], v[8:11]
	v_mfma_f32_16x16x32_bf16 v[52:55], v[174:177], v[190:193], v[52:55]
	v_mfma_f32_16x16x32_bf16 v[48:51], v[182:185], v[190:193], v[48:51]
	v_mfma_f32_16x16x32_bf16 v[36:39], v[174:177], v[198:201], v[36:39]
	v_mfma_f32_16x16x32_bf16 v[32:35], v[182:185], v[198:201], v[32:35]
	v_mfma_f32_16x16x32_bf16 v[20:23], v[174:177], v[206:209], v[20:23]
	v_mfma_f32_16x16x32_bf16 v[16:19], v[182:185], v[206:209], v[16:19]
	v_mfma_f32_16x16x32_bf16 v[4:7], v[174:177], v[216:219], v[4:7]
	v_mfma_f32_16x16x32_bf16 v[0:3], v[182:185], v[216:219], v[0:3]
	v_mfma_f32_16x16x32_bf16 v[52:55], v[178:181], v[194:197], v[52:55]
	v_mfma_f32_16x16x32_bf16 v[48:51], v[186:189], v[194:197], v[48:51]
	v_mfma_f32_16x16x32_bf16 v[36:39], v[178:181], v[202:205], v[36:39]
	v_mfma_f32_16x16x32_bf16 v[32:35], v[186:189], v[202:205], v[32:35]
	v_mfma_f32_16x16x32_bf16 v[20:23], v[178:181], v[210:213], v[20:23]
	v_mfma_f32_16x16x32_bf16 v[16:19], v[186:189], v[210:213], v[16:19]
	v_mfma_f32_16x16x32_bf16 v[4:7], v[178:181], v[220:223], v[4:7]
	v_mfma_f32_16x16x32_bf16 v[0:3], v[186:189], v[220:223], v[0:3]
	s_barrier
	s_add_i32 s83, s83, 2
	s_add_u32 s60, s60, 0x100
	s_addc_u32 s61, s61, 0
	s_cmp_gt_u32 s83, 29
	s_cbranch_scc0 .LBB0_325
	s_add_u32 s60, s79, 0xffffff00
	s_addc_u32 s61, s80, -1
	s_andn2_b64 vcc, exec, s[6:7]
	s_cbranch_vccnz .LBB0_328
	v_mov_b32_e32 v0, 0
	s_mov_b32 s22, s26
	s_mov_b32 s18, s28
	s_mov_b64 s[0:1], s[58:59]
	s_mov_b32 s75, s78
	v_mov_b32_e32 v1, v0
	v_mov_b32_e32 v2, v0
	v_mov_b32_e32 v3, v0
	v_mov_b32_e32 v4, v0
	v_mov_b32_e32 v5, v0
	v_mov_b32_e32 v6, v0
	v_mov_b32_e32 v7, v0
	v_mov_b32_e32 v16, v0
	v_mov_b32_e32 v17, v0
	v_mov_b32_e32 v18, v0
	v_mov_b32_e32 v19, v0
	v_mov_b32_e32 v20, v0
	v_mov_b32_e32 v21, v0
	v_mov_b32_e32 v22, v0
	v_mov_b32_e32 v23, v0
	v_mov_b32_e32 v32, v0
	v_mov_b32_e32 v33, v0
	v_mov_b32_e32 v34, v0
	v_mov_b32_e32 v35, v0
	v_mov_b32_e32 v36, v0
	v_mov_b32_e32 v37, v0
	v_mov_b32_e32 v38, v0
	v_mov_b32_e32 v39, v0
	v_mov_b32_e32 v48, v0
	v_mov_b32_e32 v49, v0
	v_mov_b32_e32 v50, v0
	v_mov_b32_e32 v51, v0
	v_mov_b32_e32 v52, v0
	v_mov_b32_e32 v53, v0
	v_mov_b32_e32 v54, v0
	v_mov_b32_e32 v55, v0
	v_mov_b32_e32 v8, v0
	v_mov_b32_e32 v9, v0
	v_mov_b32_e32 v10, v0
	v_mov_b32_e32 v11, v0
	v_mov_b32_e32 v12, v0
	v_mov_b32_e32 v13, v0
	v_mov_b32_e32 v14, v0
	v_mov_b32_e32 v15, v0
	v_mov_b32_e32 v24, v0
	v_mov_b32_e32 v25, v0
	v_mov_b32_e32 v26, v0
	v_mov_b32_e32 v27, v0
	v_mov_b32_e32 v28, v0
	v_mov_b32_e32 v29, v0
	v_mov_b32_e32 v30, v0
	v_mov_b32_e32 v31, v0
	v_mov_b32_e32 v40, v0
	v_mov_b32_e32 v41, v0
	v_mov_b32_e32 v42, v0
	v_mov_b32_e32 v43, v0
	v_mov_b32_e32 v44, v0
	v_mov_b32_e32 v45, v0
	v_mov_b32_e32 v46, v0
	v_mov_b32_e32 v47, v0
	v_mov_b32_e32 v56, v0
	v_mov_b32_e32 v57, v0
	v_mov_b32_e32 v58, v0
	v_mov_b32_e32 v59, v0
	v_mov_b32_e32 v60, v0
	v_mov_b32_e32 v61, v0
	v_mov_b32_e32 v62, v0
	v_mov_b32_e32 v63, v0
	v_mov_b32_e32 v64, v0
	v_mov_b32_e32 v65, v0
	v_mov_b32_e32 v66, v0
	v_mov_b32_e32 v67, v0
	v_mov_b32_e32 v68, v0
	v_mov_b32_e32 v69, v0
	v_mov_b32_e32 v70, v0
	v_mov_b32_e32 v71, v0
	v_mov_b32_e32 v80, v0
	v_mov_b32_e32 v81, v0
	v_mov_b32_e32 v82, v0
	v_mov_b32_e32 v83, v0
	v_mov_b32_e32 v84, v0
	v_mov_b32_e32 v85, v0
	v_mov_b32_e32 v86, v0
	v_mov_b32_e32 v87, v0
	v_mov_b32_e32 v96, v0
	v_mov_b32_e32 v97, v0
	v_mov_b32_e32 v98, v0
	v_mov_b32_e32 v99, v0
	v_mov_b32_e32 v100, v0
	v_mov_b32_e32 v101, v0
	v_mov_b32_e32 v102, v0
	v_mov_b32_e32 v103, v0
	v_mov_b32_e32 v112, v0
	v_mov_b32_e32 v113, v0
	v_mov_b32_e32 v114, v0
	v_mov_b32_e32 v115, v0
	v_mov_b32_e32 v116, v0
	v_mov_b32_e32 v117, v0
	v_mov_b32_e32 v118, v0
	v_mov_b32_e32 v119, v0
	v_mov_b32_e32 v72, v0
	v_mov_b32_e32 v73, v0
	v_mov_b32_e32 v74, v0
	v_mov_b32_e32 v75, v0
	v_mov_b32_e32 v76, v0
	v_mov_b32_e32 v77, v0
	v_mov_b32_e32 v78, v0
	v_mov_b32_e32 v79, v0
	v_mov_b32_e32 v88, v0
	v_mov_b32_e32 v89, v0
	v_mov_b32_e32 v90, v0
	v_mov_b32_e32 v91, v0
	v_mov_b32_e32 v92, v0
	v_mov_b32_e32 v93, v0
	v_mov_b32_e32 v94, v0
	v_mov_b32_e32 v95, v0
	v_mov_b32_e32 v104, v0
	v_mov_b32_e32 v105, v0
	v_mov_b32_e32 v106, v0
	v_mov_b32_e32 v107, v0
	v_mov_b32_e32 v108, v0
	v_mov_b32_e32 v109, v0
	v_mov_b32_e32 v110, v0
	v_mov_b32_e32 v111, v0
	v_mov_b32_e32 v120, v0
	v_mov_b32_e32 v121, v0
	v_mov_b32_e32 v122, v0
	v_mov_b32_e32 v123, v0
	v_mov_b32_e32 v124, v0
	v_mov_b32_e32 v125, v0
	v_mov_b32_e32 v126, v0
	v_mov_b32_e32 v127, v0
	s_andn2_b64 vcc, exec, s[4:5]
	s_cbranch_vccnz .LBB0_329
	s_branch .LBB0_330

; __device__ __forceinline__ unsigned xb_add(unsigned* p, unsigned v) { return __hip_atomic_fetch_add(p, v, __ATOMIC_RELAXED, __HIP_MEMORY_SCOPE_AGENT); }
; __device__ __forceinline__ void xcd_barrier(const XcdBarrier& b) {
;     asm volatile("s_waitcnt vmcnt(0)" ::: "memory");
;     __syncthreads();
;     if (threadIdx.x == 0) {
;         unsigned* bar = b.bar;
;         __builtin_amdgcn_s_waitcnt(0);
;         unsigned nloc = b.st[0], nx = b.st[1];
;         if (nloc == 0u) { xcd_barrier_complete(bar, b.x, nloc, nx); b.st[0] = nloc; b.st[1] = nx; }
;         const unsigned old = xb_add(&bar[XB_XSUB(b.x)], 1u);
;         const unsigned gen = old / nloc;
;         if (old + 1u == (gen + 1u) * nloc) {
;             __builtin_amdgcn_fence(__ATOMIC_RELEASE, "agent");
;             asm volatile("s_waitcnt vmcnt(0)" ::: "memory");
;             const unsigned og = xb_add(&bar[XB_TOP], 1u);
.LBB0_366:
	s_cmp_gt_u32 s43, 4
	s_setprio 0
	s_cselect_b64 s[0:1], -1, 0
	s_and_b64 s[0:1], s[16:17], s[0:1]
	s_andn2_b64 vcc, exec, s[0:1]
	s_cbranch_vccnz .LBB0_416
	s_waitcnt vmcnt(0)
	s_waitcnt vmcnt(0) lgkmcnt(0)
	s_barrier
	s_and_saveexec_b64 s[0:1], s[12:13]
	s_cbranch_execz .LBB0_415
	s_and_b32 s98, s2, 7
	s_lshl_b32 s98, s98, 2
	s_bfe_u32 s99, s2, 0x20003
	s_or_b32 s98, s98, s99
	s_lshl_b32 s98, s98, 6
	s_add_i32 s98, s98, 0xa400
	v_mov_b32_e32 v250, s98
	v_mov_b32_e32 v252, 1
	v_mov_b32_e32 v253, 0x20008
	ds_write_b32 v253, v255
	v_mov_b32_e32 v253, 0x2000c
	ds_read_b32 v254, v253
	s_waitcnt lgkmcnt(0)
	v_readfirstlane_b32 s99, v254
	s_cmp_eq_u32 s99, 1
	s_cbranch_scc1 .Lpb3_fast
	buffer_wbl2 sc1
	s_waitcnt vmcnt(0)

; __global__ void __launch_bounds__(NTHREADS, 2) mk_fwd(Params P) {
;     ...
;     if (IN(5)) {
;         transpose_convert(lds, P.w_in_b, WINB, 2048, 8192, G, bid);
.LBB0_416:
	s_cmp_lt_i32 s42, 6
	s_cselect_b64 s[0:1], -1, 0
	s_cmp_gt_i32 s43, 5
	s_setprio 0
	s_cselect_b64 s[4:5], -1, 0
	s_and_b64 s[0:1], s[0:1], s[4:5]
	s_andn2_b64 vcc, exec, s[0:1]
	s_cbranch_vccnz .LBB0_448
	v_and_b32_e32 v20, 15, v164
	v_mov_b32_e32 v46, 0x20008
	ds_read_b32 v48, v46
	s_waitcnt lgkmcnt(0)
	v_readfirstlane_b32 s99, v48
	s_and_b32 s99, s99, 0xff
	s_lshr_b32 s3, s99, 5
	s_and_b32 s4, s99, 31
	s_mov_b32 s100, 11
	s_mov_b32 s5, 0
	s_cmp_lt_u32 s3, 1
	s_cbranch_scc1 .Lrk5_done
	s_mov_b32 s100, 10
	s_movk_i32 s5, 352
	s_cmp_lt_u32 s3, 2
	s_cbranch_scc1 .Lrk5_done
	s_mov_b32 s100, 9
	s_movk_i32 s5, 672
	s_cmp_lt_u32 s3, 3
	s_cbranch_scc1 .Lrk5_done
	s_mov_b32 s100, 9
	s_movk_i32 s5, 960
	s_cmp_lt_u32 s3, 4
	s_cbranch_scc1 .Lrk5_done
	s_mov_b32 s100, 8
	s_movk_i32 s5, 1248
	s_cmp_lt_u32 s3, 5
	s_cbranch_scc1 .Lrk5_done
	s_mov_b32 s100, 7
	s_movk_i32 s5, 1504
	s_cmp_lt_u32 s3, 6
	s_cbranch_scc1 .Lrk5_done
	s_mov_b32 s100, 6
	s_movk_i32 s5, 1728
	s_cmp_lt_u32 s3, 7
	s_cbranch_scc1 .Lrk5_done
	s_mov_b32 s100, 4
	s_movk_i32 s5, 1920

; #define PG8_STAGE(bufoff, gbase, voff) do { _Pragma("unroll") for (int _i = 0; _i < 2; ++_i) \
;         __builtin_amdgcn_global_load_lds((const unsigned*)((const char*)(gbase) + (voff)[_i]), (LAS unsigned*)(lds + (bufoff) + ldsw + _i * 8192), 16, 0, 0); } while (0)
; #define PG8_WAIT_V(n) asm volatile("s_waitcnt vmcnt(" #n ")" ::: "memory")
; #define PG8_BAR __builtin_amdgcn_s_barrier()
; template <class Epi, bool ALIGN_EPI = false, bool SP2 = true>
; __device__ __forceinline__ void gemm_phase(LAS unsigned char* lds, const Gemm g, const StaticOrder& S, const Epi& E) {
;     ...
;     const char* cA = (const char*)g.A + (size_t)cur.pm * tstep; const char* cB = (const char*)g.Bt + (size_t)(cur.pn + (cur.pm >= g.bsplit ? g.badd : 0)) * tstep;
;     if constexpr (SP2) {
;         PG8_STAGE(PG8_SB(0, 0), cB, voffB); PG8_STAGE(PG8_SB(0, 1), cB + hstep, voffB); PG8_STAGE(PG8_SA(0, 0), cA, voffA); PG8_STAGE(PG8_SA(0, 1), cA + hstep, voffA);
;         if (wr == 1) PG8_BAR;
;         PG8_WAIT_V(2); PG8_BAR;
;         PG8_STAGE(PG8_SB(1, 0), cB + kstep, voffB); PG8_STAGE(PG8_SA(1, 0), cA + kstep, voffA); PG8_STAGE(PG8_SB(1, 1), cB + hstep + kstep, voffB);
;         PG8_WAIT_V(6); PG8_BAR;
.LBB0_429:
	v_lshrrev_b32_e32 v2, 1, v164
	v_and_b32_e32 v11, 24, v2
	v_lshrrev_b32_e32 v2, 5, v164
	s_ashr_i32 s4, s7, 3
	v_and_b32_e32 v2, 4, v2
	v_bfe_u32 v3, v164, 2, 2
	v_lshlrev_b32_e32 v0, 4, v164
	v_and_b32_e32 v1, 32, v164
	v_bfe_u32 v10, v164, 2, 4
	v_or3_b32 v2, v2, v3, v11
	v_lshrrev_b32_e32 v3, 3, v164
	s_movk_i32 s7, 0x70
	s_add_i32 s4, s6, s4
	v_bitop3_b32 v8, v0, v1, 48 bitop3:0x6c
	v_and_b32_e32 v9, 64, v164
	v_and_or_b32 v4, v3, s7, v10
	s_movk_i32 s7, 0x60
	v_add_u32_e32 v12, 0x2000, v0
	s_ashr_i32 s6, s4, 31
	v_or_b32_e32 v1, v8, v9
	v_and_or_b32 v3, v3, s7, v2
	v_lshrrev_b32_e32 v0, 7, v12
	s_movk_i32 s7, 0xf0
	s_lshr_b32 s6, s6, 27
	v_lshl_or_b32 v168, v3, 12, v1
	v_and_or_b32 v3, v0, s7, v10
	s_movk_i32 s7, 0xe0
	s_add_i32 s6, s4, s6
	v_and_or_b32 v0, v0, s7, v2
	s_ashr_i32 s7, s6, 5
	s_andn2_b32 s6, s6, 31
	s_sub_i32 s6, s4, s6
	s_bfe_i32 s4, s6, 0x80000
	s_bfe_u32 s4, s4, 0x2000d
	s_add_i32 s17, s6, s4
	s_bfe_i32 s4, s17, 0x80000
	s_and_b32 s17, s17, 0xfc
	s_sub_i32 s6, s6, s17
	s_lshl_b32 s7, s7, 2
	s_sext_i32_i16 s4, s4
	s_sext_i32_i8 s6, s6
	s_lshr_b32 s5, s18, 8
	s_lshr_b32 s4, s4, 2
	s_add_i32 s30, s7, s6
	s_lshr_b32 s16, s18, 6
	s_ashr_i32 s31, s30, 31
	s_bfe_i64 s[22:23], s[4:5], 0x100000
	s_lshl_b32 s60, s16, 10
	s_lshl_b64 s[6:7], s[30:31], 20
	s_lshl_b64 s[22:23], s[22:23], 20
	s_add_u32 s56, s52, s22
	s_addc_u32 s57, s53, s23
	s_add_i32 s31, s60, 0
	s_add_i32 m0, s31, 0x10000
	v_lshl_or_b32 v172, v0, 12, v1
	global_load_lds_dwordx4 v168, s[56:57]
	s_add_i32 m0, s31, 0x12000
	s_add_u32 s22, s56, 0x80000
	global_load_lds_dwordx4 v172, s[56:57]
	s_addc_u32 s23, s57, 0
	s_add_i32 m0, s31, 0x14000
	v_lshl_or_b32 v166, v4, 12, v1
	global_load_lds_dwordx4 v168, s[22:23]
	s_add_i32 m0, s31, 0x16000
	s_add_u32 s36, s10, s6
	s_addc_u32 s37, s11, s7
	s_add_i32 s61, s31, 0x2000
	global_load_lds_dwordx4 v172, s[22:23]
	s_mov_b32 m0, s31
	s_add_u32 s6, s36, 0x80000
	v_lshl_or_b32 v170, v3, 12, v1
	global_load_lds_dwordx4 v166, s[36:37]
	s_mov_b32 m0, s61
	s_addc_u32 s7, s37, 0
	s_add_i32 s62, s31, 0x4000
	global_load_lds_dwordx4 v170, s[36:37]
	s_mov_b32 m0, s62
	s_add_i32 s63, s31, 0x6000
	global_load_lds_dwordx4 v166, s[6:7]
	s_mov_b32 m0, s63
	v_mov_b32_e32 v169, 0
	global_load_lds_dwordx4 v170, s[6:7]
	v_mov_b32_e32 v173, v169
	v_mov_b32_e32 v167, v169
	v_mov_b32_e32 v171, v169
	s_cmp_eq_u32 s5, 1
	s_mov_b32 s64, 0
	s_mov_b32 s65, 0x10000
	v_lshl_add_u64 v[6:7], s[56:57], 0, v[168:169]
	v_lshl_add_u64 v[4:5], s[56:57], 0, v[172:173]
	v_lshl_add_u64 v[0:1], s[36:37], 0, v[166:167]
	s_cselect_b64 s[6:7], -1, 0
	s_cmp_lg_u32 s5, 1
	v_lshl_add_u64 v[2:3], s[36:37], 0, v[170:171]
	s_cbranch_scc1 .LBB0_431
	s_barrier
	s_setprio 1

; #define PG8_STAGE(bufoff, gbase, voff) do { _Pragma("unroll") for (int _i = 0; _i < 2; ++_i) \
;         __builtin_amdgcn_global_load_lds((const unsigned*)((const char*)(gbase) + (voff)[_i]), (LAS unsigned*)(lds + (bufoff) + ldsw + _i * 8192), 16, 0, 0); } while (0)
; #define PG8_LDA(dst, b, h) do { _Pragma("unroll") for (int m = 0; m < 4; ++m) _Pragma("unroll") for (int k = 0; k < 2; ++k) dst[m][k] = *(const LAS bf16x8*)(lds + PG8_SA(b, h) + aoff + m * 2048 + k * 1024); } while (0)
; #define PG8_LDB(dst, b, h) do { _Pragma("unroll") for (int n = 0; n < 2; ++n) _Pragma("unroll") for (int k = 0; k < 2; ++k) dst[n][k] = *(const LAS bf16x8*)(lds + PG8_SB(b, h) + boff + n * 2048 + k * 1024); } while (0)
; #define PG8_WAIT_V(n) asm volatile("s_waitcnt vmcnt(" #n ")" ::: "memory")
; #define PG8_WAIT_L(n) asm volatile("s_waitcnt lgkmcnt(" #n ")" ::: "memory")
; #define PG8_BAR __builtin_amdgcn_s_barrier()
; #define PG8_SCHED __builtin_amdgcn_sched_barrier(0)
; template <class Epi, bool ALIGN_EPI = false, bool SP2 = true>
; __device__ __forceinline__ void gemm_phase(LAS unsigned char* lds, const Gemm g, const StaticOrder& S, const Epi& E) {
;     ...
;         const bool has_next = S.next(ui + 1, nxt);
;         const char* nA = has_next ? (const char*)g.A + (size_t)nxt.pm * tstep : cA; const char* nB = has_next ? (const char*)g.Bt + (size_t)(nxt.pn + (nxt.pm >= g.bsplit ? g.badd : 0)) * tstep : cB;
;         for (int t = 0; t < nt; t += 2) {
;             const bool last = (t == nt - 2);
;             const char* a1 = cA + (size_t)(t + 1) * kstep;
;             const char* a2 = last ? nA : cA + (size_t)(t + 2) * kstep; const char* b2 = last ? nB : cB + (size_t)(t + 2) * kstep;
;             const char* a3 = a2 + kstep; const char* b3 = b2 + kstep;
;             if constexpr (SP2) {
;             PG8_LDB(B0, 0, 0); PG8_LDB(B1, 0, 1); PG8_SCHED; PG8_LDA(At, 0, 0); PG8_STAGE(PG8_SA(1, 1), a1 + hstep, voffA);
;             PG8_WAIT_V(8); PG8_WAIT_L(0); PG8_BAR; PG8_MMA(0, 0, At, B0); PG8_MMA(0, 1, At, B1); PG8_BAR; PG8_SCHED;
;             PG8_LDA(At, 0, 1); PG8_STAGE(PG8_SB(0, 0), b2, voffB); PG8_STAGE(PG8_SB(0, 1), b2 + hstep, voffB); PG8_STAGE(PG8_SA(0, 0), a2, voffA);
;             PG8_WAIT_V(8); PG8_WAIT_L(0); PG8_BAR; PG8_MMA(1, 0, At, B0); PG8_MMA(1, 1, At, B1); PG8_BAR; PG8_SCHED;
.LBB0_441:
	ds_read_b128 v[128:131], v188
	ds_read_b128 v[132:135], v188 offset:1024
	ds_read_b128 v[136:139], v188 offset:2048
	ds_read_b128 v[140:143], v188 offset:3072
	ds_read_b128 v[144:147], v189
	ds_read_b128 v[148:151], v189 offset:1024
	ds_read_b128 v[152:155], v189 offset:2048
	ds_read_b128 v[156:159], v189 offset:3072
	s_add_u32 s56, s36, 0xfff80080
	s_addc_u32 s57, s37, -1
	s_cmp_eq_u32 s79, 28
	s_cselect_b32 s59, s25, s57
	s_cselect_b32 s58, s75, s56
	s_cselect_b32 s57, s23, s78
	s_cselect_b32 s56, s76, s77
	v_lshl_add_u64 v[212:213], s[36:37], 0, v[174:175]
	s_add_i32 m0, s31, 0xc000
	ds_read_b128 v[160:163], v190
	ds_read_b128 v[182:185], v190 offset:1024
	ds_read_b128 v[192:195], v190 offset:2048
	ds_read_b128 v[196:199], v190 offset:3072
	ds_read_b128 v[200:203], v190 offset:4096
	ds_read_b128 v[204:207], v190 offset:5120
	ds_read_b128 v[208:211], v190 offset:6144
	ds_read_b128 v[216:219], v190 offset:7168
	global_load_lds_dwordx4 v[212:213], off
	v_lshl_add_u64 v[212:213], s[36:37], 0, v[176:177]
	s_add_i32 m0, s31, 0xe000
	s_nop 0
	global_load_lds_dwordx4 v[212:213], off
	s_waitcnt vmcnt(8)
	s_waitcnt lgkmcnt(0)
	s_barrier
	s_waitcnt lgkmcnt(0)
	v_mfma_f32_16x16x32_bf16 v[124:127], v[128:131], v[160:163], v[124:127]
	v_mfma_f32_16x16x32_bf16 v[120:123], v[136:139], v[160:163], v[120:123]
	v_mfma_f32_16x16x32_bf16 v[108:111], v[128:131], v[192:195], v[108:111]
	v_mfma_f32_16x16x32_bf16 v[104:107], v[136:139], v[192:195], v[104:107]
	v_mfma_f32_16x16x32_bf16 v[92:95], v[128:131], v[200:203], v[92:95]
	v_mfma_f32_16x16x32_bf16 v[88:91], v[136:139], v[200:203], v[88:91]
	v_mfma_f32_16x16x32_bf16 v[76:79], v[128:131], v[208:211], v[76:79]
	v_mfma_f32_16x16x32_bf16 v[72:75], v[136:139], v[208:211], v[72:75]
	v_mfma_f32_16x16x32_bf16 v[124:127], v[132:135], v[182:185], v[124:127]
	v_mfma_f32_16x16x32_bf16 v[120:123], v[140:143], v[182:185], v[120:123]
	v_mfma_f32_16x16x32_bf16 v[108:111], v[132:135], v[196:199], v[108:111]
	v_mfma_f32_16x16x32_bf16 v[104:107], v[140:143], v[196:199], v[104:107]
	v_mfma_f32_16x16x32_bf16 v[92:95], v[132:135], v[204:207], v[92:95]
	v_mfma_f32_16x16x32_bf16 v[88:91], v[140:143], v[204:207], v[88:91]
	v_mfma_f32_16x16x32_bf16 v[76:79], v[132:135], v[216:219], v[76:79]
	v_mfma_f32_16x16x32_bf16 v[72:75], v[140:143], v[216:219], v[72:75]
	v_mfma_f32_16x16x32_bf16 v[116:119], v[144:147], v[160:163], v[116:119]
	v_mfma_f32_16x16x32_bf16 v[112:115], v[152:155], v[160:163], v[112:115]
	v_mfma_f32_16x16x32_bf16 v[100:103], v[144:147], v[192:195], v[100:103]
	v_mfma_f32_16x16x32_bf16 v[96:99], v[152:155], v[192:195], v[96:99]
	v_mfma_f32_16x16x32_bf16 v[84:87], v[144:147], v[200:203], v[84:87]
	v_mfma_f32_16x16x32_bf16 v[80:83], v[152:155], v[200:203], v[80:83]
	v_mfma_f32_16x16x32_bf16 v[68:71], v[144:147], v[208:211], v[68:71]
	v_mfma_f32_16x16x32_bf16 v[64:67], v[152:155], v[208:211], v[64:67]
	v_mfma_f32_16x16x32_bf16 v[116:119], v[148:151], v[182:185], v[116:119]
	v_mfma_f32_16x16x32_bf16 v[112:115], v[156:159], v[182:185], v[112:115]
	v_mfma_f32_16x16x32_bf16 v[100:103], v[148:151], v[196:199], v[100:103]
	v_mfma_f32_16x16x32_bf16 v[96:99], v[156:159], v[196:199], v[96:99]
	v_mfma_f32_16x16x32_bf16 v[84:87], v[148:151], v[204:207], v[84:87]
	v_mfma_f32_16x16x32_bf16 v[80:83], v[156:159], v[204:207], v[80:83]
	v_mfma_f32_16x16x32_bf16 v[68:71], v[148:151], v[216:219], v[68:71]
	v_mfma_f32_16x16x32_bf16 v[64:67], v[156:159], v[216:219], v[64:67]
	s_barrier
	s_add_i32 s80, s70, s60
	v_lshl_add_u64 v[212:213], s[56:57], 0, v[168:169]
	s_mov_b32 m0, s80
	ds_read_b128 v[160:163], v190 offset:16384
	ds_read_b128 v[182:185], v190 offset:17408
	ds_read_b128 v[192:195], v190 offset:18432
	ds_read_b128 v[196:199], v190 offset:19456
	ds_read_b128 v[200:203], v190 offset:20480
	ds_read_b128 v[204:207], v190 offset:21504
	ds_read_b128 v[208:211], v190 offset:22528
	ds_read_b128 v[216:219], v190 offset:23552
	global_load_lds_dwordx4 v[212:213], off
	s_add_i32 m0, s80, 0x2000
	s_add_u32 s80, s56, 0x80000
	v_lshl_add_u64 v[220:221], s[56:57], 0, v[172:173]
	s_addc_u32 s81, s57, 0
	s_add_i32 s82, s71, s60
	global_load_lds_dwordx4 v[220:221], off
	v_lshl_add_u64 v[222:223], s[80:81], 0, v[168:169]
	s_mov_b32 m0, s82
	v_lshl_add_u64 v[224:225], s[58:59], 0, v[170:171]
	global_load_lds_dwordx4 v[222:223], off
	v_lshl_add_u64 v[222:223], s[80:81], 0, v[172:173]
	s_add_i32 m0, s82, 0x2000
	s_nop 0
	global_load_lds_dwordx4 v[222:223], off
	v_lshl_add_u64 v[222:223], s[58:59], 0, v[166:167]
	s_mov_b32 m0, s31
	s_nop 0
	global_load_lds_dwordx4 v[222:223], off
	s_mov_b32 m0, s61
	s_nop 0
	global_load_lds_dwordx4 v[224:225], off
	s_waitcnt vmcnt(8)
	s_waitcnt lgkmcnt(0)
	s_barrier
; #define PG8_STAGE(bufoff, gbase, voff) do { _Pragma("unroll") for (int _i = 0; _i < 2; ++_i) \
;         __builtin_amdgcn_global_load_lds((const unsigned*)((const char*)(gbase) + (voff)[_i]), (LAS unsigned*)(lds + (bufoff) + ldsw + _i * 8192), 16, 0, 0); } while (0)
; #define PG8_LDA(dst, b, h) do { _Pragma("unroll") for (int m = 0; m < 4; ++m) _Pragma("unroll") for (int k = 0; k < 2; ++k) dst[m][k] = *(const LAS bf16x8*)(lds + PG8_SA(b, h) + aoff + m * 2048 + k * 1024); } while (0)
; #define PG8_LDB(dst, b, h) do { _Pragma("unroll") for (int n = 0; n < 2; ++n) _Pragma("unroll") for (int k = 0; k < 2; ++k) dst[n][k] = *(const LAS bf16x8*)(lds + PG8_SB(b, h) + boff + n * 2048 + k * 1024); } while (0)
; #define PG8_MMA(ai, bj, At, Bt) do { __builtin_amdgcn_s_setprio(1); _Pragma("unroll") for (int m = 0; m < 4; ++m) _Pragma("unroll") for (int n = 0; n < 2; ++n) _Pragma("unroll") for (int k = 0; k < 2; ++k) \
;         acc[ai][bj][m][n] = __builtin_amdgcn_mfma_f32_16x16x32_bf16(Bt[n][k], At[m][k], acc[ai][bj][m][n], 0, 0, 0); __builtin_amdgcn_s_setprio(0); } while (0)
; #define PG8_WAIT_V(n) asm volatile("s_waitcnt vmcnt(" #n ")" ::: "memory")
; #define PG8_WAIT_L(n) asm volatile("s_waitcnt lgkmcnt(" #n ")" ::: "memory")
; #define PG8_BAR __builtin_amdgcn_s_barrier()
; #define PG8_SCHED __builtin_amdgcn_sched_barrier(0)
; template <class Epi, bool ALIGN_EPI = false, bool SP2 = true>
; __device__ __forceinline__ void gemm_phase(LAS unsigned char* lds, const Gemm g, const StaticOrder& S, const Epi& E) {
;     ...
;             PG8_WAIT_V(8); PG8_WAIT_L(0); PG8_BAR; PG8_MMA(0, 0, At, B0); PG8_MMA(0, 1, At, B1); PG8_BAR; PG8_SCHED;
;             PG8_LDA(At, 0, 1); PG8_STAGE(PG8_SB(0, 0), b2, voffB); PG8_STAGE(PG8_SB(0, 1), b2 + hstep, voffB); PG8_STAGE(PG8_SA(0, 0), a2, voffA);
;             PG8_WAIT_V(8); PG8_WAIT_L(0); PG8_BAR; PG8_MMA(1, 0, At, B0); PG8_MMA(1, 1, At, B1); PG8_BAR; PG8_SCHED;
;             PG8_LDB(B0, 1, 0); PG8_LDB(B1, 1, 1); PG8_SCHED; PG8_LDA(At, 1, 0); PG8_STAGE(PG8_SA(0, 1), a2 + hstep, voffA);
;             PG8_WAIT_V(8); PG8_WAIT_L(0); PG8_BAR; PG8_MMA(0, 0, At, B0); PG8_MMA(0, 1, At, B1); PG8_BAR; PG8_SCHED;
	s_waitcnt lgkmcnt(0)
	v_mfma_f32_16x16x32_bf16 v[60:63], v[128:131], v[160:163], v[60:63]
	v_mfma_f32_16x16x32_bf16 v[56:59], v[136:139], v[160:163], v[56:59]
	v_mfma_f32_16x16x32_bf16 v[44:47], v[128:131], v[192:195], v[44:47]
	v_mfma_f32_16x16x32_bf16 v[40:43], v[136:139], v[192:195], v[40:43]
	v_mfma_f32_16x16x32_bf16 v[28:31], v[128:131], v[200:203], v[28:31]
	v_mfma_f32_16x16x32_bf16 v[24:27], v[136:139], v[200:203], v[24:27]
	v_mfma_f32_16x16x32_bf16 v[12:15], v[128:131], v[208:211], v[12:15]
	v_mfma_f32_16x16x32_bf16 v[8:11], v[136:139], v[208:211], v[8:11]
	v_mfma_f32_16x16x32_bf16 v[60:63], v[132:135], v[182:185], v[60:63]
	v_mfma_f32_16x16x32_bf16 v[56:59], v[140:143], v[182:185], v[56:59]
	v_mfma_f32_16x16x32_bf16 v[44:47], v[132:135], v[196:199], v[44:47]
	v_mfma_f32_16x16x32_bf16 v[40:43], v[140:143], v[196:199], v[40:43]
	v_mfma_f32_16x16x32_bf16 v[28:31], v[132:135], v[204:207], v[28:31]
	v_mfma_f32_16x16x32_bf16 v[24:27], v[140:143], v[204:207], v[24:27]
	v_mfma_f32_16x16x32_bf16 v[12:15], v[132:135], v[216:219], v[12:15]
	v_mfma_f32_16x16x32_bf16 v[8:11], v[140:143], v[216:219], v[8:11]
	v_mfma_f32_16x16x32_bf16 v[52:55], v[144:147], v[160:163], v[52:55]
	v_mfma_f32_16x16x32_bf16 v[48:51], v[152:155], v[160:163], v[48:51]
	v_mfma_f32_16x16x32_bf16 v[36:39], v[144:147], v[192:195], v[36:39]
	v_mfma_f32_16x16x32_bf16 v[32:35], v[152:155], v[192:195], v[32:35]
	v_mfma_f32_16x16x32_bf16 v[20:23], v[144:147], v[200:203], v[20:23]
	v_mfma_f32_16x16x32_bf16 v[16:19], v[152:155], v[200:203], v[16:19]
	v_mfma_f32_16x16x32_bf16 v[4:7], v[144:147], v[208:211], v[4:7]
	v_mfma_f32_16x16x32_bf16 v[0:3], v[152:155], v[208:211], v[0:3]
	v_mfma_f32_16x16x32_bf16 v[52:55], v[148:151], v[182:185], v[52:55]
	v_mfma_f32_16x16x32_bf16 v[48:51], v[156:159], v[182:185], v[48:51]
	v_mfma_f32_16x16x32_bf16 v[36:39], v[148:151], v[196:199], v[36:39]
	v_mfma_f32_16x16x32_bf16 v[32:35], v[156:159], v[196:199], v[32:35]
	v_mfma_f32_16x16x32_bf16 v[20:23], v[148:151], v[204:207], v[20:23]
	v_mfma_f32_16x16x32_bf16 v[16:19], v[156:159], v[204:207], v[16:19]
	v_mfma_f32_16x16x32_bf16 v[4:7], v[148:151], v[216:219], v[4:7]
	v_mfma_f32_16x16x32_bf16 v[0:3], v[156:159], v[216:219], v[0:3]
	s_barrier
	s_add_i32 s80, 0, 0x18000
	s_add_i32 s81, 0, 0x1c000
	v_add_u32_e32 v140, s80, v186
	v_add_u32_e32 v156, s81, v186
	ds_read_b128 v[128:131], v140
	ds_read_b128 v[132:135], v140 offset:1024
	ds_read_b128 v[136:139], v140 offset:2048
	ds_read_b128 v[140:143], v140 offset:3072
	ds_read_b128 v[144:147], v156
	ds_read_b128 v[148:151], v156 offset:1024
	ds_read_b128 v[152:155], v156 offset:2048
	ds_read_b128 v[156:159], v156 offset:3072
	s_add_u32 s58, s58, 0x80000
	s_addc_u32 s59, s59, 0
	s_mov_b32 m0, s62
	v_lshl_add_u64 v[226:227], s[58:59], 0, v[166:167]
	ds_read_b128 v[160:163], v190 offset:32768
	ds_read_b128 v[182:185], v190 offset:33792
	ds_read_b128 v[192:195], v190 offset:34816
	ds_read_b128 v[196:199], v190 offset:35840
	ds_read_b128 v[200:203], v190 offset:36864
	ds_read_b128 v[204:207], v190 offset:37888
	ds_read_b128 v[208:211], v190 offset:38912
	ds_read_b128 v[216:219], v190 offset:39936
	global_load_lds_dwordx4 v[226:227], off
	v_lshl_add_u64 v[226:227], s[58:59], 0, v[170:171]
	s_mov_b32 m0, s63
	s_nop 0
	global_load_lds_dwordx4 v[226:227], off
	s_waitcnt vmcnt(8)
	s_waitcnt lgkmcnt(0)
	s_barrier
	s_waitcnt lgkmcnt(0)
	v_mfma_f32_16x16x32_bf16 v[124:127], v[128:131], v[160:163], v[124:127]
	v_mfma_f32_16x16x32_bf16 v[120:123], v[136:139], v[160:163], v[120:123]
	v_mfma_f32_16x16x32_bf16 v[108:111], v[128:131], v[192:195], v[108:111]
	v_mfma_f32_16x16x32_bf16 v[104:107], v[136:139], v[192:195], v[104:107]
	v_mfma_f32_16x16x32_bf16 v[92:95], v[128:131], v[200:203], v[92:95]
	v_mfma_f32_16x16x32_bf16 v[88:91], v[136:139], v[200:203], v[88:91]
	v_mfma_f32_16x16x32_bf16 v[76:79], v[128:131], v[208:211], v[76:79]
	v_mfma_f32_16x16x32_bf16 v[72:75], v[136:139], v[208:211], v[72:75]
	v_mfma_f32_16x16x32_bf16 v[124:127], v[132:135], v[182:185], v[124:127]
	v_mfma_f32_16x16x32_bf16 v[120:123], v[140:143], v[182:185], v[120:123]
	v_mfma_f32_16x16x32_bf16 v[108:111], v[132:135], v[196:199], v[108:111]
	v_mfma_f32_16x16x32_bf16 v[104:107], v[140:143], v[196:199], v[104:107]
	v_mfma_f32_16x16x32_bf16 v[92:95], v[132:135], v[204:207], v[92:95]
	v_mfma_f32_16x16x32_bf16 v[88:91], v[140:143], v[204:207], v[88:91]
	v_mfma_f32_16x16x32_bf16 v[76:79], v[132:135], v[216:219], v[76:79]
	v_mfma_f32_16x16x32_bf16 v[72:75], v[140:143], v[216:219], v[72:75]
	v_mfma_f32_16x16x32_bf16 v[116:119], v[144:147], v[160:163], v[116:119]
	v_mfma_f32_16x16x32_bf16 v[112:115], v[152:155], v[160:163], v[112:115]
	v_mfma_f32_16x16x32_bf16 v[100:103], v[144:147], v[192:195], v[100:103]
	v_mfma_f32_16x16x32_bf16 v[96:99], v[152:155], v[192:195], v[96:99]
	v_mfma_f32_16x16x32_bf16 v[84:87], v[144:147], v[200:203], v[84:87]
	v_mfma_f32_16x16x32_bf16 v[80:83], v[152:155], v[200:203], v[80:83]
	v_mfma_f32_16x16x32_bf16 v[68:71], v[144:147], v[208:211], v[68:71]
	v_mfma_f32_16x16x32_bf16 v[64:67], v[152:155], v[208:211], v[64:67]
	v_mfma_f32_16x16x32_bf16 v[116:119], v[148:151], v[182:185], v[116:119]
	v_mfma_f32_16x16x32_bf16 v[112:115], v[156:159], v[182:185], v[112:115]
	v_mfma_f32_16x16x32_bf16 v[100:103], v[148:151], v[196:199], v[100:103]
	v_mfma_f32_16x16x32_bf16 v[96:99], v[156:159], v[196:199], v[96:99]
	v_mfma_f32_16x16x32_bf16 v[84:87], v[148:151], v[204:207], v[84:87]
	v_mfma_f32_16x16x32_bf16 v[80:83], v[156:159], v[204:207], v[80:83]
	v_mfma_f32_16x16x32_bf16 v[68:71], v[148:151], v[216:219], v[68:71]
	v_mfma_f32_16x16x32_bf16 v[64:67], v[156:159], v[216:219], v[64:67]
	s_barrier
; #define PG8_STAGE(bufoff, gbase, voff) do { _Pragma("unroll") for (int _i = 0; _i < 2; ++_i) \
;         __builtin_amdgcn_global_load_lds((const unsigned*)((const char*)(gbase) + (voff)[_i]), (LAS unsigned*)(lds + (bufoff) + ldsw + _i * 8192), 16, 0, 0); } while (0)
; #define PG8_LDA(dst, b, h) do { _Pragma("unroll") for (int m = 0; m < 4; ++m) _Pragma("unroll") for (int k = 0; k < 2; ++k) dst[m][k] = *(const LAS bf16x8*)(lds + PG8_SA(b, h) + aoff + m * 2048 + k * 1024); } while (0)
; #define PG8_LDB(dst, b, h) do { _Pragma("unroll") for (int n = 0; n < 2; ++n) _Pragma("unroll") for (int k = 0; k < 2; ++k) dst[n][k] = *(const LAS bf16x8*)(lds + PG8_SB(b, h) + boff + n * 2048 + k * 1024); } while (0)
; #define PG8_MMA(ai, bj, At, Bt) do { __builtin_amdgcn_s_setprio(1); _Pragma("unroll") for (int m = 0; m < 4; ++m) _Pragma("unroll") for (int n = 0; n < 2; ++n) _Pragma("unroll") for (int k = 0; k < 2; ++k) \
;         acc[ai][bj][m][n] = __builtin_amdgcn_mfma_f32_16x16x32_bf16(Bt[n][k], At[m][k], acc[ai][bj][m][n], 0, 0, 0); __builtin_amdgcn_s_setprio(0); } while (0)
; #define PG8_WAIT_V(n) asm volatile("s_waitcnt vmcnt(" #n ")" ::: "memory")
; #define PG8_WAIT_L(n) asm volatile("s_waitcnt lgkmcnt(" #n ")" ::: "memory")
; #define PG8_BAR __builtin_amdgcn_s_barrier()
; #define PG8_SCHED __builtin_amdgcn_sched_barrier(0)
; template <class Epi, bool ALIGN_EPI = false, bool SP2 = true>
; __device__ __forceinline__ void gemm_phase(LAS unsigned char* lds, const Gemm g, const StaticOrder& S, const Epi& E) {
;     ...
;             PG8_LDB(B0, 1, 0); PG8_LDB(B1, 1, 1); PG8_SCHED; PG8_LDA(At, 1, 0); PG8_STAGE(PG8_SA(0, 1), a2 + hstep, voffA);
;             PG8_WAIT_V(8); PG8_WAIT_L(0); PG8_BAR; PG8_MMA(0, 0, At, B0); PG8_MMA(0, 1, At, B1); PG8_BAR; PG8_SCHED;
;             PG8_LDA(At, 1, 1); PG8_STAGE(PG8_SB(1, 0), b3, voffB); PG8_STAGE(PG8_SB(1, 1), b3 + hstep, voffB); PG8_STAGE(PG8_SA(1, 0), a3, voffA);
;             PG8_WAIT_V(8); PG8_WAIT_L(0); PG8_BAR; PG8_MMA(1, 0, At, B0); PG8_MMA(1, 1, At, B1); PG8_BAR; PG8_SCHED;
	s_add_i32 s58, s80, s60
	v_lshl_add_u64 v[212:213], v[212:213], 0, s[16:17]
	s_mov_b32 m0, s58
	ds_read_b128 v[160:163], v190 offset:49152
	ds_read_b128 v[182:185], v190 offset:50176
	ds_read_b128 v[192:195], v190 offset:51200
	ds_read_b128 v[196:199], v190 offset:52224
	ds_read_b128 v[200:203], v190 offset:53248
	ds_read_b128 v[204:207], v190 offset:54272
	ds_read_b128 v[208:211], v190 offset:55296
	ds_read_b128 v[216:219], v190 offset:56320
	global_load_lds_dwordx4 v[212:213], off
	s_add_i32 m0, s58, 0x2000
	s_add_u32 s56, s56, 0x80080
	v_lshl_add_u64 v[212:213], v[220:221], 0, s[16:17]
	s_addc_u32 s57, s57, 0
	s_add_i32 s58, s81, s60
	global_load_lds_dwordx4 v[212:213], off
	v_lshl_add_u64 v[212:213], s[56:57], 0, v[168:169]
	s_mov_b32 m0, s58
	s_nop 0
	global_load_lds_dwordx4 v[212:213], off
	v_lshl_add_u64 v[212:213], s[56:57], 0, v[172:173]
	s_add_i32 m0, s58, 0x2000
	s_nop 0
	global_load_lds_dwordx4 v[212:213], off
	v_lshl_add_u64 v[212:213], v[222:223], 0, s[16:17]
	s_mov_b32 m0, s66
	s_nop 0
	global_load_lds_dwordx4 v[212:213], off
	v_lshl_add_u64 v[212:213], v[224:225], 0, s[16:17]
	s_mov_b32 m0, s67
	s_nop 0
	global_load_lds_dwordx4 v[212:213], off
	s_waitcnt vmcnt(8)
	s_waitcnt lgkmcnt(0)
	s_barrier
	s_waitcnt lgkmcnt(0)
	v_mfma_f32_16x16x32_bf16 v[60:63], v[128:131], v[160:163], v[60:63]
	v_mfma_f32_16x16x32_bf16 v[56:59], v[136:139], v[160:163], v[56:59]
	v_mfma_f32_16x16x32_bf16 v[44:47], v[128:131], v[192:195], v[44:47]
	v_mfma_f32_16x16x32_bf16 v[40:43], v[136:139], v[192:195], v[40:43]
	v_mfma_f32_16x16x32_bf16 v[28:31], v[128:131], v[200:203], v[28:31]
	v_mfma_f32_16x16x32_bf16 v[24:27], v[136:139], v[200:203], v[24:27]
	v_mfma_f32_16x16x32_bf16 v[12:15], v[128:131], v[208:211], v[12:15]
	v_mfma_f32_16x16x32_bf16 v[8:11], v[136:139], v[208:211], v[8:11]
	v_mfma_f32_16x16x32_bf16 v[60:63], v[132:135], v[182:185], v[60:63]
	v_mfma_f32_16x16x32_bf16 v[56:59], v[140:143], v[182:185], v[56:59]
	v_mfma_f32_16x16x32_bf16 v[44:47], v[132:135], v[196:199], v[44:47]
	v_mfma_f32_16x16x32_bf16 v[40:43], v[140:143], v[196:199], v[40:43]
	v_mfma_f32_16x16x32_bf16 v[28:31], v[132:135], v[204:207], v[28:31]
	v_mfma_f32_16x16x32_bf16 v[24:27], v[140:143], v[204:207], v[24:27]
	v_mfma_f32_16x16x32_bf16 v[12:15], v[132:135], v[216:219], v[12:15]
	v_mfma_f32_16x16x32_bf16 v[8:11], v[140:143], v[216:219], v[8:11]
	v_mfma_f32_16x16x32_bf16 v[52:55], v[144:147], v[160:163], v[52:55]
	v_mfma_f32_16x16x32_bf16 v[48:51], v[152:155], v[160:163], v[48:51]
	v_mfma_f32_16x16x32_bf16 v[36:39], v[144:147], v[192:195], v[36:39]
	v_mfma_f32_16x16x32_bf16 v[32:35], v[152:155], v[192:195], v[32:35]
	v_mfma_f32_16x16x32_bf16 v[20:23], v[144:147], v[200:203], v[20:23]
	v_mfma_f32_16x16x32_bf16 v[16:19], v[152:155], v[200:203], v[16:19]
	v_mfma_f32_16x16x32_bf16 v[4:7], v[144:147], v[208:211], v[4:7]
	v_mfma_f32_16x16x32_bf16 v[0:3], v[152:155], v[208:211], v[0:3]
	v_mfma_f32_16x16x32_bf16 v[52:55], v[148:151], v[182:185], v[52:55]
	v_mfma_f32_16x16x32_bf16 v[48:51], v[156:159], v[182:185], v[48:51]
	v_mfma_f32_16x16x32_bf16 v[36:39], v[148:151], v[196:199], v[36:39]
	v_mfma_f32_16x16x32_bf16 v[32:35], v[156:159], v[196:199], v[32:35]
	v_mfma_f32_16x16x32_bf16 v[20:23], v[148:151], v[204:207], v[20:23]
	v_mfma_f32_16x16x32_bf16 v[16:19], v[156:159], v[204:207], v[16:19]
	v_mfma_f32_16x16x32_bf16 v[4:7], v[148:151], v[216:219], v[4:7]
	v_mfma_f32_16x16x32_bf16 v[0:3], v[156:159], v[216:219], v[0:3]
	s_barrier
	s_add_i32 s79, s79, 2
	s_add_u32 s36, s36, 0x100
	s_addc_u32 s37, s37, 0
	s_add_u32 s77, s77, 0x100
	s_addc_u32 s78, s78, 0
	s_cmp_gt_u32 s79, 29
	s_cbranch_scc0 .LBB0_441
	s_and_b64 vcc, exec, s[18:19]
	s_cbranch_vccz .LBB0_444
	s_barrier

; __device__ __forceinline__ unsigned xb_add(unsigned* p, unsigned v) { return __hip_atomic_fetch_add(p, v, __ATOMIC_RELAXED, __HIP_MEMORY_SCOPE_AGENT); }
; __device__ __forceinline__ void xcd_barrier(const XcdBarrier& b) {
;     asm volatile("s_waitcnt vmcnt(0)" ::: "memory");
;     __syncthreads();
;     if (threadIdx.x == 0) {
;         unsigned* bar = b.bar;
;         __builtin_amdgcn_s_waitcnt(0);
;         unsigned nloc = b.st[0], nx = b.st[1];
;         if (nloc == 0u) { xcd_barrier_complete(bar, b.x, nloc, nx); b.st[0] = nloc; b.st[1] = nx; }
;         const unsigned old = xb_add(&bar[XB_XSUB(b.x)], 1u);
;         const unsigned gen = old / nloc;
;         if (old + 1u == (gen + 1u) * nloc) {
;             __builtin_amdgcn_fence(__ATOMIC_RELEASE, "agent");
;             asm volatile("s_waitcnt vmcnt(0)" ::: "memory");
;             const unsigned og = xb_add(&bar[XB_TOP], 1u);
.LBB0_448:
	s_cmp_gt_i32 s43, 6
	s_setprio 0
	s_cselect_b64 s[4:5], -1, 0
	s_and_b64 s[0:1], s[0:1], s[4:5]
	s_andn2_b64 vcc, exec, s[0:1]
	s_cbranch_vccnz .LBB0_498
	s_waitcnt vmcnt(0)
	s_waitcnt vmcnt(0) lgkmcnt(0)
	s_barrier
	s_and_saveexec_b64 s[0:1], s[12:13]
	s_cbranch_execz .LBB0_497
	s_and_b32 s98, s2, 7
	s_lshl_b32 s98, s98, 2
	s_bfe_u32 s99, s2, 0x20003
	s_or_b32 s98, s98, s99
	s_lshl_b32 s98, s98, 6
	s_add_i32 s98, s98, 0xa400
	v_mov_b32_e32 v250, s98
	v_mov_b32_e32 v252, 1
	v_mov_b32_e32 v253, 0x2000c
	ds_read_b32 v254, v253
	s_waitcnt lgkmcnt(0)
	v_readfirstlane_b32 s99, v254
	s_cmp_eq_u32 s99, 1
	s_cbranch_scc1 .Lpb5_fast
	buffer_wbl2 sc1
	s_waitcnt vmcnt(0)

; #define PG8_STAGE(bufoff, gbase, voff) do { _Pragma("unroll") for (int _i = 0; _i < 2; ++_i) \
;         __builtin_amdgcn_global_load_lds((const unsigned*)((const char*)(gbase) + (voff)[_i]), (LAS unsigned*)(lds + (bufoff) + ldsw + _i * 8192), 16, 0, 0); } while (0)
; #define PG8_WAIT_V(n) asm volatile("s_waitcnt vmcnt(" #n ")" ::: "memory")
; #define PG8_BAR __builtin_amdgcn_s_barrier()
; template <class Epi, bool ALIGN_EPI = false, bool SP2 = true>
; __device__ __forceinline__ void gemm_phase(LAS unsigned char* lds, const Gemm g, const StaticOrder& S, const Epi& E) {
;     ...
;     const char* cA = (const char*)g.A + (size_t)cur.pm * tstep; const char* cB = (const char*)g.Bt + (size_t)(cur.pn + (cur.pm >= g.bsplit ? g.badd : 0)) * tstep;
;     if constexpr (SP2) {
;         PG8_STAGE(PG8_SB(0, 0), cB, voffB); PG8_STAGE(PG8_SB(0, 1), cB + hstep, voffB); PG8_STAGE(PG8_SA(0, 0), cA, voffA); PG8_STAGE(PG8_SA(0, 1), cA + hstep, voffA);
;         if (wr == 1) PG8_BAR;
;         PG8_WAIT_V(2); PG8_BAR;
;         PG8_STAGE(PG8_SB(1, 0), cB + kstep, voffB); PG8_STAGE(PG8_SA(1, 0), cA + kstep, voffA); PG8_STAGE(PG8_SB(1, 1), cB + hstep + kstep, voffB);
;         PG8_WAIT_V(6); PG8_BAR;
.LBB0_505:
	s_andn2_b64 vcc, exec, s[4:5]
	s_cbranch_vccnz .LBB0_571
	s_waitcnt vmcnt(0)
	v_lshrrev_b32_e32 v2, 1, v164
	v_and_b32_e32 v11, 24, v2
	v_lshrrev_b32_e32 v2, 5, v164
	v_and_b32_e32 v2, 4, v2
	v_bfe_u32 v3, v164, 2, 2
	v_lshlrev_b32_e32 v0, 4, v164
	v_and_b32_e32 v1, 32, v164
	v_bfe_u32 v10, v164, 2, 4
	v_or3_b32 v2, v2, v3, v11
	v_lshrrev_b32_e32 v3, 3, v164
	s_movk_i32 s4, 0x70
	v_bitop3_b32 v8, v0, v1, 48 bitop3:0x6c
	v_and_b32_e32 v9, 64, v164
	v_and_or_b32 v4, v3, s4, v10
	s_movk_i32 s4, 0x60
	v_add_u32_e32 v12, 0x2000, v0
	v_or_b32_e32 v1, v8, v9
	v_and_or_b32 v3, v3, s4, v2
	v_lshrrev_b32_e32 v0, 7, v12
	s_movk_i32 s4, 0xf0
	v_lshl_or_b32 v130, v3, 12, v1
	v_and_or_b32 v3, v0, s4, v10
	s_movk_i32 s4, 0xe0
	v_and_or_b32 v0, v0, s4, v2
	s_lshr_b32 s4, s26, 6
	s_ashr_i32 s19, s18, 31
	s_ashr_i32 s9, s8, 31
	s_lshr_b32 s29, s26, 8
	s_lshl_b32 s64, s4, 10
	s_lshl_b64 s[6:7], s[18:19], 20
	s_lshl_b64 s[10:11], s[8:9], 20
	s_add_u32 s60, s40, s10
	s_addc_u32 s61, s41, s11
	s_add_i32 s65, s64, 0
	s_add_i32 m0, s65, 0x10000
	v_lshl_or_b32 v134, v0, 12, v1
	global_load_lds_dwordx4 v130, s[60:61]
	s_add_i32 m0, s65, 0x12000
	s_add_u32 s10, s60, 0x80000
	global_load_lds_dwordx4 v134, s[60:61]
	s_addc_u32 s11, s61, 0
	s_add_i32 m0, s65, 0x14000
	v_lshl_or_b32 v128, v4, 12, v1
	global_load_lds_dwordx4 v130, s[10:11]
	s_add_i32 m0, s65, 0x16000
	v_lshl_or_b32 v132, v3, 12, v1
	global_load_lds_dwordx4 v134, s[10:11]
	s_add_u32 s10, s20, s6
	s_addc_u32 s11, s21, s7
	s_add_i32 s66, s65, 0x2000
	s_mov_b32 m0, s65
	s_add_u32 s6, s10, 0x80000
	global_load_lds_dwordx4 v128, s[10:11]
	s_mov_b32 m0, s66
	s_addc_u32 s7, s11, 0
	s_add_i32 s67, s65, 0x4000
	global_load_lds_dwordx4 v132, s[10:11]
	s_mov_b32 m0, s67
	s_add_i32 s68, s65, 0x6000
	global_load_lds_dwordx4 v128, s[6:7]
	s_mov_b32 m0, s68
	v_mov_b32_e32 v137, 0
	global_load_lds_dwordx4 v132, s[6:7]
	v_mov_b32_e32 v131, v137
	v_mov_b32_e32 v135, v137
	v_mov_b32_e32 v129, v137
	v_mov_b32_e32 v133, v137
	s_cmp_eq_u32 s29, 1
	s_mov_b32 s19, 0
	v_lshl_add_u64 v[6:7], s[60:61], 0, v[130:131]
	v_lshl_add_u64 v[4:5], s[60:61], 0, v[134:135]
	v_lshl_add_u64 v[0:1], s[10:11], 0, v[128:129]
	s_cselect_b64 s[22:23], -1, 0
	s_cmp_lg_u32 s29, 1
	v_lshl_add_u64 v[2:3], s[10:11], 0, v[132:133]
	s_cbranch_scc1 .LBB0_508
	s_barrier
	s_setprio 1

; #define PG8_STAGE(bufoff, gbase, voff) do { _Pragma("unroll") for (int _i = 0; _i < 2; ++_i) \
;         __builtin_amdgcn_global_load_lds((const unsigned*)((const char*)(gbase) + (voff)[_i]), (LAS unsigned*)(lds + (bufoff) + ldsw + _i * 8192), 16, 0, 0); } while (0)
; #define PG8_LDA(dst, b, h) do { _Pragma("unroll") for (int m = 0; m < 4; ++m) _Pragma("unroll") for (int k = 0; k < 2; ++k) dst[m][k] = *(const LAS bf16x8*)(lds + PG8_SA(b, h) + aoff + m * 2048 + k * 1024); } while (0)
; #define PG8_LDB(dst, b, h) do { _Pragma("unroll") for (int n = 0; n < 2; ++n) _Pragma("unroll") for (int k = 0; k < 2; ++k) dst[n][k] = *(const LAS bf16x8*)(lds + PG8_SB(b, h) + boff + n * 2048 + k * 1024); } while (0)
; #define PG8_WAIT_V(n) asm volatile("s_waitcnt vmcnt(" #n ")" ::: "memory")
; #define PG8_WAIT_L(n) asm volatile("s_waitcnt lgkmcnt(" #n ")" ::: "memory")
; #define PG8_BAR __builtin_amdgcn_s_barrier()
; #define PG8_SCHED __builtin_amdgcn_sched_barrier(0)
; template <class Epi, bool ALIGN_EPI = false, bool SP2 = true>
; __device__ __forceinline__ void gemm_phase(LAS unsigned char* lds, const Gemm g, const StaticOrder& S, const Epi& E) {
;     ...
;         const bool has_next = S.next(ui + 1, nxt);
;         const char* nA = has_next ? (const char*)g.A + (size_t)nxt.pm * tstep : cA; const char* nB = has_next ? (const char*)g.Bt + (size_t)(nxt.pn + (nxt.pm >= g.bsplit ? g.badd : 0)) * tstep : cB;
;         for (int t = 0; t < nt; t += 2) {
;             const bool last = (t == nt - 2);
;             const char* a1 = cA + (size_t)(t + 1) * kstep;
;             const char* a2 = last ? nA : cA + (size_t)(t + 2) * kstep; const char* b2 = last ? nB : cB + (size_t)(t + 2) * kstep;
;             const char* a3 = a2 + kstep; const char* b3 = b2 + kstep;
;             if constexpr (SP2) {
;             PG8_LDB(B0, 0, 0); PG8_LDB(B1, 0, 1); PG8_SCHED; PG8_LDA(At, 0, 0); PG8_STAGE(PG8_SA(1, 1), a1 + hstep, voffA);
;             PG8_WAIT_V(8); PG8_WAIT_L(0); PG8_BAR; PG8_MMA(0, 0, At, B0); PG8_MMA(0, 1, At, B1); PG8_BAR; PG8_SCHED;
;             PG8_LDA(At, 0, 1); PG8_STAGE(PG8_SB(0, 0), b2, voffB); PG8_STAGE(PG8_SB(0, 1), b2 + hstep, voffB); PG8_STAGE(PG8_SA(0, 0), a2, voffA);
;             PG8_WAIT_V(8); PG8_WAIT_L(0); PG8_BAR; PG8_MMA(1, 0, At, B0); PG8_MMA(1, 1, At, B1); PG8_BAR; PG8_SCHED;
.LBB0_518:
	ds_read_b128 v[148:151], v166
	s_waitcnt lgkmcnt(0)
	ds_read_b128 v[152:155], v166 offset:1024
	ds_read_b128 v[156:159], v166 offset:2048
	ds_read_b128 v[170:173], v166 offset:3072
	ds_read_b128 v[174:177], v167
	ds_read_b128 v[178:181], v167 offset:1024
	ds_read_b128 v[182:185], v167 offset:2048
	ds_read_b128 v[186:189], v167 offset:3072
	s_add_u32 s60, s10, 0xfff80080
	s_addc_u32 s61, s11, -1
	s_cmp_eq_u32 s82, 28
	s_cselect_b32 s63, s9, s61
	s_cselect_b32 s62, s37, s60
	s_cselect_b32 s61, s31, s81
	s_cselect_b32 s60, s79, s80
	v_lshl_add_u64 v[160:161], s[10:11], 0, v[138:139]
	s_add_i32 m0, s65, 0xc000
	ds_read_b128 v[190:193], v168
	ds_read_b128 v[194:197], v168 offset:1024
	ds_read_b128 v[198:201], v168 offset:2048
	ds_read_b128 v[202:205], v168 offset:3072
	ds_read_b128 v[206:209], v168 offset:4096
	ds_read_b128 v[210:213], v168 offset:5120
	ds_read_b128 v[216:219], v168 offset:6144
	ds_read_b128 v[220:223], v168 offset:7168
	global_load_lds_dwordx4 v[160:161], off
	v_lshl_add_u64 v[160:161], s[10:11], 0, v[140:141]
	s_add_i32 m0, s65, 0xe000
	s_nop 0
	global_load_lds_dwordx4 v[160:161], off
	s_waitcnt vmcnt(8)
	s_waitcnt lgkmcnt(0)
	s_barrier
	s_waitcnt lgkmcnt(0)
	v_mfma_f32_16x16x32_bf16 v[124:127], v[148:151], v[190:193], v[124:127]
	v_mfma_f32_16x16x32_bf16 v[92:95], v[156:159], v[190:193], v[92:95]
	v_mfma_f32_16x16x32_bf16 v[120:123], v[148:151], v[198:201], v[120:123]
	v_mfma_f32_16x16x32_bf16 v[88:91], v[156:159], v[198:201], v[88:91]
	v_mfma_f32_16x16x32_bf16 v[116:119], v[148:151], v[206:209], v[116:119]
	v_mfma_f32_16x16x32_bf16 v[84:87], v[156:159], v[206:209], v[84:87]
	v_mfma_f32_16x16x32_bf16 v[112:115], v[148:151], v[216:219], v[112:115]
	v_mfma_f32_16x16x32_bf16 v[80:83], v[156:159], v[216:219], v[80:83]
	v_mfma_f32_16x16x32_bf16 v[124:127], v[152:155], v[194:197], v[124:127]
	v_mfma_f32_16x16x32_bf16 v[92:95], v[170:173], v[194:197], v[92:95]
	v_mfma_f32_16x16x32_bf16 v[120:123], v[152:155], v[202:205], v[120:123]
	v_mfma_f32_16x16x32_bf16 v[88:91], v[170:173], v[202:205], v[88:91]
	v_mfma_f32_16x16x32_bf16 v[116:119], v[152:155], v[210:213], v[116:119]
	v_mfma_f32_16x16x32_bf16 v[84:87], v[170:173], v[210:213], v[84:87]
	v_mfma_f32_16x16x32_bf16 v[112:115], v[152:155], v[220:223], v[112:115]
	v_mfma_f32_16x16x32_bf16 v[80:83], v[170:173], v[220:223], v[80:83]
	v_mfma_f32_16x16x32_bf16 v[60:63], v[174:177], v[190:193], v[60:63]
	v_mfma_f32_16x16x32_bf16 v[28:31], v[182:185], v[190:193], v[28:31]
	v_mfma_f32_16x16x32_bf16 v[56:59], v[174:177], v[198:201], v[56:59]
	v_mfma_f32_16x16x32_bf16 v[24:27], v[182:185], v[198:201], v[24:27]
	v_mfma_f32_16x16x32_bf16 v[52:55], v[174:177], v[206:209], v[52:55]
	v_mfma_f32_16x16x32_bf16 v[20:23], v[182:185], v[206:209], v[20:23]
	v_mfma_f32_16x16x32_bf16 v[48:51], v[174:177], v[216:219], v[48:51]
	v_mfma_f32_16x16x32_bf16 v[16:19], v[182:185], v[216:219], v[16:19]
	v_mfma_f32_16x16x32_bf16 v[60:63], v[178:181], v[194:197], v[60:63]
	v_mfma_f32_16x16x32_bf16 v[28:31], v[186:189], v[194:197], v[28:31]
	v_mfma_f32_16x16x32_bf16 v[56:59], v[178:181], v[202:205], v[56:59]
	v_mfma_f32_16x16x32_bf16 v[24:27], v[186:189], v[202:205], v[24:27]
	v_mfma_f32_16x16x32_bf16 v[52:55], v[178:181], v[210:213], v[52:55]
	v_mfma_f32_16x16x32_bf16 v[20:23], v[186:189], v[210:213], v[20:23]
	v_mfma_f32_16x16x32_bf16 v[48:51], v[178:181], v[220:223], v[48:51]
	v_mfma_f32_16x16x32_bf16 v[16:19], v[186:189], v[220:223], v[16:19]
	s_barrier
	s_add_i32 s83, s75, s64
	v_lshl_add_u64 v[160:161], s[60:61], 0, v[130:131]
	s_mov_b32 m0, s83
	ds_read_b128 v[190:193], v168 offset:16384
	ds_read_b128 v[194:197], v168 offset:17408
	ds_read_b128 v[198:201], v168 offset:18432
	ds_read_b128 v[202:205], v168 offset:19456
	ds_read_b128 v[206:209], v168 offset:20480
	ds_read_b128 v[210:213], v168 offset:21504
	ds_read_b128 v[216:219], v168 offset:22528
	ds_read_b128 v[220:223], v168 offset:23552
	global_load_lds_dwordx4 v[160:161], off
	s_add_i32 m0, s83, 0x2000
	s_add_u32 s84, s60, 0x80000
	v_lshl_add_u64 v[224:225], s[60:61], 0, v[134:135]
	s_addc_u32 s85, s61, 0
	s_add_i32 s83, s77, s64
	global_load_lds_dwordx4 v[224:225], off
	v_lshl_add_u64 v[226:227], s[84:85], 0, v[130:131]
	s_mov_b32 m0, s83
	v_lshl_add_u64 v[228:229], s[62:63], 0, v[132:133]
	global_load_lds_dwordx4 v[226:227], off
	v_lshl_add_u64 v[226:227], s[84:85], 0, v[134:135]
	s_add_i32 m0, s83, 0x2000
	s_nop 0
	global_load_lds_dwordx4 v[226:227], off
	v_lshl_add_u64 v[226:227], s[62:63], 0, v[128:129]
	s_mov_b32 m0, s65
	s_nop 0
	global_load_lds_dwordx4 v[226:227], off
	s_mov_b32 m0, s66
	s_nop 0
	global_load_lds_dwordx4 v[228:229], off
	s_waitcnt vmcnt(8)
	s_waitcnt lgkmcnt(0)
	s_barrier
; #define PG8_STAGE(bufoff, gbase, voff) do { _Pragma("unroll") for (int _i = 0; _i < 2; ++_i) \
;         __builtin_amdgcn_global_load_lds((const unsigned*)((const char*)(gbase) + (voff)[_i]), (LAS unsigned*)(lds + (bufoff) + ldsw + _i * 8192), 16, 0, 0); } while (0)
; #define PG8_LDA(dst, b, h) do { _Pragma("unroll") for (int m = 0; m < 4; ++m) _Pragma("unroll") for (int k = 0; k < 2; ++k) dst[m][k] = *(const LAS bf16x8*)(lds + PG8_SA(b, h) + aoff + m * 2048 + k * 1024); } while (0)
; #define PG8_LDB(dst, b, h) do { _Pragma("unroll") for (int n = 0; n < 2; ++n) _Pragma("unroll") for (int k = 0; k < 2; ++k) dst[n][k] = *(const LAS bf16x8*)(lds + PG8_SB(b, h) + boff + n * 2048 + k * 1024); } while (0)
; #define PG8_MMA(ai, bj, At, Bt) do { __builtin_amdgcn_s_setprio(1); _Pragma("unroll") for (int m = 0; m < 4; ++m) _Pragma("unroll") for (int n = 0; n < 2; ++n) _Pragma("unroll") for (int k = 0; k < 2; ++k) \
;         acc[ai][bj][m][n] = __builtin_amdgcn_mfma_f32_16x16x32_bf16(Bt[n][k], At[m][k], acc[ai][bj][m][n], 0, 0, 0); __builtin_amdgcn_s_setprio(0); } while (0)
; #define PG8_WAIT_V(n) asm volatile("s_waitcnt vmcnt(" #n ")" ::: "memory")
; #define PG8_WAIT_L(n) asm volatile("s_waitcnt lgkmcnt(" #n ")" ::: "memory")
; #define PG8_BAR __builtin_amdgcn_s_barrier()
; #define PG8_SCHED __builtin_amdgcn_sched_barrier(0)
; template <class Epi, bool ALIGN_EPI = false, bool SP2 = true>
; __device__ __forceinline__ void gemm_phase(LAS unsigned char* lds, const Gemm g, const StaticOrder& S, const Epi& E) {
;     ...
;             PG8_WAIT_V(8); PG8_WAIT_L(0); PG8_BAR; PG8_MMA(0, 0, At, B0); PG8_MMA(0, 1, At, B1); PG8_BAR; PG8_SCHED;
;             PG8_LDA(At, 0, 1); PG8_STAGE(PG8_SB(0, 0), b2, voffB); PG8_STAGE(PG8_SB(0, 1), b2 + hstep, voffB); PG8_STAGE(PG8_SA(0, 0), a2, voffA);
;             PG8_WAIT_V(8); PG8_WAIT_L(0); PG8_BAR; PG8_MMA(1, 0, At, B0); PG8_MMA(1, 1, At, B1); PG8_BAR; PG8_SCHED;
;             PG8_LDB(B0, 1, 0); PG8_LDB(B1, 1, 1); PG8_SCHED; PG8_LDA(At, 1, 0); PG8_STAGE(PG8_SA(0, 1), a2 + hstep, voffA);
;             PG8_WAIT_V(8); PG8_WAIT_L(0); PG8_BAR; PG8_MMA(0, 0, At, B0); PG8_MMA(0, 1, At, B1); PG8_BAR; PG8_SCHED;
	s_waitcnt lgkmcnt(0)
	v_mfma_f32_16x16x32_bf16 v[108:111], v[148:151], v[190:193], v[108:111]
	v_mfma_f32_16x16x32_bf16 v[76:79], v[156:159], v[190:193], v[76:79]
	v_mfma_f32_16x16x32_bf16 v[104:107], v[148:151], v[198:201], v[104:107]
	v_mfma_f32_16x16x32_bf16 v[72:75], v[156:159], v[198:201], v[72:75]
	v_mfma_f32_16x16x32_bf16 v[100:103], v[148:151], v[206:209], v[100:103]
	v_mfma_f32_16x16x32_bf16 v[68:71], v[156:159], v[206:209], v[68:71]
	v_mfma_f32_16x16x32_bf16 v[96:99], v[148:151], v[216:219], v[96:99]
	v_mfma_f32_16x16x32_bf16 v[64:67], v[156:159], v[216:219], v[64:67]
	v_mfma_f32_16x16x32_bf16 v[108:111], v[152:155], v[194:197], v[108:111]
	v_mfma_f32_16x16x32_bf16 v[76:79], v[170:173], v[194:197], v[76:79]
	v_mfma_f32_16x16x32_bf16 v[104:107], v[152:155], v[202:205], v[104:107]
	v_mfma_f32_16x16x32_bf16 v[72:75], v[170:173], v[202:205], v[72:75]
	v_mfma_f32_16x16x32_bf16 v[100:103], v[152:155], v[210:213], v[100:103]
	v_mfma_f32_16x16x32_bf16 v[68:71], v[170:173], v[210:213], v[68:71]
	v_mfma_f32_16x16x32_bf16 v[96:99], v[152:155], v[220:223], v[96:99]
	v_mfma_f32_16x16x32_bf16 v[64:67], v[170:173], v[220:223], v[64:67]
	v_mfma_f32_16x16x32_bf16 v[44:47], v[174:177], v[190:193], v[44:47]
	v_mfma_f32_16x16x32_bf16 v[12:15], v[182:185], v[190:193], v[12:15]
	v_mfma_f32_16x16x32_bf16 v[40:43], v[174:177], v[198:201], v[40:43]
	v_mfma_f32_16x16x32_bf16 v[8:11], v[182:185], v[198:201], v[8:11]
	v_mfma_f32_16x16x32_bf16 v[36:39], v[174:177], v[206:209], v[36:39]
	v_mfma_f32_16x16x32_bf16 v[4:7], v[182:185], v[206:209], v[4:7]
	v_mfma_f32_16x16x32_bf16 v[32:35], v[174:177], v[216:219], v[32:35]
	v_mfma_f32_16x16x32_bf16 v[0:3], v[182:185], v[216:219], v[0:3]
	v_mfma_f32_16x16x32_bf16 v[44:47], v[178:181], v[194:197], v[44:47]
	v_mfma_f32_16x16x32_bf16 v[12:15], v[186:189], v[194:197], v[12:15]
	v_mfma_f32_16x16x32_bf16 v[40:43], v[178:181], v[202:205], v[40:43]
	v_mfma_f32_16x16x32_bf16 v[8:11], v[186:189], v[202:205], v[8:11]
	v_mfma_f32_16x16x32_bf16 v[36:39], v[178:181], v[210:213], v[36:39]
	v_mfma_f32_16x16x32_bf16 v[4:7], v[186:189], v[210:213], v[4:7]
	v_mfma_f32_16x16x32_bf16 v[32:35], v[178:181], v[220:223], v[32:35]
	v_mfma_f32_16x16x32_bf16 v[0:3], v[186:189], v[220:223], v[0:3]
	s_barrier
	s_add_i32 s83, 0, 0x18000
	v_add_u32_e32 v136, s83, v163
	s_add_i32 s84, 0, 0x1c000
	ds_read_b128 v[148:151], v136
	ds_read_b128 v[152:155], v136 offset:1024
	ds_read_b128 v[156:159], v136 offset:2048
	ds_read_b128 v[170:173], v136 offset:3072
	v_add_u32_e32 v136, s84, v163
	ds_read_b128 v[174:177], v136
	ds_read_b128 v[178:181], v136 offset:1024
	ds_read_b128 v[182:185], v136 offset:2048
	ds_read_b128 v[186:189], v136 offset:3072
	s_add_u32 s62, s62, 0x80000
	s_addc_u32 s63, s63, 0
	s_mov_b32 m0, s67
	v_lshl_add_u64 v[230:231], s[62:63], 0, v[128:129]
	ds_read_b128 v[190:193], v168 offset:32768
	ds_read_b128 v[194:197], v168 offset:33792
	ds_read_b128 v[198:201], v168 offset:34816
	ds_read_b128 v[202:205], v168 offset:35840
	ds_read_b128 v[206:209], v168 offset:36864
	ds_read_b128 v[210:213], v168 offset:37888
	ds_read_b128 v[216:219], v168 offset:38912
	ds_read_b128 v[220:223], v168 offset:39936
	global_load_lds_dwordx4 v[230:231], off
	v_lshl_add_u64 v[230:231], s[62:63], 0, v[132:133]
	s_mov_b32 m0, s68
	s_nop 0
	global_load_lds_dwordx4 v[230:231], off
	s_waitcnt vmcnt(8)
	s_waitcnt lgkmcnt(0)
	s_barrier
	s_waitcnt lgkmcnt(0)
	v_mfma_f32_16x16x32_bf16 v[124:127], v[148:151], v[190:193], v[124:127]
	v_mfma_f32_16x16x32_bf16 v[92:95], v[156:159], v[190:193], v[92:95]
	v_mfma_f32_16x16x32_bf16 v[120:123], v[148:151], v[198:201], v[120:123]
	v_mfma_f32_16x16x32_bf16 v[88:91], v[156:159], v[198:201], v[88:91]
	v_mfma_f32_16x16x32_bf16 v[116:119], v[148:151], v[206:209], v[116:119]
	v_mfma_f32_16x16x32_bf16 v[84:87], v[156:159], v[206:209], v[84:87]
	v_mfma_f32_16x16x32_bf16 v[112:115], v[148:151], v[216:219], v[112:115]
	v_mfma_f32_16x16x32_bf16 v[80:83], v[156:159], v[216:219], v[80:83]
	v_mfma_f32_16x16x32_bf16 v[124:127], v[152:155], v[194:197], v[124:127]
	v_mfma_f32_16x16x32_bf16 v[92:95], v[170:173], v[194:197], v[92:95]
	v_mfma_f32_16x16x32_bf16 v[120:123], v[152:155], v[202:205], v[120:123]
	v_mfma_f32_16x16x32_bf16 v[88:91], v[170:173], v[202:205], v[88:91]
	v_mfma_f32_16x16x32_bf16 v[116:119], v[152:155], v[210:213], v[116:119]
	v_mfma_f32_16x16x32_bf16 v[84:87], v[170:173], v[210:213], v[84:87]
	v_mfma_f32_16x16x32_bf16 v[112:115], v[152:155], v[220:223], v[112:115]
	v_mfma_f32_16x16x32_bf16 v[80:83], v[170:173], v[220:223], v[80:83]
	v_mfma_f32_16x16x32_bf16 v[60:63], v[174:177], v[190:193], v[60:63]
	v_mfma_f32_16x16x32_bf16 v[28:31], v[182:185], v[190:193], v[28:31]
	v_mfma_f32_16x16x32_bf16 v[56:59], v[174:177], v[198:201], v[56:59]
	v_mfma_f32_16x16x32_bf16 v[24:27], v[182:185], v[198:201], v[24:27]
	v_mfma_f32_16x16x32_bf16 v[52:55], v[174:177], v[206:209], v[52:55]
	v_mfma_f32_16x16x32_bf16 v[20:23], v[182:185], v[206:209], v[20:23]
	v_mfma_f32_16x16x32_bf16 v[48:51], v[174:177], v[216:219], v[48:51]
	v_mfma_f32_16x16x32_bf16 v[16:19], v[182:185], v[216:219], v[16:19]
	v_mfma_f32_16x16x32_bf16 v[60:63], v[178:181], v[194:197], v[60:63]
	v_mfma_f32_16x16x32_bf16 v[28:31], v[186:189], v[194:197], v[28:31]
	v_mfma_f32_16x16x32_bf16 v[56:59], v[178:181], v[202:205], v[56:59]
	v_mfma_f32_16x16x32_bf16 v[24:27], v[186:189], v[202:205], v[24:27]
	v_mfma_f32_16x16x32_bf16 v[52:55], v[178:181], v[210:213], v[52:55]
	v_mfma_f32_16x16x32_bf16 v[20:23], v[186:189], v[210:213], v[20:23]
	v_mfma_f32_16x16x32_bf16 v[48:51], v[178:181], v[220:223], v[48:51]
	v_mfma_f32_16x16x32_bf16 v[16:19], v[186:189], v[220:223], v[16:19]
	s_barrier
; #define PG8_STAGE(bufoff, gbase, voff) do { _Pragma("unroll") for (int _i = 0; _i < 2; ++_i) \
;         __builtin_amdgcn_global_load_lds((const unsigned*)((const char*)(gbase) + (voff)[_i]), (LAS unsigned*)(lds + (bufoff) + ldsw + _i * 8192), 16, 0, 0); } while (0)
; #define PG8_LDA(dst, b, h) do { _Pragma("unroll") for (int m = 0; m < 4; ++m) _Pragma("unroll") for (int k = 0; k < 2; ++k) dst[m][k] = *(const LAS bf16x8*)(lds + PG8_SA(b, h) + aoff + m * 2048 + k * 1024); } while (0)
; #define PG8_LDB(dst, b, h) do { _Pragma("unroll") for (int n = 0; n < 2; ++n) _Pragma("unroll") for (int k = 0; k < 2; ++k) dst[n][k] = *(const LAS bf16x8*)(lds + PG8_SB(b, h) + boff + n * 2048 + k * 1024); } while (0)
; #define PG8_MMA(ai, bj, At, Bt) do { __builtin_amdgcn_s_setprio(1); _Pragma("unroll") for (int m = 0; m < 4; ++m) _Pragma("unroll") for (int n = 0; n < 2; ++n) _Pragma("unroll") for (int k = 0; k < 2; ++k) \
;         acc[ai][bj][m][n] = __builtin_amdgcn_mfma_f32_16x16x32_bf16(Bt[n][k], At[m][k], acc[ai][bj][m][n], 0, 0, 0); __builtin_amdgcn_s_setprio(0); } while (0)
; #define PG8_WAIT_V(n) asm volatile("s_waitcnt vmcnt(" #n ")" ::: "memory")
; #define PG8_WAIT_L(n) asm volatile("s_waitcnt lgkmcnt(" #n ")" ::: "memory")
; #define PG8_BAR __builtin_amdgcn_s_barrier()
; #define PG8_SCHED __builtin_amdgcn_sched_barrier(0)
; template <class Epi, bool ALIGN_EPI = false, bool SP2 = true>
; __device__ __forceinline__ void gemm_phase(LAS unsigned char* lds, const Gemm g, const StaticOrder& S, const Epi& E) {
;     ...
;             PG8_LDB(B0, 1, 0); PG8_LDB(B1, 1, 1); PG8_SCHED; PG8_LDA(At, 1, 0); PG8_STAGE(PG8_SA(0, 1), a2 + hstep, voffA);
;             PG8_WAIT_V(8); PG8_WAIT_L(0); PG8_BAR; PG8_MMA(0, 0, At, B0); PG8_MMA(0, 1, At, B1); PG8_BAR; PG8_SCHED;
;             PG8_LDA(At, 1, 1); PG8_STAGE(PG8_SB(1, 0), b3, voffB); PG8_STAGE(PG8_SB(1, 1), b3 + hstep, voffB); PG8_STAGE(PG8_SA(1, 0), a3, voffA);
;             PG8_WAIT_V(8); PG8_WAIT_L(0); PG8_BAR; PG8_MMA(1, 0, At, B0); PG8_MMA(1, 1, At, B1); PG8_BAR; PG8_SCHED;
	s_add_i32 s62, s83, s64
	v_lshl_add_u64 v[160:161], v[160:161], 0, s[24:25]
	s_mov_b32 m0, s62
	ds_read_b128 v[190:193], v168 offset:49152
	ds_read_b128 v[194:197], v168 offset:50176
	ds_read_b128 v[198:201], v168 offset:51200
	ds_read_b128 v[202:205], v168 offset:52224
	ds_read_b128 v[206:209], v168 offset:53248
	ds_read_b128 v[210:213], v168 offset:54272
	ds_read_b128 v[216:219], v168 offset:55296
	ds_read_b128 v[220:223], v168 offset:56320
	global_load_lds_dwordx4 v[160:161], off
	s_add_i32 m0, s62, 0x2000
	s_add_u32 s60, s60, 0x80080
	v_lshl_add_u64 v[160:161], v[224:225], 0, s[24:25]
	s_addc_u32 s61, s61, 0
	s_add_i32 s62, s84, s64
	global_load_lds_dwordx4 v[160:161], off
	v_lshl_add_u64 v[160:161], s[60:61], 0, v[130:131]
	s_mov_b32 m0, s62
	s_nop 0
	global_load_lds_dwordx4 v[160:161], off
	v_lshl_add_u64 v[160:161], s[60:61], 0, v[134:135]
	s_add_i32 m0, s62, 0x2000
	s_nop 0
	global_load_lds_dwordx4 v[160:161], off
	v_lshl_add_u64 v[160:161], v[226:227], 0, s[24:25]
	s_mov_b32 m0, s70
	s_nop 0
	global_load_lds_dwordx4 v[160:161], off
	v_lshl_add_u64 v[160:161], v[228:229], 0, s[24:25]
	s_mov_b32 m0, s71
	s_nop 0
	global_load_lds_dwordx4 v[160:161], off
	s_waitcnt vmcnt(8)
	s_waitcnt lgkmcnt(0)
	s_barrier
	s_waitcnt lgkmcnt(0)
	v_mfma_f32_16x16x32_bf16 v[108:111], v[148:151], v[190:193], v[108:111]
	v_mfma_f32_16x16x32_bf16 v[76:79], v[156:159], v[190:193], v[76:79]
	v_mfma_f32_16x16x32_bf16 v[104:107], v[148:151], v[198:201], v[104:107]
	v_mfma_f32_16x16x32_bf16 v[72:75], v[156:159], v[198:201], v[72:75]
	v_mfma_f32_16x16x32_bf16 v[100:103], v[148:151], v[206:209], v[100:103]
	v_mfma_f32_16x16x32_bf16 v[68:71], v[156:159], v[206:209], v[68:71]
	v_mfma_f32_16x16x32_bf16 v[96:99], v[148:151], v[216:219], v[96:99]
	v_mfma_f32_16x16x32_bf16 v[64:67], v[156:159], v[216:219], v[64:67]
	v_mfma_f32_16x16x32_bf16 v[108:111], v[152:155], v[194:197], v[108:111]
	v_mfma_f32_16x16x32_bf16 v[76:79], v[170:173], v[194:197], v[76:79]
	v_mfma_f32_16x16x32_bf16 v[104:107], v[152:155], v[202:205], v[104:107]
	v_mfma_f32_16x16x32_bf16 v[72:75], v[170:173], v[202:205], v[72:75]
	v_mfma_f32_16x16x32_bf16 v[100:103], v[152:155], v[210:213], v[100:103]
	v_mfma_f32_16x16x32_bf16 v[68:71], v[170:173], v[210:213], v[68:71]
	v_mfma_f32_16x16x32_bf16 v[96:99], v[152:155], v[220:223], v[96:99]
	v_mfma_f32_16x16x32_bf16 v[64:67], v[170:173], v[220:223], v[64:67]
	v_mfma_f32_16x16x32_bf16 v[44:47], v[174:177], v[190:193], v[44:47]
	v_mfma_f32_16x16x32_bf16 v[12:15], v[182:185], v[190:193], v[12:15]
	v_mfma_f32_16x16x32_bf16 v[40:43], v[174:177], v[198:201], v[40:43]
	v_mfma_f32_16x16x32_bf16 v[8:11], v[182:185], v[198:201], v[8:11]
	v_mfma_f32_16x16x32_bf16 v[36:39], v[174:177], v[206:209], v[36:39]
	v_mfma_f32_16x16x32_bf16 v[4:7], v[182:185], v[206:209], v[4:7]
	v_mfma_f32_16x16x32_bf16 v[32:35], v[174:177], v[216:219], v[32:35]
	v_mfma_f32_16x16x32_bf16 v[0:3], v[182:185], v[216:219], v[0:3]
	v_mfma_f32_16x16x32_bf16 v[44:47], v[178:181], v[194:197], v[44:47]
	v_mfma_f32_16x16x32_bf16 v[12:15], v[186:189], v[194:197], v[12:15]
	v_mfma_f32_16x16x32_bf16 v[40:43], v[178:181], v[202:205], v[40:43]
	v_mfma_f32_16x16x32_bf16 v[8:11], v[186:189], v[202:205], v[8:11]
	v_mfma_f32_16x16x32_bf16 v[36:39], v[178:181], v[210:213], v[36:39]
	v_mfma_f32_16x16x32_bf16 v[4:7], v[186:189], v[210:213], v[4:7]
	v_mfma_f32_16x16x32_bf16 v[32:35], v[178:181], v[220:223], v[32:35]
	v_mfma_f32_16x16x32_bf16 v[0:3], v[186:189], v[220:223], v[0:3]
	s_barrier
	s_add_i32 s82, s82, 2
	s_add_u32 s10, s10, 0x100
	s_addc_u32 s11, s11, 0
	s_add_u32 s80, s80, 0x100
	s_addc_u32 s81, s81, 0
	s_cmp_gt_u32 s82, 29
	s_cbranch_scc0 .LBB0_518
	s_and_b64 vcc, exec, s[26:27]
	s_cbranch_vccz .LBB0_521
	s_barrier

; __device__ __forceinline__ unsigned xb_add(unsigned* p, unsigned v) { return __hip_atomic_fetch_add(p, v, __ATOMIC_RELAXED, __HIP_MEMORY_SCOPE_AGENT); }
; __device__ __forceinline__ void xcd_barrier(const XcdBarrier& b) {
;     asm volatile("s_waitcnt vmcnt(0)" ::: "memory");
;     __syncthreads();
;     if (threadIdx.x == 0) {
;         unsigned* bar = b.bar;
;         __builtin_amdgcn_s_waitcnt(0);
;         unsigned nloc = b.st[0], nx = b.st[1];
;         if (nloc == 0u) { xcd_barrier_complete(bar, b.x, nloc, nx); b.st[0] = nloc; b.st[1] = nx; }
;         const unsigned old = xb_add(&bar[XB_XSUB(b.x)], 1u);
;         const unsigned gen = old / nloc;
;         if (old + 1u == (gen + 1u) * nloc) {
;             __builtin_amdgcn_fence(__ATOMIC_RELEASE, "agent");
;             asm volatile("s_waitcnt vmcnt(0)" ::: "memory");
;             const unsigned og = xb_add(&bar[XB_TOP], 1u);
.LBB0_571:
	s_cmp_gt_i32 s43, 7
	s_setprio 0
	s_cselect_b64 s[4:5], -1, 0
	s_and_b64 s[6:7], s[16:17], s[4:5]
	s_andn2_b64 vcc, exec, s[6:7]
	s_cbranch_vccnz .LBB0_621
	s_waitcnt vmcnt(0)
	s_waitcnt vmcnt(0) lgkmcnt(0)
	s_barrier
	s_and_saveexec_b64 s[6:7], s[12:13]
	s_cbranch_execz .LBB0_620
	v_mov_b32_e32 v253, 0x82c0
	s_mov_b32 s99, 0

; __device__ __forceinline__ unsigned xb_add(unsigned* p, unsigned v) { return __hip_atomic_fetch_add(p, v, __ATOMIC_RELAXED, __HIP_MEMORY_SCOPE_AGENT); }
; __device__ __forceinline__ void xcd_barrier(const XcdBarrier& b) {
;     asm volatile("s_waitcnt vmcnt(0)" ::: "memory");
;     __syncthreads();
;     if (threadIdx.x == 0) {
;         unsigned* bar = b.bar;
;         __builtin_amdgcn_s_waitcnt(0);
;         unsigned nloc = b.st[0], nx = b.st[1];
;         if (nloc == 0u) { xcd_barrier_complete(bar, b.x, nloc, nx); b.st[0] = nloc; b.st[1] = nx; }
;         const unsigned old = xb_add(&bar[XB_XSUB(b.x)], 1u);
;         const unsigned gen = old / nloc;
;         if (old + 1u == (gen + 1u) * nloc) {
;             __builtin_amdgcn_fence(__ATOMIC_RELEASE, "agent");
;             asm volatile("s_waitcnt vmcnt(0)" ::: "memory");
;             const unsigned og = xb_add(&bar[XB_TOP], 1u);
.LBB0_680:
	s_cmp_gt_i32 s43, 8
	s_setprio 0
	s_cselect_b64 s[0:1], -1, 0
	s_and_b64 s[4:5], s[26:27], s[0:1]
	s_andn2_b64 vcc, exec, s[4:5]
	s_cbranch_vccnz .LBB0_730
	s_waitcnt vmcnt(0)
	s_waitcnt vmcnt(0) lgkmcnt(0)
	s_barrier
	s_and_saveexec_b64 s[4:5], s[12:13]
	s_cbranch_execz .LBB0_729
	s_and_b32 s98, s2, 7
	s_lshl_b32 s98, s98, 6
	s_add_i32 s98, s98, 0x8000
	v_mov_b32_e32 v250, s98
	v_mov_b32_e32 v252, 1
	v_mov_b32_e32 v253, 0x2000c
	ds_read_b32 v254, v253
	s_waitcnt lgkmcnt(0)
	v_readfirstlane_b32 s99, v254
	s_cmp_eq_u32 s99, 1
	s_cbranch_scc1 .Lgg7_f
	buffer_wbl2 sc1
	s_waitcnt vmcnt(0)

; #define PG8_STAGE(bufoff, gbase, voff) do { _Pragma("unroll") for (int _i = 0; _i < 2; ++_i) \
;         __builtin_amdgcn_global_load_lds((const unsigned*)((const char*)(gbase) + (voff)[_i]), (LAS unsigned*)(lds + (bufoff) + ldsw + _i * 8192), 16, 0, 0); } while (0)
; #define PG8_WAIT_V(n) asm volatile("s_waitcnt vmcnt(" #n ")" ::: "memory")
; #define PG8_BAR __builtin_amdgcn_s_barrier()
; template <class Epi, bool ALIGN_EPI = false, bool SP2 = true>
; __device__ __forceinline__ void gemm_phase(LAS unsigned char* lds, const Gemm g, const StaticOrder& S, const Epi& E) {
;     ...
;     const char* cA = (const char*)g.A + (size_t)cur.pm * tstep; const char* cB = (const char*)g.Bt + (size_t)(cur.pn + (cur.pm >= g.bsplit ? g.badd : 0)) * tstep;
;     if constexpr (SP2) {
;         PG8_STAGE(PG8_SB(0, 0), cB, voffB); PG8_STAGE(PG8_SB(0, 1), cB + hstep, voffB); PG8_STAGE(PG8_SA(0, 0), cA, voffA); PG8_STAGE(PG8_SA(0, 1), cA + hstep, voffA);
;         if (wr == 1) PG8_BAR;
;         PG8_WAIT_V(2); PG8_BAR;
;         PG8_STAGE(PG8_SB(1, 0), cB + kstep, voffB); PG8_STAGE(PG8_SA(1, 0), cA + kstep, voffA); PG8_STAGE(PG8_SB(1, 1), cB + hstep + kstep, voffB);
;         PG8_WAIT_V(6); PG8_BAR;
.LBB0_736:
	v_lshrrev_b32_e32 v148, 1, v164
	s_waitcnt vmcnt(0)
	v_lshrrev_b32_e32 v3, 5, v164
	v_and_b32_e32 v2, 24, v148
	v_and_b32_e32 v3, 4, v3
	v_bfe_u32 v4, v164, 2, 2
	v_lshlrev_b32_e32 v0, 4, v164
	v_and_b32_e32 v1, 32, v164
	v_bfe_u32 v10, v164, 2, 4
	v_or3_b32 v2, v3, v4, v2
	v_lshrrev_b32_e32 v3, 3, v164
	s_movk_i32 s1, 0x70
	v_bitop3_b32 v8, v0, v1, 48 bitop3:0x6c
	v_and_b32_e32 v9, 64, v164
	v_and_or_b32 v4, v3, s1, v10
	s_movk_i32 s1, 0x60
	v_add_u32_e32 v11, 0x2000, v0
	s_ashr_i32 s0, s5, 3
	v_or_b32_e32 v1, v8, v9
	v_and_or_b32 v3, v3, s1, v2
	v_lshrrev_b32_e32 v0, 7, v11
	s_movk_i32 s1, 0xf0
	v_lshl_or_b32 v130, v3, 12, v1
	v_and_or_b32 v3, v0, s1, v10
	s_movk_i32 s1, 0xe0
	s_add_i32 s0, s4, s0
	v_and_or_b32 v0, v0, s1, v2
	s_ashr_i32 s1, s0, 31
	s_lshr_b32 s1, s1, 27
	s_add_i32 s1, s0, s1
	s_ashr_i32 s4, s1, 5
	s_andn2_b32 s1, s1, 31
	s_sub_i32 s0, s0, s1
	s_bfe_i32 s1, s0, 0x80000
	s_bfe_u32 s1, s1, 0x2000d
	s_add_i32 s1, s0, s1
	s_lshl_b32 s6, s4, 2
	s_bfe_i32 s4, s1, 0x80000
	s_and_b32 s1, s1, 0xfc
	s_sub_i32 s0, s0, s1
	s_sext_i32_i16 s4, s4
	s_sext_i32_i8 s0, s0
	s_lshr_b32 s5, s3, 8
	s_lshr_b32 s4, s4, 2
	s_add_i32 s10, s6, s0
	s_lshr_b32 s15, s3, 6
	s_ashr_i32 s11, s10, 31
	s_bfe_i64 s[6:7], s[4:5], 0x100000
	s_lshl_b32 s57, s15, 10
	s_lshl_b64 s[0:1], s[10:11], 20
	s_lshl_b64 s[6:7], s[6:7], 20
	s_add_u32 s36, s24, s6
	s_addc_u32 s37, s25, s7
	s_add_i32 s58, s57, 0
	s_add_i32 m0, s58, 0x10000
	v_lshl_or_b32 v134, v0, 12, v1
	global_load_lds_dwordx4 v130, s[36:37]
	s_add_i32 m0, s58, 0x12000
	s_add_u32 s6, s36, 0x80000
	global_load_lds_dwordx4 v134, s[36:37]
	s_addc_u32 s7, s37, 0
	s_add_i32 m0, s58, 0x14000
	v_lshl_or_b32 v128, v4, 12, v1
	global_load_lds_dwordx4 v130, s[6:7]
	s_add_i32 m0, s58, 0x16000
	s_add_u32 s0, s38, s0
	s_addc_u32 s1, s39, s1
	s_add_i32 s59, s58, 0x2000
	global_load_lds_dwordx4 v134, s[6:7]
	s_mov_b32 m0, s58
	s_add_u32 s6, s0, 0x80000
	v_lshl_or_b32 v132, v3, 12, v1
	global_load_lds_dwordx4 v128, s[0:1]
	s_mov_b32 m0, s59
	s_addc_u32 s7, s1, 0
	s_add_i32 s60, s58, 0x4000
	global_load_lds_dwordx4 v132, s[0:1]
	s_mov_b32 m0, s60
	s_add_i32 s61, s58, 0x6000
	global_load_lds_dwordx4 v128, s[6:7]
	s_mov_b32 m0, s61
	v_mov_b32_e32 v131, 0
	global_load_lds_dwordx4 v132, s[6:7]
	v_mov_b32_e32 v135, v131
	v_mov_b32_e32 v129, v131
	v_mov_b32_e32 v133, v131
	v_lshl_add_u64 v[6:7], s[36:37], 0, v[130:131]
	v_lshl_add_u64 v[4:5], s[36:37], 0, v[134:135]
	v_lshl_add_u64 v[2:3], s[0:1], 0, v[128:129]
	s_cmp_lg_u32 s5, 1
	v_lshl_add_u64 v[0:1], s[0:1], 0, v[132:133]
	s_cbranch_scc1 .LBB0_738
	s_barrier
	s_setprio 1

; #define PG8_STAGE(bufoff, gbase, voff) do { _Pragma("unroll") for (int _i = 0; _i < 2; ++_i) \
;         __builtin_amdgcn_global_load_lds((const unsigned*)((const char*)(gbase) + (voff)[_i]), (LAS unsigned*)(lds + (bufoff) + ldsw + _i * 8192), 16, 0, 0); } while (0)
; #define PG8_LDA(dst, b, h) do { _Pragma("unroll") for (int m = 0; m < 4; ++m) _Pragma("unroll") for (int k = 0; k < 2; ++k) dst[m][k] = *(const LAS bf16x8*)(lds + PG8_SA(b, h) + aoff + m * 2048 + k * 1024); } while (0)
; #define PG8_LDB(dst, b, h) do { _Pragma("unroll") for (int n = 0; n < 2; ++n) _Pragma("unroll") for (int k = 0; k < 2; ++k) dst[n][k] = *(const LAS bf16x8*)(lds + PG8_SB(b, h) + boff + n * 2048 + k * 1024); } while (0)
; #define PG8_WAIT_V(n) asm volatile("s_waitcnt vmcnt(" #n ")" ::: "memory")
; #define PG8_WAIT_L(n) asm volatile("s_waitcnt lgkmcnt(" #n ")" ::: "memory")
; #define PG8_BAR __builtin_amdgcn_s_barrier()
; #define PG8_SCHED __builtin_amdgcn_sched_barrier(0)
; template <class Epi, bool ALIGN_EPI = false, bool SP2 = true>
; __device__ __forceinline__ void gemm_phase(LAS unsigned char* lds, const Gemm g, const StaticOrder& S, const Epi& E) {
;     ...
;         const bool has_next = S.next(ui + 1, nxt);
;         const char* nA = has_next ? (const char*)g.A + (size_t)nxt.pm * tstep : cA; const char* nB = has_next ? (const char*)g.Bt + (size_t)(nxt.pn + (nxt.pm >= g.bsplit ? g.badd : 0)) * tstep : cB;
;         for (int t = 0; t < nt; t += 2) {
;             const bool last = (t == nt - 2);
;             const char* a1 = cA + (size_t)(t + 1) * kstep;
;             const char* a2 = last ? nA : cA + (size_t)(t + 2) * kstep; const char* b2 = last ? nB : cB + (size_t)(t + 2) * kstep;
;             const char* a3 = a2 + kstep; const char* b3 = b2 + kstep;
;             if constexpr (SP2) {
;             PG8_LDB(B0, 0, 0); PG8_LDB(B1, 0, 1); PG8_SCHED; PG8_LDA(At, 0, 0); PG8_STAGE(PG8_SA(1, 1), a1 + hstep, voffA);
;             PG8_WAIT_V(8); PG8_WAIT_L(0); PG8_BAR; PG8_MMA(0, 0, At, B0); PG8_MMA(0, 1, At, B1); PG8_BAR; PG8_SCHED;
;             PG8_LDA(At, 0, 1); PG8_STAGE(PG8_SB(0, 0), b2, voffB); PG8_STAGE(PG8_SB(0, 1), b2 + hstep, voffB); PG8_STAGE(PG8_SA(0, 0), a2, voffA);
;             PG8_WAIT_V(8); PG8_WAIT_L(0); PG8_BAR; PG8_MMA(1, 0, At, B0); PG8_MMA(1, 1, At, B1); PG8_BAR; PG8_SCHED;
.LBB0_746:
	v_add_u32_e32 v161, s66, v150
	s_waitcnt lgkmcnt(0)
	ds_read_b128 v[152:155], v161
	ds_read_b128 v[156:159], v161 offset:1024
	ds_read_b128 v[166:169], v161 offset:2048
	ds_read_b128 v[170:173], v161 offset:3072
	v_add_u32_e32 v161, s67, v150
	s_add_u32 s44, s0, s36
	ds_read_b128 v[174:177], v161
	ds_read_b128 v[178:181], v161 offset:1024
	ds_read_b128 v[182:185], v161 offset:2048
	ds_read_b128 v[186:189], v161 offset:3072
	s_addc_u32 s45, s1, s37
	s_add_u32 s44, s44, 0x100
	s_addc_u32 s45, s45, 0
	s_add_u32 s74, s69, s36
	s_addc_u32 s75, s70, s37
	s_cmpk_eq_i32 s36, 0xf00
	s_cselect_b32 s51, s27, s45
	s_cselect_b32 s50, s71, s44
	s_cselect_b32 s45, s19, s75
	s_cselect_b32 s44, s72, s74
	v_lshl_add_u64 v[162:163], v[144:145], 0, s[36:37]
	s_add_i32 m0, s58, 0xc000
	ds_read_b128 v[190:193], v151
	ds_read_b128 v[194:197], v151 offset:1024
	ds_read_b128 v[198:201], v151 offset:2048
	ds_read_b128 v[202:205], v151 offset:3072
	ds_read_b128 v[206:209], v151 offset:4096
	ds_read_b128 v[210:213], v151 offset:5120
	ds_read_b128 v[214:217], v151 offset:6144
	ds_read_b128 v[218:221], v151 offset:7168
	global_load_lds_dwordx4 v[162:163], off
	v_lshl_add_u64 v[162:163], v[146:147], 0, s[36:37]
	s_add_i32 m0, s58, 0xe000
	s_nop 0
	global_load_lds_dwordx4 v[162:163], off
	s_waitcnt vmcnt(8)
	s_waitcnt lgkmcnt(0)
	s_barrier
	s_waitcnt lgkmcnt(0)
	v_mfma_f32_16x16x32_bf16 v[124:127], v[152:155], v[190:193], v[124:127]
	v_mfma_f32_16x16x32_bf16 v[120:123], v[166:169], v[190:193], v[120:123]
	v_mfma_f32_16x16x32_bf16 v[108:111], v[152:155], v[198:201], v[108:111]
	v_mfma_f32_16x16x32_bf16 v[104:107], v[166:169], v[198:201], v[104:107]
	v_mfma_f32_16x16x32_bf16 v[92:95], v[152:155], v[206:209], v[92:95]
	v_mfma_f32_16x16x32_bf16 v[88:91], v[166:169], v[206:209], v[88:91]
	v_mfma_f32_16x16x32_bf16 v[76:79], v[152:155], v[214:217], v[76:79]
	v_mfma_f32_16x16x32_bf16 v[72:75], v[166:169], v[214:217], v[72:75]
	v_mfma_f32_16x16x32_bf16 v[124:127], v[156:159], v[194:197], v[124:127]
	v_mfma_f32_16x16x32_bf16 v[120:123], v[170:173], v[194:197], v[120:123]
	v_mfma_f32_16x16x32_bf16 v[108:111], v[156:159], v[202:205], v[108:111]
	v_mfma_f32_16x16x32_bf16 v[104:107], v[170:173], v[202:205], v[104:107]
	v_mfma_f32_16x16x32_bf16 v[92:95], v[156:159], v[210:213], v[92:95]
	v_mfma_f32_16x16x32_bf16 v[88:91], v[170:173], v[210:213], v[88:91]
	v_mfma_f32_16x16x32_bf16 v[76:79], v[156:159], v[218:221], v[76:79]
	v_mfma_f32_16x16x32_bf16 v[72:75], v[170:173], v[218:221], v[72:75]
	v_mfma_f32_16x16x32_bf16 v[116:119], v[174:177], v[190:193], v[116:119]
	v_mfma_f32_16x16x32_bf16 v[112:115], v[182:185], v[190:193], v[112:115]
	v_mfma_f32_16x16x32_bf16 v[100:103], v[174:177], v[198:201], v[100:103]
	v_mfma_f32_16x16x32_bf16 v[96:99], v[182:185], v[198:201], v[96:99]
	v_mfma_f32_16x16x32_bf16 v[84:87], v[174:177], v[206:209], v[84:87]
	v_mfma_f32_16x16x32_bf16 v[80:83], v[182:185], v[206:209], v[80:83]
	v_mfma_f32_16x16x32_bf16 v[68:71], v[174:177], v[214:217], v[68:71]
	v_mfma_f32_16x16x32_bf16 v[64:67], v[182:185], v[214:217], v[64:67]
	v_mfma_f32_16x16x32_bf16 v[116:119], v[178:181], v[194:197], v[116:119]
	v_mfma_f32_16x16x32_bf16 v[112:115], v[186:189], v[194:197], v[112:115]
	v_mfma_f32_16x16x32_bf16 v[100:103], v[178:181], v[202:205], v[100:103]
	v_mfma_f32_16x16x32_bf16 v[96:99], v[186:189], v[202:205], v[96:99]
	v_mfma_f32_16x16x32_bf16 v[84:87], v[178:181], v[210:213], v[84:87]
	v_mfma_f32_16x16x32_bf16 v[80:83], v[186:189], v[210:213], v[80:83]
	v_mfma_f32_16x16x32_bf16 v[68:71], v[178:181], v[218:221], v[68:71]
	v_mfma_f32_16x16x32_bf16 v[64:67], v[186:189], v[218:221], v[64:67]
	s_barrier
	s_add_i32 s74, s66, s57
	v_lshl_add_u64 v[162:163], s[44:45], 0, v[130:131]
	s_mov_b32 m0, s74
	ds_read_b128 v[190:193], v151 offset:16384
	ds_read_b128 v[194:197], v151 offset:17408
	ds_read_b128 v[198:201], v151 offset:18432
	ds_read_b128 v[202:205], v151 offset:19456
	ds_read_b128 v[206:209], v151 offset:20480
	ds_read_b128 v[210:213], v151 offset:21504
	ds_read_b128 v[214:217], v151 offset:22528
	ds_read_b128 v[218:221], v151 offset:23552
	global_load_lds_dwordx4 v[162:163], off
	s_add_i32 m0, s74, 0x2000
	s_add_u32 s74, s44, 0x80000
	v_lshl_add_u64 v[222:223], s[44:45], 0, v[134:135]
	s_addc_u32 s75, s45, 0
	s_add_i32 s76, s67, s57
	global_load_lds_dwordx4 v[222:223], off
	v_lshl_add_u64 v[224:225], s[74:75], 0, v[130:131]
	s_mov_b32 m0, s76
	v_lshl_add_u64 v[226:227], s[50:51], 0, v[132:133]
	global_load_lds_dwordx4 v[224:225], off
	v_lshl_add_u64 v[224:225], s[74:75], 0, v[134:135]
	s_add_i32 m0, s76, 0x2000
	s_nop 0
	global_load_lds_dwordx4 v[224:225], off
	v_lshl_add_u64 v[224:225], s[50:51], 0, v[128:129]
	s_mov_b32 m0, s58
	s_nop 0
	global_load_lds_dwordx4 v[224:225], off
	s_mov_b32 m0, s59
	s_nop 0
	global_load_lds_dwordx4 v[226:227], off
	s_waitcnt vmcnt(8)
	s_waitcnt lgkmcnt(0)
	s_barrier
; #define PG8_STAGE(bufoff, gbase, voff) do { _Pragma("unroll") for (int _i = 0; _i < 2; ++_i) \
;         __builtin_amdgcn_global_load_lds((const unsigned*)((const char*)(gbase) + (voff)[_i]), (LAS unsigned*)(lds + (bufoff) + ldsw + _i * 8192), 16, 0, 0); } while (0)
; #define PG8_LDA(dst, b, h) do { _Pragma("unroll") for (int m = 0; m < 4; ++m) _Pragma("unroll") for (int k = 0; k < 2; ++k) dst[m][k] = *(const LAS bf16x8*)(lds + PG8_SA(b, h) + aoff + m * 2048 + k * 1024); } while (0)
; #define PG8_LDB(dst, b, h) do { _Pragma("unroll") for (int n = 0; n < 2; ++n) _Pragma("unroll") for (int k = 0; k < 2; ++k) dst[n][k] = *(const LAS bf16x8*)(lds + PG8_SB(b, h) + boff + n * 2048 + k * 1024); } while (0)
; #define PG8_MMA(ai, bj, At, Bt) do { __builtin_amdgcn_s_setprio(1); _Pragma("unroll") for (int m = 0; m < 4; ++m) _Pragma("unroll") for (int n = 0; n < 2; ++n) _Pragma("unroll") for (int k = 0; k < 2; ++k) \
;         acc[ai][bj][m][n] = __builtin_amdgcn_mfma_f32_16x16x32_bf16(Bt[n][k], At[m][k], acc[ai][bj][m][n], 0, 0, 0); __builtin_amdgcn_s_setprio(0); } while (0)
; #define PG8_WAIT_V(n) asm volatile("s_waitcnt vmcnt(" #n ")" ::: "memory")
; #define PG8_WAIT_L(n) asm volatile("s_waitcnt lgkmcnt(" #n ")" ::: "memory")
; #define PG8_BAR __builtin_amdgcn_s_barrier()
; #define PG8_SCHED __builtin_amdgcn_sched_barrier(0)
; template <class Epi, bool ALIGN_EPI = false, bool SP2 = true>
; __device__ __forceinline__ void gemm_phase(LAS unsigned char* lds, const Gemm g, const StaticOrder& S, const Epi& E) {
;     ...
;             PG8_WAIT_V(8); PG8_WAIT_L(0); PG8_BAR; PG8_MMA(0, 0, At, B0); PG8_MMA(0, 1, At, B1); PG8_BAR; PG8_SCHED;
;             PG8_LDA(At, 0, 1); PG8_STAGE(PG8_SB(0, 0), b2, voffB); PG8_STAGE(PG8_SB(0, 1), b2 + hstep, voffB); PG8_STAGE(PG8_SA(0, 0), a2, voffA);
;             PG8_WAIT_V(8); PG8_WAIT_L(0); PG8_BAR; PG8_MMA(1, 0, At, B0); PG8_MMA(1, 1, At, B1); PG8_BAR; PG8_SCHED;
;             PG8_LDB(B0, 1, 0); PG8_LDB(B1, 1, 1); PG8_SCHED; PG8_LDA(At, 1, 0); PG8_STAGE(PG8_SA(0, 1), a2 + hstep, voffA);
;             PG8_WAIT_V(8); PG8_WAIT_L(0); PG8_BAR; PG8_MMA(0, 0, At, B0); PG8_MMA(0, 1, At, B1); PG8_BAR; PG8_SCHED;
	s_waitcnt lgkmcnt(0)
	v_mfma_f32_16x16x32_bf16 v[60:63], v[152:155], v[190:193], v[60:63]
	v_mfma_f32_16x16x32_bf16 v[56:59], v[166:169], v[190:193], v[56:59]
	v_mfma_f32_16x16x32_bf16 v[44:47], v[152:155], v[198:201], v[44:47]
	v_mfma_f32_16x16x32_bf16 v[40:43], v[166:169], v[198:201], v[40:43]
	v_mfma_f32_16x16x32_bf16 v[28:31], v[152:155], v[206:209], v[28:31]
	v_mfma_f32_16x16x32_bf16 v[24:27], v[166:169], v[206:209], v[24:27]
	v_mfma_f32_16x16x32_bf16 v[12:15], v[152:155], v[214:217], v[12:15]
	v_mfma_f32_16x16x32_bf16 v[8:11], v[166:169], v[214:217], v[8:11]
	v_mfma_f32_16x16x32_bf16 v[60:63], v[156:159], v[194:197], v[60:63]
	v_mfma_f32_16x16x32_bf16 v[56:59], v[170:173], v[194:197], v[56:59]
	v_mfma_f32_16x16x32_bf16 v[44:47], v[156:159], v[202:205], v[44:47]
	v_mfma_f32_16x16x32_bf16 v[40:43], v[170:173], v[202:205], v[40:43]
	v_mfma_f32_16x16x32_bf16 v[28:31], v[156:159], v[210:213], v[28:31]
	v_mfma_f32_16x16x32_bf16 v[24:27], v[170:173], v[210:213], v[24:27]
	v_mfma_f32_16x16x32_bf16 v[12:15], v[156:159], v[218:221], v[12:15]
	v_mfma_f32_16x16x32_bf16 v[8:11], v[170:173], v[218:221], v[8:11]
	v_mfma_f32_16x16x32_bf16 v[52:55], v[174:177], v[190:193], v[52:55]
	v_mfma_f32_16x16x32_bf16 v[48:51], v[182:185], v[190:193], v[48:51]
	v_mfma_f32_16x16x32_bf16 v[36:39], v[174:177], v[198:201], v[36:39]
	v_mfma_f32_16x16x32_bf16 v[32:35], v[182:185], v[198:201], v[32:35]
	v_mfma_f32_16x16x32_bf16 v[20:23], v[174:177], v[206:209], v[20:23]
	v_mfma_f32_16x16x32_bf16 v[16:19], v[182:185], v[206:209], v[16:19]
	v_mfma_f32_16x16x32_bf16 v[4:7], v[174:177], v[214:217], v[4:7]
	v_mfma_f32_16x16x32_bf16 v[0:3], v[182:185], v[214:217], v[0:3]
	v_mfma_f32_16x16x32_bf16 v[52:55], v[178:181], v[194:197], v[52:55]
	v_mfma_f32_16x16x32_bf16 v[48:51], v[186:189], v[194:197], v[48:51]
	v_mfma_f32_16x16x32_bf16 v[36:39], v[178:181], v[202:205], v[36:39]
	v_mfma_f32_16x16x32_bf16 v[32:35], v[186:189], v[202:205], v[32:35]
	v_mfma_f32_16x16x32_bf16 v[20:23], v[178:181], v[210:213], v[20:23]
	v_mfma_f32_16x16x32_bf16 v[16:19], v[186:189], v[210:213], v[16:19]
	v_mfma_f32_16x16x32_bf16 v[4:7], v[178:181], v[218:221], v[4:7]
	v_mfma_f32_16x16x32_bf16 v[0:3], v[186:189], v[218:221], v[0:3]
	s_barrier
	s_add_i32 s74, 0, 0x18000
	v_add_u32_e32 v161, s74, v150
	s_add_i32 s75, 0, 0x1c000
	ds_read_b128 v[152:155], v161
	ds_read_b128 v[156:159], v161 offset:1024
	ds_read_b128 v[166:169], v161 offset:2048
	ds_read_b128 v[170:173], v161 offset:3072
	v_add_u32_e32 v161, s75, v150
	ds_read_b128 v[174:177], v161
	ds_read_b128 v[178:181], v161 offset:1024
	ds_read_b128 v[182:185], v161 offset:2048
	ds_read_b128 v[186:189], v161 offset:3072
	s_add_u32 s50, s50, 0x80000
	s_addc_u32 s51, s51, 0
	s_mov_b32 m0, s60
	v_lshl_add_u64 v[228:229], s[50:51], 0, v[128:129]
	ds_read_b128 v[190:193], v151 offset:32768
	ds_read_b128 v[194:197], v151 offset:33792
	ds_read_b128 v[198:201], v151 offset:34816
	ds_read_b128 v[202:205], v151 offset:35840
	ds_read_b128 v[206:209], v151 offset:36864
	ds_read_b128 v[210:213], v151 offset:37888
	ds_read_b128 v[214:217], v151 offset:38912
	ds_read_b128 v[218:221], v151 offset:39936
	global_load_lds_dwordx4 v[228:229], off
	v_lshl_add_u64 v[228:229], s[50:51], 0, v[132:133]
	s_mov_b32 m0, s61
	s_nop 0
	global_load_lds_dwordx4 v[228:229], off
	s_waitcnt vmcnt(8)
	s_waitcnt lgkmcnt(0)
	s_barrier
	s_waitcnt lgkmcnt(0)
	v_mfma_f32_16x16x32_bf16 v[124:127], v[152:155], v[190:193], v[124:127]
	v_mfma_f32_16x16x32_bf16 v[120:123], v[166:169], v[190:193], v[120:123]
	v_mfma_f32_16x16x32_bf16 v[108:111], v[152:155], v[198:201], v[108:111]
	v_mfma_f32_16x16x32_bf16 v[104:107], v[166:169], v[198:201], v[104:107]
	v_mfma_f32_16x16x32_bf16 v[92:95], v[152:155], v[206:209], v[92:95]
	v_mfma_f32_16x16x32_bf16 v[88:91], v[166:169], v[206:209], v[88:91]
	v_mfma_f32_16x16x32_bf16 v[76:79], v[152:155], v[214:217], v[76:79]
	v_mfma_f32_16x16x32_bf16 v[72:75], v[166:169], v[214:217], v[72:75]
	v_mfma_f32_16x16x32_bf16 v[124:127], v[156:159], v[194:197], v[124:127]
	v_mfma_f32_16x16x32_bf16 v[120:123], v[170:173], v[194:197], v[120:123]
	v_mfma_f32_16x16x32_bf16 v[108:111], v[156:159], v[202:205], v[108:111]
	v_mfma_f32_16x16x32_bf16 v[104:107], v[170:173], v[202:205], v[104:107]
	v_mfma_f32_16x16x32_bf16 v[92:95], v[156:159], v[210:213], v[92:95]
	v_mfma_f32_16x16x32_bf16 v[88:91], v[170:173], v[210:213], v[88:91]
	v_mfma_f32_16x16x32_bf16 v[76:79], v[156:159], v[218:221], v[76:79]
	v_mfma_f32_16x16x32_bf16 v[72:75], v[170:173], v[218:221], v[72:75]
	v_mfma_f32_16x16x32_bf16 v[116:119], v[174:177], v[190:193], v[116:119]
	v_mfma_f32_16x16x32_bf16 v[112:115], v[182:185], v[190:193], v[112:115]
	v_mfma_f32_16x16x32_bf16 v[100:103], v[174:177], v[198:201], v[100:103]
	v_mfma_f32_16x16x32_bf16 v[96:99], v[182:185], v[198:201], v[96:99]
	v_mfma_f32_16x16x32_bf16 v[84:87], v[174:177], v[206:209], v[84:87]
	v_mfma_f32_16x16x32_bf16 v[80:83], v[182:185], v[206:209], v[80:83]
	v_mfma_f32_16x16x32_bf16 v[68:71], v[174:177], v[214:217], v[68:71]
	v_mfma_f32_16x16x32_bf16 v[64:67], v[182:185], v[214:217], v[64:67]
	v_mfma_f32_16x16x32_bf16 v[116:119], v[178:181], v[194:197], v[116:119]
	v_mfma_f32_16x16x32_bf16 v[112:115], v[186:189], v[194:197], v[112:115]
	v_mfma_f32_16x16x32_bf16 v[100:103], v[178:181], v[202:205], v[100:103]
	v_mfma_f32_16x16x32_bf16 v[96:99], v[186:189], v[202:205], v[96:99]
	v_mfma_f32_16x16x32_bf16 v[84:87], v[178:181], v[210:213], v[84:87]
	v_mfma_f32_16x16x32_bf16 v[80:83], v[186:189], v[210:213], v[80:83]
	v_mfma_f32_16x16x32_bf16 v[68:71], v[178:181], v[218:221], v[68:71]
	v_mfma_f32_16x16x32_bf16 v[64:67], v[186:189], v[218:221], v[64:67]
	s_barrier
; #define PG8_STAGE(bufoff, gbase, voff) do { _Pragma("unroll") for (int _i = 0; _i < 2; ++_i) \
;         __builtin_amdgcn_global_load_lds((const unsigned*)((const char*)(gbase) + (voff)[_i]), (LAS unsigned*)(lds + (bufoff) + ldsw + _i * 8192), 16, 0, 0); } while (0)
; #define PG8_LDA(dst, b, h) do { _Pragma("unroll") for (int m = 0; m < 4; ++m) _Pragma("unroll") for (int k = 0; k < 2; ++k) dst[m][k] = *(const LAS bf16x8*)(lds + PG8_SA(b, h) + aoff + m * 2048 + k * 1024); } while (0)
; #define PG8_LDB(dst, b, h) do { _Pragma("unroll") for (int n = 0; n < 2; ++n) _Pragma("unroll") for (int k = 0; k < 2; ++k) dst[n][k] = *(const LAS bf16x8*)(lds + PG8_SB(b, h) + boff + n * 2048 + k * 1024); } while (0)
; #define PG8_MMA(ai, bj, At, Bt) do { __builtin_amdgcn_s_setprio(1); _Pragma("unroll") for (int m = 0; m < 4; ++m) _Pragma("unroll") for (int n = 0; n < 2; ++n) _Pragma("unroll") for (int k = 0; k < 2; ++k) \
;         acc[ai][bj][m][n] = __builtin_amdgcn_mfma_f32_16x16x32_bf16(Bt[n][k], At[m][k], acc[ai][bj][m][n], 0, 0, 0); __builtin_amdgcn_s_setprio(0); } while (0)
; #define PG8_WAIT_V(n) asm volatile("s_waitcnt vmcnt(" #n ")" ::: "memory")
; #define PG8_WAIT_L(n) asm volatile("s_waitcnt lgkmcnt(" #n ")" ::: "memory")
; #define PG8_BAR __builtin_amdgcn_s_barrier()
; #define PG8_SCHED __builtin_amdgcn_sched_barrier(0)
; template <class Epi, bool ALIGN_EPI = false, bool SP2 = true>
; __device__ __forceinline__ void gemm_phase(LAS unsigned char* lds, const Gemm g, const StaticOrder& S, const Epi& E) {
;     ...
;             PG8_LDB(B0, 1, 0); PG8_LDB(B1, 1, 1); PG8_SCHED; PG8_LDA(At, 1, 0); PG8_STAGE(PG8_SA(0, 1), a2 + hstep, voffA);
;             PG8_WAIT_V(8); PG8_WAIT_L(0); PG8_BAR; PG8_MMA(0, 0, At, B0); PG8_MMA(0, 1, At, B1); PG8_BAR; PG8_SCHED;
;             PG8_LDA(At, 1, 1); PG8_STAGE(PG8_SB(1, 0), b3, voffB); PG8_STAGE(PG8_SB(1, 1), b3 + hstep, voffB); PG8_STAGE(PG8_SA(1, 0), a3, voffA);
;             PG8_WAIT_V(8); PG8_WAIT_L(0); PG8_BAR; PG8_MMA(1, 0, At, B0); PG8_MMA(1, 1, At, B1); PG8_BAR; PG8_SCHED;
;     ...
; #pragma unroll
;         for (int a = 0; a < 2; ++a)
; #pragma unroll
;             for (int b = 0; b < 2; ++b)
; #pragma unroll
;                 for (int m = 0; m < 4; ++m)
; #pragma unroll
;                     for (int n = 0; n < 2; ++n) acc[a][b][m][n] = (f32x4){0.f, 0.f, 0.f, 0.f};
;         cur = nxt; cA = nA; cB = nB; ++ui;
	s_add_i32 s50, s74, s57
	v_lshl_add_u64 v[162:163], v[162:163], 0, s[16:17]
	s_mov_b32 m0, s50
	ds_read_b128 v[190:193], v151 offset:49152
	ds_read_b128 v[194:197], v151 offset:50176
	ds_read_b128 v[198:201], v151 offset:51200
	ds_read_b128 v[202:205], v151 offset:52224
	ds_read_b128 v[206:209], v151 offset:53248
	ds_read_b128 v[210:213], v151 offset:54272
	ds_read_b128 v[214:217], v151 offset:55296
	ds_read_b128 v[218:221], v151 offset:56320
	global_load_lds_dwordx4 v[162:163], off
	s_add_i32 m0, s50, 0x2000
	s_add_u32 s44, s44, 0x80080
	v_lshl_add_u64 v[162:163], v[222:223], 0, s[16:17]
	s_addc_u32 s45, s45, 0
	s_add_i32 s50, s75, s57
	global_load_lds_dwordx4 v[162:163], off
	v_lshl_add_u64 v[162:163], s[44:45], 0, v[130:131]
	s_mov_b32 m0, s50
	s_nop 0
	global_load_lds_dwordx4 v[162:163], off
	v_lshl_add_u64 v[162:163], s[44:45], 0, v[134:135]
	s_add_i32 m0, s50, 0x2000
	s_nop 0
	global_load_lds_dwordx4 v[162:163], off
	v_lshl_add_u64 v[162:163], v[224:225], 0, s[16:17]
	s_mov_b32 m0, s63
	s_nop 0
	global_load_lds_dwordx4 v[162:163], off
	v_lshl_add_u64 v[162:163], v[226:227], 0, s[16:17]
	s_mov_b32 m0, s64
	s_nop 0
	global_load_lds_dwordx4 v[162:163], off
	s_waitcnt vmcnt(8)
	s_waitcnt lgkmcnt(0)
	s_barrier
	s_waitcnt lgkmcnt(0)
	v_mfma_f32_16x16x32_bf16 v[60:63], v[152:155], v[190:193], v[60:63]
	v_mfma_f32_16x16x32_bf16 v[56:59], v[166:169], v[190:193], v[56:59]
	v_mfma_f32_16x16x32_bf16 v[44:47], v[152:155], v[198:201], v[44:47]
	v_mfma_f32_16x16x32_bf16 v[40:43], v[166:169], v[198:201], v[40:43]
	v_mfma_f32_16x16x32_bf16 v[28:31], v[152:155], v[206:209], v[28:31]
	v_mfma_f32_16x16x32_bf16 v[24:27], v[166:169], v[206:209], v[24:27]
	v_mfma_f32_16x16x32_bf16 v[12:15], v[152:155], v[214:217], v[12:15]
	v_mfma_f32_16x16x32_bf16 v[8:11], v[166:169], v[214:217], v[8:11]
	v_mfma_f32_16x16x32_bf16 v[60:63], v[156:159], v[194:197], v[60:63]
	v_mfma_f32_16x16x32_bf16 v[56:59], v[170:173], v[194:197], v[56:59]
	v_mfma_f32_16x16x32_bf16 v[44:47], v[156:159], v[202:205], v[44:47]
	v_mfma_f32_16x16x32_bf16 v[40:43], v[170:173], v[202:205], v[40:43]
	v_mfma_f32_16x16x32_bf16 v[28:31], v[156:159], v[210:213], v[28:31]
	v_mfma_f32_16x16x32_bf16 v[24:27], v[170:173], v[210:213], v[24:27]
	v_mfma_f32_16x16x32_bf16 v[12:15], v[156:159], v[218:221], v[12:15]
	v_mfma_f32_16x16x32_bf16 v[8:11], v[170:173], v[218:221], v[8:11]
	v_mfma_f32_16x16x32_bf16 v[52:55], v[174:177], v[190:193], v[52:55]
	v_mfma_f32_16x16x32_bf16 v[48:51], v[182:185], v[190:193], v[48:51]
	v_mfma_f32_16x16x32_bf16 v[36:39], v[174:177], v[198:201], v[36:39]
	v_mfma_f32_16x16x32_bf16 v[32:35], v[182:185], v[198:201], v[32:35]
	v_mfma_f32_16x16x32_bf16 v[20:23], v[174:177], v[206:209], v[20:23]
	v_mfma_f32_16x16x32_bf16 v[16:19], v[182:185], v[206:209], v[16:19]
	v_mfma_f32_16x16x32_bf16 v[4:7], v[174:177], v[214:217], v[4:7]
	v_mfma_f32_16x16x32_bf16 v[0:3], v[182:185], v[214:217], v[0:3]
	v_mfma_f32_16x16x32_bf16 v[52:55], v[178:181], v[194:197], v[52:55]
	v_mfma_f32_16x16x32_bf16 v[48:51], v[186:189], v[194:197], v[48:51]
	v_mfma_f32_16x16x32_bf16 v[36:39], v[178:181], v[202:205], v[36:39]
	v_mfma_f32_16x16x32_bf16 v[32:35], v[186:189], v[202:205], v[32:35]
	v_mfma_f32_16x16x32_bf16 v[20:23], v[178:181], v[210:213], v[20:23]
	v_mfma_f32_16x16x32_bf16 v[16:19], v[186:189], v[210:213], v[16:19]
	v_mfma_f32_16x16x32_bf16 v[4:7], v[178:181], v[218:221], v[4:7]
	v_mfma_f32_16x16x32_bf16 v[0:3], v[186:189], v[218:221], v[0:3]
	s_barrier
	s_add_i32 s73, s73, 2
	s_add_u32 s36, s36, 0x100
	s_addc_u32 s37, s37, 0
	s_cmp_gt_u32 s73, 29
	s_cbranch_scc0 .LBB0_746
	s_add_u32 s36, s69, 0xffffff00
	s_addc_u32 s37, s70, -1
	s_andn2_b64 vcc, exec, s[6:7]
	s_cbranch_vccnz .LBB0_749
	v_mov_b32_e32 v0, 0
	s_mov_b32 s14, s18
	s_mov_b32 s10, s26
	s_mov_b64 s[0:1], s[30:31]
	s_mov_b32 s65, s68
	v_mov_b32_e32 v1, v0
	v_mov_b32_e32 v2, v0
	v_mov_b32_e32 v3, v0
	v_mov_b32_e32 v4, v0
	v_mov_b32_e32 v5, v0
	v_mov_b32_e32 v6, v0
	v_mov_b32_e32 v7, v0
	v_mov_b32_e32 v16, v0
	v_mov_b32_e32 v17, v0
	v_mov_b32_e32 v18, v0
	v_mov_b32_e32 v19, v0
	v_mov_b32_e32 v20, v0
	v_mov_b32_e32 v21, v0
	v_mov_b32_e32 v22, v0
	v_mov_b32_e32 v23, v0
	v_mov_b32_e32 v32, v0
	v_mov_b32_e32 v33, v0
	v_mov_b32_e32 v34, v0
	v_mov_b32_e32 v35, v0
	v_mov_b32_e32 v36, v0
	v_mov_b32_e32 v37, v0
	v_mov_b32_e32 v38, v0
	v_mov_b32_e32 v39, v0
	v_mov_b32_e32 v48, v0
	v_mov_b32_e32 v49, v0
	v_mov_b32_e32 v50, v0
	v_mov_b32_e32 v51, v0
	v_mov_b32_e32 v52, v0
	v_mov_b32_e32 v53, v0
	v_mov_b32_e32 v54, v0
	v_mov_b32_e32 v55, v0
	v_mov_b32_e32 v8, v0
	v_mov_b32_e32 v9, v0
	v_mov_b32_e32 v10, v0
	v_mov_b32_e32 v11, v0
	v_mov_b32_e32 v12, v0
	v_mov_b32_e32 v13, v0
	v_mov_b32_e32 v14, v0
	v_mov_b32_e32 v15, v0
	v_mov_b32_e32 v24, v0
	v_mov_b32_e32 v25, v0
	v_mov_b32_e32 v26, v0
	v_mov_b32_e32 v27, v0
	v_mov_b32_e32 v28, v0
	v_mov_b32_e32 v29, v0
	v_mov_b32_e32 v30, v0
	v_mov_b32_e32 v31, v0
	v_mov_b32_e32 v40, v0
	v_mov_b32_e32 v41, v0
	v_mov_b32_e32 v42, v0
	v_mov_b32_e32 v43, v0
	v_mov_b32_e32 v44, v0
	v_mov_b32_e32 v45, v0
	v_mov_b32_e32 v46, v0
	v_mov_b32_e32 v47, v0
	v_mov_b32_e32 v56, v0
	v_mov_b32_e32 v57, v0
	v_mov_b32_e32 v58, v0
	v_mov_b32_e32 v59, v0
	v_mov_b32_e32 v60, v0
	v_mov_b32_e32 v61, v0
	v_mov_b32_e32 v62, v0
	v_mov_b32_e32 v63, v0
	v_mov_b32_e32 v64, v0
	v_mov_b32_e32 v65, v0
	v_mov_b32_e32 v66, v0
	v_mov_b32_e32 v67, v0
	v_mov_b32_e32 v68, v0
	v_mov_b32_e32 v69, v0
	v_mov_b32_e32 v70, v0
	v_mov_b32_e32 v71, v0
	v_mov_b32_e32 v80, v0
	v_mov_b32_e32 v81, v0
	v_mov_b32_e32 v82, v0
	v_mov_b32_e32 v83, v0
	v_mov_b32_e32 v84, v0
	v_mov_b32_e32 v85, v0
	v_mov_b32_e32 v86, v0
	v_mov_b32_e32 v87, v0
	v_mov_b32_e32 v96, v0
	v_mov_b32_e32 v97, v0
	v_mov_b32_e32 v98, v0
	v_mov_b32_e32 v99, v0
	v_mov_b32_e32 v100, v0
	v_mov_b32_e32 v101, v0
	v_mov_b32_e32 v102, v0
	v_mov_b32_e32 v103, v0
	v_mov_b32_e32 v112, v0
	v_mov_b32_e32 v113, v0
	v_mov_b32_e32 v114, v0
	v_mov_b32_e32 v115, v0
	v_mov_b32_e32 v116, v0
	v_mov_b32_e32 v117, v0
	v_mov_b32_e32 v118, v0
	v_mov_b32_e32 v119, v0
	v_mov_b32_e32 v72, v0
	v_mov_b32_e32 v73, v0
	v_mov_b32_e32 v74, v0
	v_mov_b32_e32 v75, v0
	v_mov_b32_e32 v76, v0
	v_mov_b32_e32 v77, v0
	v_mov_b32_e32 v78, v0
	v_mov_b32_e32 v79, v0
	v_mov_b32_e32 v88, v0
	v_mov_b32_e32 v89, v0
	v_mov_b32_e32 v90, v0
	v_mov_b32_e32 v91, v0
	v_mov_b32_e32 v92, v0
	v_mov_b32_e32 v93, v0
	v_mov_b32_e32 v94, v0
	v_mov_b32_e32 v95, v0
	v_mov_b32_e32 v104, v0
	v_mov_b32_e32 v105, v0
	v_mov_b32_e32 v106, v0
	v_mov_b32_e32 v107, v0
	v_mov_b32_e32 v108, v0
	v_mov_b32_e32 v109, v0
	v_mov_b32_e32 v110, v0
	v_mov_b32_e32 v111, v0
	v_mov_b32_e32 v120, v0
	v_mov_b32_e32 v121, v0
	v_mov_b32_e32 v122, v0
	v_mov_b32_e32 v123, v0
	v_mov_b32_e32 v124, v0
	v_mov_b32_e32 v125, v0
	v_mov_b32_e32 v126, v0
	v_mov_b32_e32 v127, v0
	s_andn2_b64 vcc, exec, s[4:5]
	s_cbranch_vccnz .LBB0_750
	s_branch .LBB0_751

; __device__ __forceinline__ unsigned xb_add(unsigned* p, unsigned v) { return __hip_atomic_fetch_add(p, v, __ATOMIC_RELAXED, __HIP_MEMORY_SCOPE_AGENT); }
; __device__ __forceinline__ void xcd_barrier(const XcdBarrier& b) {
;     asm volatile("s_waitcnt vmcnt(0)" ::: "memory");
;     __syncthreads();
;     if (threadIdx.x == 0) {
;         unsigned* bar = b.bar;
;         __builtin_amdgcn_s_waitcnt(0);
;         unsigned nloc = b.st[0], nx = b.st[1];
;         if (nloc == 0u) { xcd_barrier_complete(bar, b.x, nloc, nx); b.st[0] = nloc; b.st[1] = nx; }
;         const unsigned old = xb_add(&bar[XB_XSUB(b.x)], 1u);
;         const unsigned gen = old / nloc;
;         if (old + 1u == (gen + 1u) * nloc) {
;             __builtin_amdgcn_fence(__ATOMIC_RELEASE, "agent");
;             asm volatile("s_waitcnt vmcnt(0)" ::: "memory");
;             const unsigned og = xb_add(&bar[XB_TOP], 1u);
.LBB0_787:
	s_cmp_gt_u32 s43, 9
	s_setprio 0
	s_cselect_b64 s[0:1], -1, 0
	s_and_b64 s[0:1], s[8:9], s[0:1]
	s_andn2_b64 vcc, exec, s[0:1]
	s_cbranch_vccnz .LBB0_837
	s_waitcnt vmcnt(0)
	s_waitcnt vmcnt(0) lgkmcnt(0)
	s_barrier
	s_and_saveexec_b64 s[0:1], s[12:13]
	s_cbranch_execz .LBB0_836
	s_and_b32 s98, s2, 7
	s_lshl_b32 s98, s98, 2
	s_bfe_u32 s99, s2, 0x20003
	s_or_b32 s98, s98, s99
	s_lshl_b32 s98, s98, 6
	s_add_i32 s98, s98, 0xa400
	v_mov_b32_e32 v250, s98
	v_mov_b32_e32 v252, 1
	v_mov_b32_e32 v253, 0x2000c
	ds_read_b32 v254, v253
	s_waitcnt lgkmcnt(0)
	v_readfirstlane_b32 s99, v254
	s_cmp_eq_u32 s99, 1
	s_cbranch_scc1 .Lpb8_fast
	buffer_wbl2 sc1
	s_waitcnt vmcnt(0)

;     __device__ bool next(int i, Unit& u) const {
;         const long L = (long)i * G + c; if (L >= nwg) return false;
;         int wgid = (int)L; { const int q = nwg / NXCD, r = nwg % NXCD, xcd = wgid % NXCD, off = wgid / NXCD; wgid = (xcd < r ? xcd * (q + 1) : r * (q + 1) + (xcd - r) * q) + off; }
;         const int nig = WGM * nN, gid = wgid / nig, fm = gid * WGM, gsz = (nM - fm) < WGM ? (nM - fm) : WGM;
;         u.pm = fm + ((wgid % nig) % gsz); u.pn = (wgid % nig) / gsz; return true;
; __global__ void __launch_bounds__(NTHREADS, 2) mk_fwd(Params P) {
;     ...
;     if (IN(10)) {
;         pg8::Gemm g{X3B, WG1, MTOK, 2048, 2048, 1 << 30, 0}; pg8::StaticOrder S; S.init(MTOK, 2048, G, bid);
.LBB0_837:
	s_cmp_lt_i32 s42, 11
	s_cselect_b64 s[0:1], -1, 0
	s_cmp_gt_i32 s43, 10
	s_setprio 0
	s_cselect_b64 s[4:5], -1, 0
	s_and_b64 s[0:1], s[0:1], s[4:5]
	s_andn2_b64 vcc, exec, s[0:1]
	s_cbranch_vccnz .LBB0_862
	s_cmpk_gt_i32 s2, 0xff
	v_readfirstlane_b32 s10, v164
	s_cbranch_scc1 .LBB0_862
	s_ashr_i32 s3, s2, 31
	s_lshr_b32 s0, s3, 29
	s_add_i32 s6, s2, s0
	s_and_b32 s0, s6, -8
	s_sub_i32 s5, s2, s0
	s_cmp_gt_i32 s5, -1
	s_cbranch_scc0 .LBB0_841
	s_lshl_b32 s4, s5, 5
	s_ashr_i32 s0, s6, 3
	s_cbranch_execz .LBB0_842
	s_branch .LBB0_843

; #define PG8_STAGE(bufoff, gbase, voff) do { _Pragma("unroll") for (int _i = 0; _i < 2; ++_i) \
;         __builtin_amdgcn_global_load_lds((const unsigned*)((const char*)(gbase) + (voff)[_i]), (LAS unsigned*)(lds + (bufoff) + ldsw + _i * 8192), 16, 0, 0); } while (0)
; #define PG8_WAIT_V(n) asm volatile("s_waitcnt vmcnt(" #n ")" ::: "memory")
; #define PG8_BAR __builtin_amdgcn_s_barrier()
; template <class Epi, bool ALIGN_EPI = false, bool SP2 = true>
; __device__ __forceinline__ void gemm_phase(LAS unsigned char* lds, const Gemm g, const StaticOrder& S, const Epi& E) {
;     ...
;     const char* cA = (const char*)g.A + (size_t)cur.pm * tstep; const char* cB = (const char*)g.Bt + (size_t)(cur.pn + (cur.pm >= g.bsplit ? g.badd : 0)) * tstep;
;     if constexpr (SP2) {
;         PG8_STAGE(PG8_SB(0, 0), cB, voffB); PG8_STAGE(PG8_SB(0, 1), cB + hstep, voffB); PG8_STAGE(PG8_SA(0, 0), cA, voffA); PG8_STAGE(PG8_SA(0, 1), cA + hstep, voffA);
;         if (wr == 1) PG8_BAR;
;         PG8_WAIT_V(2); PG8_BAR;
;         PG8_STAGE(PG8_SB(1, 0), cB + kstep, voffB); PG8_STAGE(PG8_SA(1, 0), cA + kstep, voffA); PG8_STAGE(PG8_SB(1, 1), cB + hstep + kstep, voffB);
;         PG8_WAIT_V(6); PG8_BAR;
.LBB0_843:
	s_waitcnt vmcnt(0)
	v_lshrrev_b32_e32 v2, 1, v164
	v_and_b32_e32 v11, 24, v2
	v_lshrrev_b32_e32 v2, 5, v164
	v_and_b32_e32 v2, 4, v2
	v_bfe_u32 v3, v164, 2, 2
	v_lshlrev_b32_e32 v0, 4, v164
	v_and_b32_e32 v1, 32, v164
	v_bfe_u32 v10, v164, 2, 4
	v_or3_b32 v2, v2, v3, v11
	v_lshrrev_b32_e32 v3, 3, v164
	s_movk_i32 s5, 0x70
	s_add_i32 s0, s4, s0
	v_bitop3_b32 v8, v0, v1, 48 bitop3:0x6c
	v_and_b32_e32 v9, 64, v164
	v_and_or_b32 v4, v3, s5, v10
	s_movk_i32 s5, 0x60
	v_add_u32_e32 v12, 0x2000, v0
	s_ashr_i32 s4, s0, 31
	v_or_b32_e32 v1, v8, v9
	v_and_or_b32 v3, v3, s5, v2
	v_lshrrev_b32_e32 v0, 7, v12
	s_movk_i32 s5, 0xf0
	s_lshr_b32 s4, s4, 27
	v_lshl_or_b32 v168, v3, 12, v1
	v_and_or_b32 v3, v0, s5, v10
	s_movk_i32 s5, 0xe0
	s_add_i32 s4, s0, s4
	v_and_or_b32 v0, v0, s5, v2
	s_ashr_i32 s5, s4, 5
	s_and_b32 s4, s4, 0xffe0
	s_sub_i32 s4, s0, s4
	s_bfe_i32 s0, s4, 0x80000
	s_bfe_u32 s0, s0, 0x2000d
	s_add_i32 s7, s4, s0
	s_bfe_i32 s0, s7, 0x80000
	s_and_b32 s7, s7, 0xfc
	s_sub_i32 s4, s4, s7
	s_lshl_b32 s5, s5, 2
	s_sext_i32_i16 s0, s0
	s_sext_i32_i8 s4, s4
	s_lshr_b32 s1, s10, 8
	s_lshr_b32 s0, s0, 2
	s_add_i32 s42, s5, s4
	s_lshr_b32 s6, s10, 6
	s_ashr_i32 s43, s42, 31
	s_bfe_i64 s[8:9], s[0:1], 0x100000
	s_lshl_b32 s33, s6, 10
	s_lshl_b64 s[4:5], s[42:43], 20
	s_lshl_b64 s[8:9], s[8:9], 20
	s_add_u32 s44, s22, s8
	s_addc_u32 s45, s23, s9
	s_add_i32 s35, s33, 0
	s_add_i32 m0, s35, 0x10000
	v_lshl_or_b32 v172, v0, 12, v1
	global_load_lds_dwordx4 v168, s[44:45]
	s_add_i32 m0, s35, 0x12000
	s_add_u32 s8, s44, 0x80000
	global_load_lds_dwordx4 v172, s[44:45]
	s_addc_u32 s9, s45, 0
	s_add_i32 m0, s35, 0x14000
	v_lshl_or_b32 v166, v4, 12, v1
	global_load_lds_dwordx4 v168, s[8:9]
	s_add_i32 m0, s35, 0x16000
	s_add_u32 s46, s52, s4
	s_addc_u32 s47, s53, s5
	s_add_i32 s43, s35, 0x2000
	global_load_lds_dwordx4 v172, s[8:9]
	s_mov_b32 m0, s35
	s_add_u32 s4, s46, 0x80000
	v_lshl_or_b32 v170, v3, 12, v1
	global_load_lds_dwordx4 v166, s[46:47]
	s_mov_b32 m0, s43
	s_addc_u32 s5, s47, 0
	s_add_i32 s48, s35, 0x4000
	global_load_lds_dwordx4 v170, s[46:47]
	s_mov_b32 m0, s48
	s_add_i32 s49, s35, 0x6000
	global_load_lds_dwordx4 v166, s[4:5]
	s_mov_b32 m0, s49
	v_mov_b32_e32 v169, 0
	global_load_lds_dwordx4 v170, s[4:5]
	v_mov_b32_e32 v173, v169
	v_mov_b32_e32 v167, v169
	v_mov_b32_e32 v171, v169
	s_cmp_eq_u32 s1, 1
	s_mov_b32 s50, 0
	s_mov_b32 s51, 0x10000
	v_lshl_add_u64 v[6:7], s[44:45], 0, v[168:169]
	v_lshl_add_u64 v[4:5], s[44:45], 0, v[172:173]
	v_lshl_add_u64 v[0:1], s[46:47], 0, v[166:167]
	s_cselect_b64 s[4:5], -1, 0
	s_cmp_lg_u32 s1, 1
	v_lshl_add_u64 v[2:3], s[46:47], 0, v[170:171]
	s_cbranch_scc1 .LBB0_845
	s_barrier
	s_setprio 1

; #define PG8_STAGE(bufoff, gbase, voff) do { _Pragma("unroll") for (int _i = 0; _i < 2; ++_i) \
;         __builtin_amdgcn_global_load_lds((const unsigned*)((const char*)(gbase) + (voff)[_i]), (LAS unsigned*)(lds + (bufoff) + ldsw + _i * 8192), 16, 0, 0); } while (0)
; #define PG8_LDA(dst, b, h) do { _Pragma("unroll") for (int m = 0; m < 4; ++m) _Pragma("unroll") for (int k = 0; k < 2; ++k) dst[m][k] = *(const LAS bf16x8*)(lds + PG8_SA(b, h) + aoff + m * 2048 + k * 1024); } while (0)
; #define PG8_LDB(dst, b, h) do { _Pragma("unroll") for (int n = 0; n < 2; ++n) _Pragma("unroll") for (int k = 0; k < 2; ++k) dst[n][k] = *(const LAS bf16x8*)(lds + PG8_SB(b, h) + boff + n * 2048 + k * 1024); } while (0)
; #define PG8_WAIT_V(n) asm volatile("s_waitcnt vmcnt(" #n ")" ::: "memory")
; #define PG8_WAIT_L(n) asm volatile("s_waitcnt lgkmcnt(" #n ")" ::: "memory")
; #define PG8_BAR __builtin_amdgcn_s_barrier()
; #define PG8_SCHED __builtin_amdgcn_sched_barrier(0)
; template <class Epi, bool ALIGN_EPI = false, bool SP2 = true>
; __device__ __forceinline__ void gemm_phase(LAS unsigned char* lds, const Gemm g, const StaticOrder& S, const Epi& E) {
;     ...
;         const bool has_next = S.next(ui + 1, nxt);
;         const char* nA = has_next ? (const char*)g.A + (size_t)nxt.pm * tstep : cA; const char* nB = has_next ? (const char*)g.Bt + (size_t)(nxt.pn + (nxt.pm >= g.bsplit ? g.badd : 0)) * tstep : cB;
;         for (int t = 0; t < nt; t += 2) {
;             const bool last = (t == nt - 2);
;             const char* a1 = cA + (size_t)(t + 1) * kstep;
;             const char* a2 = last ? nA : cA + (size_t)(t + 2) * kstep; const char* b2 = last ? nB : cB + (size_t)(t + 2) * kstep;
;             const char* a3 = a2 + kstep; const char* b3 = b2 + kstep;
;             if constexpr (SP2) {
;             PG8_LDB(B0, 0, 0); PG8_LDB(B1, 0, 1); PG8_SCHED; PG8_LDA(At, 0, 0); PG8_STAGE(PG8_SA(1, 1), a1 + hstep, voffA);
;             PG8_WAIT_V(8); PG8_WAIT_L(0); PG8_BAR; PG8_MMA(0, 0, At, B0); PG8_MMA(0, 1, At, B1); PG8_BAR; PG8_SCHED;
;             PG8_LDA(At, 0, 1); PG8_STAGE(PG8_SB(0, 0), b2, voffB); PG8_STAGE(PG8_SB(0, 1), b2 + hstep, voffB); PG8_STAGE(PG8_SA(0, 0), a2, voffA);
;             PG8_WAIT_V(8); PG8_WAIT_L(0); PG8_BAR; PG8_MMA(1, 0, At, B0); PG8_MMA(1, 1, At, B1); PG8_BAR; PG8_SCHED;
.LBB0_855:
	ds_read_b128 v[128:131], v187
	ds_read_b128 v[132:135], v187 offset:1024
	ds_read_b128 v[136:139], v187 offset:2048
	ds_read_b128 v[140:143], v187 offset:3072
	ds_read_b128 v[144:147], v188
	ds_read_b128 v[148:151], v188 offset:1024
	s_waitcnt lgkmcnt(0)
	ds_read_b128 v[152:155], v188 offset:2048
	ds_read_b128 v[156:159], v188 offset:3072
	s_add_u32 s44, s40, 0xfff80080
	s_addc_u32 s45, s41, -1
	s_cmp_eq_u32 s68, 28
	s_cselect_b32 s47, s29, s45
	s_cselect_b32 s46, s64, s44
	s_cselect_b32 s45, s27, s67
	s_cselect_b32 s44, s65, s66
	v_lshl_add_u64 v[214:215], s[40:41], 0, v[164:165]
	s_add_i32 m0, s35, 0xc000
	ds_read_b128 v[160:163], v189
	ds_read_b128 v[180:183], v189 offset:1024
	ds_read_b128 v[190:193], v189 offset:2048
	ds_read_b128 v[194:197], v189 offset:3072
	ds_read_b128 v[198:201], v189 offset:4096
	ds_read_b128 v[202:205], v189 offset:5120
	ds_read_b128 v[206:209], v189 offset:6144
	ds_read_b128 v[210:213], v189 offset:7168
	global_load_lds_dwordx4 v[214:215], off
	v_lshl_add_u64 v[214:215], s[40:41], 0, v[174:175]
	s_add_i32 m0, s35, 0xe000
	s_nop 0
	global_load_lds_dwordx4 v[214:215], off
	s_waitcnt vmcnt(8)
	s_waitcnt lgkmcnt(0)
	s_barrier
	s_waitcnt lgkmcnt(0)
	v_mfma_f32_16x16x32_bf16 v[124:127], v[128:131], v[160:163], v[124:127]
	v_mfma_f32_16x16x32_bf16 v[120:123], v[136:139], v[160:163], v[120:123]
	v_mfma_f32_16x16x32_bf16 v[108:111], v[128:131], v[190:193], v[108:111]
	v_mfma_f32_16x16x32_bf16 v[104:107], v[136:139], v[190:193], v[104:107]
	v_mfma_f32_16x16x32_bf16 v[92:95], v[128:131], v[198:201], v[92:95]
	v_mfma_f32_16x16x32_bf16 v[88:91], v[136:139], v[198:201], v[88:91]
	v_mfma_f32_16x16x32_bf16 v[76:79], v[128:131], v[206:209], v[76:79]
	v_mfma_f32_16x16x32_bf16 v[72:75], v[136:139], v[206:209], v[72:75]
	v_mfma_f32_16x16x32_bf16 v[124:127], v[132:135], v[180:183], v[124:127]
	v_mfma_f32_16x16x32_bf16 v[120:123], v[140:143], v[180:183], v[120:123]
	v_mfma_f32_16x16x32_bf16 v[108:111], v[132:135], v[194:197], v[108:111]
	v_mfma_f32_16x16x32_bf16 v[104:107], v[140:143], v[194:197], v[104:107]
	v_mfma_f32_16x16x32_bf16 v[92:95], v[132:135], v[202:205], v[92:95]
	v_mfma_f32_16x16x32_bf16 v[88:91], v[140:143], v[202:205], v[88:91]
	v_mfma_f32_16x16x32_bf16 v[76:79], v[132:135], v[210:213], v[76:79]
	v_mfma_f32_16x16x32_bf16 v[72:75], v[140:143], v[210:213], v[72:75]
	v_mfma_f32_16x16x32_bf16 v[116:119], v[144:147], v[160:163], v[116:119]
	v_mfma_f32_16x16x32_bf16 v[112:115], v[152:155], v[160:163], v[112:115]
	v_mfma_f32_16x16x32_bf16 v[100:103], v[144:147], v[190:193], v[100:103]
	v_mfma_f32_16x16x32_bf16 v[96:99], v[152:155], v[190:193], v[96:99]
	v_mfma_f32_16x16x32_bf16 v[84:87], v[144:147], v[198:201], v[84:87]
	v_mfma_f32_16x16x32_bf16 v[80:83], v[152:155], v[198:201], v[80:83]
	v_mfma_f32_16x16x32_bf16 v[68:71], v[144:147], v[206:209], v[68:71]
	v_mfma_f32_16x16x32_bf16 v[64:67], v[152:155], v[206:209], v[64:67]
	v_mfma_f32_16x16x32_bf16 v[116:119], v[148:151], v[180:183], v[116:119]
	v_mfma_f32_16x16x32_bf16 v[112:115], v[156:159], v[180:183], v[112:115]
	v_mfma_f32_16x16x32_bf16 v[100:103], v[148:151], v[194:197], v[100:103]
	v_mfma_f32_16x16x32_bf16 v[96:99], v[156:159], v[194:197], v[96:99]
	v_mfma_f32_16x16x32_bf16 v[84:87], v[148:151], v[202:205], v[84:87]
	v_mfma_f32_16x16x32_bf16 v[80:83], v[156:159], v[202:205], v[80:83]
	v_mfma_f32_16x16x32_bf16 v[68:71], v[148:151], v[210:213], v[68:71]
	v_mfma_f32_16x16x32_bf16 v[64:67], v[156:159], v[210:213], v[64:67]
	s_barrier
	s_add_i32 s69, s57, s33
	v_lshl_add_u64 v[214:215], s[44:45], 0, v[168:169]
	s_mov_b32 m0, s69
	ds_read_b128 v[160:163], v189 offset:16384
	ds_read_b128 v[180:183], v189 offset:17408
	ds_read_b128 v[190:193], v189 offset:18432
	ds_read_b128 v[194:197], v189 offset:19456
	ds_read_b128 v[198:201], v189 offset:20480
	ds_read_b128 v[202:205], v189 offset:21504
	ds_read_b128 v[206:209], v189 offset:22528
	ds_read_b128 v[210:213], v189 offset:23552
	global_load_lds_dwordx4 v[214:215], off
	s_add_i32 m0, s69, 0x2000
	s_add_u32 s70, s44, 0x80000
	v_lshl_add_u64 v[216:217], s[44:45], 0, v[172:173]
	s_addc_u32 s71, s45, 0
	s_add_i32 s69, s58, s33
	global_load_lds_dwordx4 v[216:217], off
	v_lshl_add_u64 v[218:219], s[70:71], 0, v[168:169]
	s_mov_b32 m0, s69
	v_lshl_add_u64 v[220:221], s[46:47], 0, v[170:171]
	global_load_lds_dwordx4 v[218:219], off
	v_lshl_add_u64 v[218:219], s[70:71], 0, v[172:173]
	s_add_i32 m0, s69, 0x2000
	s_nop 0
	global_load_lds_dwordx4 v[218:219], off
	v_lshl_add_u64 v[218:219], s[46:47], 0, v[166:167]
	s_mov_b32 m0, s35
	s_nop 0
	global_load_lds_dwordx4 v[218:219], off
	s_mov_b32 m0, s43
	s_nop 0
	global_load_lds_dwordx4 v[220:221], off
	s_waitcnt vmcnt(8)
	s_waitcnt lgkmcnt(0)
	s_barrier
; #define PG8_STAGE(bufoff, gbase, voff) do { _Pragma("unroll") for (int _i = 0; _i < 2; ++_i) \
;         __builtin_amdgcn_global_load_lds((const unsigned*)((const char*)(gbase) + (voff)[_i]), (LAS unsigned*)(lds + (bufoff) + ldsw + _i * 8192), 16, 0, 0); } while (0)
; #define PG8_LDA(dst, b, h) do { _Pragma("unroll") for (int m = 0; m < 4; ++m) _Pragma("unroll") for (int k = 0; k < 2; ++k) dst[m][k] = *(const LAS bf16x8*)(lds + PG8_SA(b, h) + aoff + m * 2048 + k * 1024); } while (0)
; #define PG8_LDB(dst, b, h) do { _Pragma("unroll") for (int n = 0; n < 2; ++n) _Pragma("unroll") for (int k = 0; k < 2; ++k) dst[n][k] = *(const LAS bf16x8*)(lds + PG8_SB(b, h) + boff + n * 2048 + k * 1024); } while (0)
; #define PG8_MMA(ai, bj, At, Bt) do { __builtin_amdgcn_s_setprio(1); _Pragma("unroll") for (int m = 0; m < 4; ++m) _Pragma("unroll") for (int n = 0; n < 2; ++n) _Pragma("unroll") for (int k = 0; k < 2; ++k) \
;         acc[ai][bj][m][n] = __builtin_amdgcn_mfma_f32_16x16x32_bf16(Bt[n][k], At[m][k], acc[ai][bj][m][n], 0, 0, 0); __builtin_amdgcn_s_setprio(0); } while (0)
; #define PG8_WAIT_V(n) asm volatile("s_waitcnt vmcnt(" #n ")" ::: "memory")
; #define PG8_WAIT_L(n) asm volatile("s_waitcnt lgkmcnt(" #n ")" ::: "memory")
; #define PG8_BAR __builtin_amdgcn_s_barrier()
; #define PG8_SCHED __builtin_amdgcn_sched_barrier(0)
; template <class Epi, bool ALIGN_EPI = false, bool SP2 = true>
; __device__ __forceinline__ void gemm_phase(LAS unsigned char* lds, const Gemm g, const StaticOrder& S, const Epi& E) {
;     ...
;             PG8_WAIT_V(8); PG8_WAIT_L(0); PG8_BAR; PG8_MMA(1, 0, At, B0); PG8_MMA(1, 1, At, B1); PG8_BAR; PG8_SCHED;
;             PG8_LDB(B0, 1, 0); PG8_LDB(B1, 1, 1); PG8_SCHED; PG8_LDA(At, 1, 0); PG8_STAGE(PG8_SA(0, 1), a2 + hstep, voffA);
;             PG8_WAIT_V(8); PG8_WAIT_L(0); PG8_BAR; PG8_MMA(0, 0, At, B0); PG8_MMA(0, 1, At, B1); PG8_BAR; PG8_SCHED;
	s_waitcnt lgkmcnt(0)
	v_mfma_f32_16x16x32_bf16 v[60:63], v[128:131], v[160:163], v[60:63]
	v_mfma_f32_16x16x32_bf16 v[56:59], v[136:139], v[160:163], v[56:59]
	v_mfma_f32_16x16x32_bf16 v[44:47], v[128:131], v[190:193], v[44:47]
	v_mfma_f32_16x16x32_bf16 v[40:43], v[136:139], v[190:193], v[40:43]
	v_mfma_f32_16x16x32_bf16 v[28:31], v[128:131], v[198:201], v[28:31]
	v_mfma_f32_16x16x32_bf16 v[24:27], v[136:139], v[198:201], v[24:27]
	v_mfma_f32_16x16x32_bf16 v[12:15], v[128:131], v[206:209], v[12:15]
	v_mfma_f32_16x16x32_bf16 v[8:11], v[136:139], v[206:209], v[8:11]
	v_mfma_f32_16x16x32_bf16 v[60:63], v[132:135], v[180:183], v[60:63]
	v_mfma_f32_16x16x32_bf16 v[56:59], v[140:143], v[180:183], v[56:59]
	v_mfma_f32_16x16x32_bf16 v[44:47], v[132:135], v[194:197], v[44:47]
	v_mfma_f32_16x16x32_bf16 v[40:43], v[140:143], v[194:197], v[40:43]
	v_mfma_f32_16x16x32_bf16 v[28:31], v[132:135], v[202:205], v[28:31]
	v_mfma_f32_16x16x32_bf16 v[24:27], v[140:143], v[202:205], v[24:27]
	v_mfma_f32_16x16x32_bf16 v[12:15], v[132:135], v[210:213], v[12:15]
	v_mfma_f32_16x16x32_bf16 v[8:11], v[140:143], v[210:213], v[8:11]
	v_mfma_f32_16x16x32_bf16 v[52:55], v[144:147], v[160:163], v[52:55]
	v_mfma_f32_16x16x32_bf16 v[48:51], v[152:155], v[160:163], v[48:51]
	v_mfma_f32_16x16x32_bf16 v[36:39], v[144:147], v[190:193], v[36:39]
	v_mfma_f32_16x16x32_bf16 v[32:35], v[152:155], v[190:193], v[32:35]
	v_mfma_f32_16x16x32_bf16 v[20:23], v[144:147], v[198:201], v[20:23]
	v_mfma_f32_16x16x32_bf16 v[16:19], v[152:155], v[198:201], v[16:19]
	v_mfma_f32_16x16x32_bf16 v[4:7], v[144:147], v[206:209], v[4:7]
	v_mfma_f32_16x16x32_bf16 v[0:3], v[152:155], v[206:209], v[0:3]
	v_mfma_f32_16x16x32_bf16 v[52:55], v[148:151], v[180:183], v[52:55]
	v_mfma_f32_16x16x32_bf16 v[48:51], v[156:159], v[180:183], v[48:51]
	v_mfma_f32_16x16x32_bf16 v[36:39], v[148:151], v[194:197], v[36:39]
	v_mfma_f32_16x16x32_bf16 v[32:35], v[156:159], v[194:197], v[32:35]
	v_mfma_f32_16x16x32_bf16 v[20:23], v[148:151], v[202:205], v[20:23]
	v_mfma_f32_16x16x32_bf16 v[16:19], v[156:159], v[202:205], v[16:19]
	v_mfma_f32_16x16x32_bf16 v[4:7], v[148:151], v[210:213], v[4:7]
	v_mfma_f32_16x16x32_bf16 v[0:3], v[156:159], v[210:213], v[0:3]
	s_barrier
	s_add_i32 s69, 0, 0x18000
	s_add_i32 s70, 0, 0x1c000
	v_add_u32_e32 v140, s69, v185
	v_add_u32_e32 v156, s70, v185
	ds_read_b128 v[128:131], v140
	ds_read_b128 v[132:135], v140 offset:1024
	ds_read_b128 v[136:139], v140 offset:2048
	ds_read_b128 v[140:143], v140 offset:3072
	ds_read_b128 v[144:147], v156
	ds_read_b128 v[148:151], v156 offset:1024
	ds_read_b128 v[152:155], v156 offset:2048
	ds_read_b128 v[156:159], v156 offset:3072
	s_add_u32 s46, s46, 0x80000
	s_addc_u32 s47, s47, 0
	s_mov_b32 m0, s48
	v_lshl_add_u64 v[222:223], s[46:47], 0, v[166:167]
	ds_read_b128 v[160:163], v189 offset:32768
	ds_read_b128 v[180:183], v189 offset:33792
	ds_read_b128 v[190:193], v189 offset:34816
	ds_read_b128 v[194:197], v189 offset:35840
	ds_read_b128 v[198:201], v189 offset:36864
	ds_read_b128 v[202:205], v189 offset:37888
	ds_read_b128 v[206:209], v189 offset:38912
	ds_read_b128 v[210:213], v189 offset:39936
	global_load_lds_dwordx4 v[222:223], off
	v_lshl_add_u64 v[222:223], s[46:47], 0, v[170:171]
	s_mov_b32 m0, s49
	s_nop 0
	global_load_lds_dwordx4 v[222:223], off
	s_waitcnt vmcnt(8)
	s_waitcnt lgkmcnt(0)
	s_barrier
	s_waitcnt lgkmcnt(0)
	v_mfma_f32_16x16x32_bf16 v[124:127], v[128:131], v[160:163], v[124:127]
	v_mfma_f32_16x16x32_bf16 v[120:123], v[136:139], v[160:163], v[120:123]
	v_mfma_f32_16x16x32_bf16 v[108:111], v[128:131], v[190:193], v[108:111]
	v_mfma_f32_16x16x32_bf16 v[104:107], v[136:139], v[190:193], v[104:107]
	v_mfma_f32_16x16x32_bf16 v[92:95], v[128:131], v[198:201], v[92:95]
	v_mfma_f32_16x16x32_bf16 v[88:91], v[136:139], v[198:201], v[88:91]
	v_mfma_f32_16x16x32_bf16 v[76:79], v[128:131], v[206:209], v[76:79]
	v_mfma_f32_16x16x32_bf16 v[72:75], v[136:139], v[206:209], v[72:75]
	v_mfma_f32_16x16x32_bf16 v[124:127], v[132:135], v[180:183], v[124:127]
	v_mfma_f32_16x16x32_bf16 v[120:123], v[140:143], v[180:183], v[120:123]
	v_mfma_f32_16x16x32_bf16 v[108:111], v[132:135], v[194:197], v[108:111]
	v_mfma_f32_16x16x32_bf16 v[104:107], v[140:143], v[194:197], v[104:107]
	v_mfma_f32_16x16x32_bf16 v[92:95], v[132:135], v[202:205], v[92:95]
	v_mfma_f32_16x16x32_bf16 v[88:91], v[140:143], v[202:205], v[88:91]
	v_mfma_f32_16x16x32_bf16 v[76:79], v[132:135], v[210:213], v[76:79]
	v_mfma_f32_16x16x32_bf16 v[72:75], v[140:143], v[210:213], v[72:75]
	v_mfma_f32_16x16x32_bf16 v[116:119], v[144:147], v[160:163], v[116:119]
	v_mfma_f32_16x16x32_bf16 v[112:115], v[152:155], v[160:163], v[112:115]
	v_mfma_f32_16x16x32_bf16 v[100:103], v[144:147], v[190:193], v[100:103]
	v_mfma_f32_16x16x32_bf16 v[96:99], v[152:155], v[190:193], v[96:99]
	v_mfma_f32_16x16x32_bf16 v[84:87], v[144:147], v[198:201], v[84:87]
	v_mfma_f32_16x16x32_bf16 v[80:83], v[152:155], v[198:201], v[80:83]
	v_mfma_f32_16x16x32_bf16 v[68:71], v[144:147], v[206:209], v[68:71]
	v_mfma_f32_16x16x32_bf16 v[64:67], v[152:155], v[206:209], v[64:67]
	v_mfma_f32_16x16x32_bf16 v[116:119], v[148:151], v[180:183], v[116:119]
	v_mfma_f32_16x16x32_bf16 v[112:115], v[156:159], v[180:183], v[112:115]
	v_mfma_f32_16x16x32_bf16 v[100:103], v[148:151], v[194:197], v[100:103]
	v_mfma_f32_16x16x32_bf16 v[96:99], v[156:159], v[194:197], v[96:99]
	v_mfma_f32_16x16x32_bf16 v[84:87], v[148:151], v[202:205], v[84:87]
	v_mfma_f32_16x16x32_bf16 v[80:83], v[156:159], v[202:205], v[80:83]
	v_mfma_f32_16x16x32_bf16 v[68:71], v[148:151], v[210:213], v[68:71]
	v_mfma_f32_16x16x32_bf16 v[64:67], v[156:159], v[210:213], v[64:67]
	s_barrier
; #define PG8_STAGE(bufoff, gbase, voff) do { _Pragma("unroll") for (int _i = 0; _i < 2; ++_i) \
;         __builtin_amdgcn_global_load_lds((const unsigned*)((const char*)(gbase) + (voff)[_i]), (LAS unsigned*)(lds + (bufoff) + ldsw + _i * 8192), 16, 0, 0); } while (0)
; #define PG8_LDA(dst, b, h) do { _Pragma("unroll") for (int m = 0; m < 4; ++m) _Pragma("unroll") for (int k = 0; k < 2; ++k) dst[m][k] = *(const LAS bf16x8*)(lds + PG8_SA(b, h) + aoff + m * 2048 + k * 1024); } while (0)
; #define PG8_MMA(ai, bj, At, Bt) do { __builtin_amdgcn_s_setprio(1); _Pragma("unroll") for (int m = 0; m < 4; ++m) _Pragma("unroll") for (int n = 0; n < 2; ++n) _Pragma("unroll") for (int k = 0; k < 2; ++k) \
;         acc[ai][bj][m][n] = __builtin_amdgcn_mfma_f32_16x16x32_bf16(Bt[n][k], At[m][k], acc[ai][bj][m][n], 0, 0, 0); __builtin_amdgcn_s_setprio(0); } while (0)
; #define PG8_WAIT_V(n) asm volatile("s_waitcnt vmcnt(" #n ")" ::: "memory")
; #define PG8_WAIT_L(n) asm volatile("s_waitcnt lgkmcnt(" #n ")" ::: "memory")
; #define PG8_BAR __builtin_amdgcn_s_barrier()
; #define PG8_SCHED __builtin_amdgcn_sched_barrier(0)
; template <class Epi, bool ALIGN_EPI = false, bool SP2 = true>
; __device__ __forceinline__ void gemm_phase(LAS unsigned char* lds, const Gemm g, const StaticOrder& S, const Epi& E) {
;     ...
;         for (int t = 0; t < nt; t += 2) {
;             const bool last = (t == nt - 2);
;             const char* a1 = cA + (size_t)(t + 1) * kstep;
;             const char* a2 = last ? nA : cA + (size_t)(t + 2) * kstep; const char* b2 = last ? nB : cB + (size_t)(t + 2) * kstep;
;     ...
;             PG8_LDA(At, 1, 1); PG8_STAGE(PG8_SB(1, 0), b3, voffB); PG8_STAGE(PG8_SB(1, 1), b3 + hstep, voffB); PG8_STAGE(PG8_SA(1, 0), a3, voffA);
;             PG8_WAIT_V(8); PG8_WAIT_L(0); PG8_BAR; PG8_MMA(1, 0, At, B0); PG8_MMA(1, 1, At, B1); PG8_BAR; PG8_SCHED;
	s_add_i32 s46, s69, s33
	v_lshl_add_u64 v[214:215], v[214:215], 0, s[8:9]
	s_mov_b32 m0, s46
	ds_read_b128 v[160:163], v189 offset:49152
	ds_read_b128 v[180:183], v189 offset:50176
	ds_read_b128 v[190:193], v189 offset:51200
	ds_read_b128 v[194:197], v189 offset:52224
	ds_read_b128 v[198:201], v189 offset:53248
	ds_read_b128 v[202:205], v189 offset:54272
	ds_read_b128 v[206:209], v189 offset:55296
	ds_read_b128 v[210:213], v189 offset:56320
	global_load_lds_dwordx4 v[214:215], off
	s_add_i32 m0, s46, 0x2000
	s_add_u32 s44, s44, 0x80080
	v_lshl_add_u64 v[214:215], v[216:217], 0, s[8:9]
	s_addc_u32 s45, s45, 0
	s_add_i32 s46, s70, s33
	global_load_lds_dwordx4 v[214:215], off
	v_lshl_add_u64 v[214:215], s[44:45], 0, v[168:169]
	s_mov_b32 m0, s46
	s_nop 0
	global_load_lds_dwordx4 v[214:215], off
	v_lshl_add_u64 v[214:215], s[44:45], 0, v[172:173]
	s_add_i32 m0, s46, 0x2000
	s_nop 0
	global_load_lds_dwordx4 v[214:215], off
	v_lshl_add_u64 v[214:215], v[218:219], 0, s[8:9]
	s_mov_b32 m0, s54
	s_nop 0
	global_load_lds_dwordx4 v[214:215], off
	v_lshl_add_u64 v[214:215], v[220:221], 0, s[8:9]
	s_mov_b32 m0, s55
	s_nop 0
	global_load_lds_dwordx4 v[214:215], off
	s_waitcnt vmcnt(8)
	s_waitcnt lgkmcnt(0)
	s_barrier
	s_waitcnt lgkmcnt(0)
	v_mfma_f32_16x16x32_bf16 v[60:63], v[128:131], v[160:163], v[60:63]
	v_mfma_f32_16x16x32_bf16 v[56:59], v[136:139], v[160:163], v[56:59]
	v_mfma_f32_16x16x32_bf16 v[44:47], v[128:131], v[190:193], v[44:47]
	v_mfma_f32_16x16x32_bf16 v[40:43], v[136:139], v[190:193], v[40:43]
	v_mfma_f32_16x16x32_bf16 v[28:31], v[128:131], v[198:201], v[28:31]
	v_mfma_f32_16x16x32_bf16 v[24:27], v[136:139], v[198:201], v[24:27]
	v_mfma_f32_16x16x32_bf16 v[12:15], v[128:131], v[206:209], v[12:15]
	v_mfma_f32_16x16x32_bf16 v[8:11], v[136:139], v[206:209], v[8:11]
	v_mfma_f32_16x16x32_bf16 v[60:63], v[132:135], v[180:183], v[60:63]
	v_mfma_f32_16x16x32_bf16 v[56:59], v[140:143], v[180:183], v[56:59]
	v_mfma_f32_16x16x32_bf16 v[44:47], v[132:135], v[194:197], v[44:47]
	v_mfma_f32_16x16x32_bf16 v[40:43], v[140:143], v[194:197], v[40:43]
	v_mfma_f32_16x16x32_bf16 v[28:31], v[132:135], v[202:205], v[28:31]
	v_mfma_f32_16x16x32_bf16 v[24:27], v[140:143], v[202:205], v[24:27]
	v_mfma_f32_16x16x32_bf16 v[12:15], v[132:135], v[210:213], v[12:15]
	v_mfma_f32_16x16x32_bf16 v[8:11], v[140:143], v[210:213], v[8:11]
	v_mfma_f32_16x16x32_bf16 v[52:55], v[144:147], v[160:163], v[52:55]
	v_mfma_f32_16x16x32_bf16 v[48:51], v[152:155], v[160:163], v[48:51]
	v_mfma_f32_16x16x32_bf16 v[36:39], v[144:147], v[190:193], v[36:39]
	v_mfma_f32_16x16x32_bf16 v[32:35], v[152:155], v[190:193], v[32:35]
	v_mfma_f32_16x16x32_bf16 v[20:23], v[144:147], v[198:201], v[20:23]
	v_mfma_f32_16x16x32_bf16 v[16:19], v[152:155], v[198:201], v[16:19]
	v_mfma_f32_16x16x32_bf16 v[4:7], v[144:147], v[206:209], v[4:7]
	v_mfma_f32_16x16x32_bf16 v[0:3], v[152:155], v[206:209], v[0:3]
	v_mfma_f32_16x16x32_bf16 v[52:55], v[148:151], v[180:183], v[52:55]
	v_mfma_f32_16x16x32_bf16 v[48:51], v[156:159], v[180:183], v[48:51]
	v_mfma_f32_16x16x32_bf16 v[36:39], v[148:151], v[194:197], v[36:39]
	v_mfma_f32_16x16x32_bf16 v[32:35], v[156:159], v[194:197], v[32:35]
	v_mfma_f32_16x16x32_bf16 v[20:23], v[148:151], v[202:205], v[20:23]
	v_mfma_f32_16x16x32_bf16 v[16:19], v[156:159], v[202:205], v[16:19]
	v_mfma_f32_16x16x32_bf16 v[4:7], v[148:151], v[210:213], v[4:7]
	v_mfma_f32_16x16x32_bf16 v[0:3], v[156:159], v[210:213], v[0:3]
	s_barrier
	s_add_i32 s68, s68, 2
	s_add_u32 s40, s40, 0x100
	s_addc_u32 s41, s41, 0
	s_add_u32 s66, s66, 0x100
	s_addc_u32 s67, s67, 0
	s_cmp_gt_u32 s68, 29
	s_cbranch_scc0 .LBB0_855
	s_and_b64 vcc, exec, s[10:11]
	s_cbranch_vccz .LBB0_858
	s_barrier
